# k17: LDS-DMA m0 save/restore pairs removed (scan loader, attention), canonicalising self-max folded into the row-max chain
# speedup vs baseline: 1.0090x; 1.0027x over previous
.LBB0_700:
	s_or_b64 exec, exec, s[0:1]
	s_lshl_b32 s43, s2, 4
	s_and_b32 s0, s43, 0x70
	s_add_i32 s0, s0, s71
	s_ashr_i32 s0, s0, 4
	s_ashr_i32 s1, s0, 31
	s_cmp_eq_u32 s70, 2
	s_waitcnt vmcnt(0) lgkmcnt(0)
	s_barrier
	s_cbranch_scc0 .LBB0_718
	v_lshlrev_b32_e32 v14, 4, v148
	v_mov_b32_e32 v1, 0
	v_and_b32_e32 v0, 0x70, v14
	v_readlane_b32 s16, v254, 0
	s_lshl_b64 s[10:11], s[0:1], 13
	s_mov_b32 s9, 0
	s_lshl_b32 s4, s42, 6
	v_lshl_add_u64 v[2:3], s[82:83], 0, v[0:1]
	s_lshl_b32 s8, s42, 7
	v_readlane_b32 s22, v254, 6
	v_readlane_b32 s23, v254, 7
	v_lshl_add_u64 v[10:11], v[2:3], 0, s[8:9]
	s_add_u32 s4, s80, s4
	v_lshl_add_u64 v[2:3], s[22:23], 0, v[0:1]
	v_lshrrev_b32_e32 v7, 3, v148
	v_lshl_add_u64 v[12:13], v[2:3], 0, s[8:9]
	v_lshl_add_u64 v[2:3], s[14:15], 0, v[0:1]
	s_addc_u32 s5, s81, 0
	v_lshl_add_u64 v[8:9], v[2:3], 0, s[8:9]
	v_lshl_add_u64 v[2:3], s[62:63], 0, v[0:1]
	v_and_b32_e32 v0, 48, v14
	v_or_b32_e32 v14, s10, v7
	v_mov_b32_e32 v15, s11
	s_cmp_lg_u32 0, -1
	v_lshlrev_b64 v[14:15], 11, v[14:15]
	s_cselect_b32 s6, 0, 0
	v_lshl_add_u64 v[0:1], s[4:5], 0, v[0:1]
	v_lshl_add_u64 v[16:17], v[10:11], 0, v[14:15]
	s_add_i32 s4, s6, 0x19c00
	s_mov_b32 m0, s4
	s_nop 0
	global_load_lds_dwordx4 v[16:17], off
	s_mov_b64 s[4:5], 0x4000
	v_lshl_add_u64 v[2:3], v[2:3], 0, s[8:9]
	v_lshl_add_u64 v[16:17], v[16:17], 0, s[4:5]
	s_add_i32 s7, s6, 0x1a000
	s_mov_b32 m0, s7
	s_nop 0
	global_load_lds_dwordx4 v[16:17], off
	v_lshl_add_u64 v[16:17], v[12:13], 0, v[14:15]
	s_add_i32 s7, s6, 0x1a400
	s_mov_b32 m0, s7
	s_nop 0
	global_load_lds_dwordx4 v[16:17], off
	v_lshl_add_u64 v[16:17], v[16:17], 0, s[4:5]
	s_add_i32 s7, s6, 0x1a800
	s_mov_b32 m0, s7
	s_nop 0
	global_load_lds_dwordx4 v[16:17], off
	v_lshl_add_u64 v[16:17], v[8:9], 0, v[14:15]
	s_add_i32 s7, s6, 0x1ac00
	s_mov_b32 m0, s7
	s_nop 0
	global_load_lds_dwordx4 v[16:17], off
	v_lshl_add_u64 v[16:17], v[16:17], 0, s[4:5]
	s_add_i32 s7, s6, 0x1b000
	s_mov_b32 m0, s7
	s_nop 0
	global_load_lds_dwordx4 v[16:17], off
	v_lshl_add_u64 v[14:15], v[2:3], 0, v[14:15]
	s_add_i32 s7, s6, 0x1b400
	s_mov_b32 m0, s7
	s_nop 0
	global_load_lds_dwordx4 v[14:15], off
	v_lshl_add_u64 v[14:15], v[14:15], 0, s[4:5]
	s_add_i32 s6, s6, 0x1b800
	s_mov_b32 m0, s6
	s_nop 0
	global_load_lds_dwordx4 v[14:15], off
	v_cmp_gt_u32_e32 vcc, 32, v148
	v_lshrrev_b32_e32 v5, 2, v148
	v_readlane_b32 s17, v254, 1
	v_readlane_b32 s18, v254, 2
	v_readlane_b32 s19, v254, 3
	v_readlane_b32 s20, v254, 4
	v_readlane_b32 s21, v254, 5
	s_and_saveexec_b64 s[4:5], vcc
	s_cbranch_execz .LBB0_703
	v_mov_b32_e32 v15, s11
	v_or_b32_e32 v14, s10, v5
	s_cmp_lg_u32 0, -1
	v_lshlrev_b64 v[14:15], 10, v[14:15]
	s_cselect_b32 s8, 0, 0
	v_lshl_add_u64 v[14:15], v[0:1], 0, v[14:15]
	s_add_i32 s6, s8, 0x1bc00
	s_mov_b32 m0, s6
	s_nop 0
	global_load_lds_dwordx4 v[14:15], off
	s_mov_b64 s[6:7], 0x2000
	v_lshl_add_u64 v[14:15], v[14:15], 0, s[6:7]
	s_add_i32 s8, s8, 0x1be00
	s_mov_b32 m0, s8
	s_nop 0
	global_load_lds_dwordx4 v[14:15], off
.LBB0_703:
	s_or_b64 exec, exec, s[4:5]
	v_cmp_gt_u32_e64 s[6:7], 16, v148
	s_lshl_b32 s8, s42, 4
	s_and_saveexec_b64 s[4:5], s[6:7]
	s_cbranch_execz .LBB0_705
	v_mov_b32_e32 v15, s11
	v_or_b32_e32 v14, s10, v148
	v_lshlrev_b64 v[14:15], 8, v[14:15]
	s_cmp_lg_u32 0, -1
	v_lshl_add_u64 v[14:15], s[52:53], 0, v[14:15]
	s_cselect_b32 s12, 0, 0
	v_lshl_add_u64 v[14:15], v[14:15], 0, s[8:9]
	s_add_i32 s12, s12, 0x1c400
	s_mov_b32 m0, s12
	s_nop 0
	global_load_lds_dwordx4 v[14:15], off
.LBB0_705:
	s_or_b64 exec, exec, s[4:5]
	s_or_b32 s12, s10, 16
	v_mov_b32_e32 v15, s11
	v_or_b32_e32 v14, s12, v7
	s_cmp_lg_u32 0, -1
	v_lshlrev_b64 v[14:15], 11, v[14:15]
	s_cselect_b32 s14, 0, 0
	v_lshl_add_u64 v[16:17], v[10:11], 0, v[14:15]
	s_add_i32 s4, s14, 0x1c500
	s_mov_b32 m0, s4
	s_nop 0
	global_load_lds_dwordx4 v[16:17], off
	s_mov_b64 s[4:5], 0x4000
	v_lshl_add_u64 v[16:17], v[16:17], 0, s[4:5]
	s_add_i32 s15, s14, 0x1c900
	s_mov_b32 s16, m0
	s_mov_b32 m0, s15
	s_nop 0
	global_load_lds_dwordx4 v[16:17], off
	s_mov_b32 m0, s16
	v_lshl_add_u64 v[16:17], v[12:13], 0, v[14:15]
	s_add_i32 s15, s14, 0x1cd00
	s_mov_b32 s16, m0
	s_mov_b32 m0, s15
	s_nop 0
	global_load_lds_dwordx4 v[16:17], off
	s_mov_b32 m0, s16
	v_lshl_add_u64 v[16:17], v[16:17], 0, s[4:5]
	s_add_i32 s15, s14, 0x1d100
	s_mov_b32 s16, m0
	s_mov_b32 m0, s15
	s_nop 0
	global_load_lds_dwordx4 v[16:17], off
	s_mov_b32 m0, s16
	v_lshl_add_u64 v[16:17], v[8:9], 0, v[14:15]
	s_add_i32 s15, s14, 0x1d500
	s_mov_b32 s16, m0
	s_mov_b32 m0, s15
	s_nop 0
	global_load_lds_dwordx4 v[16:17], off
	s_mov_b32 m0, s16
	v_lshl_add_u64 v[16:17], v[16:17], 0, s[4:5]
	s_add_i32 s15, s14, 0x1d900
	s_mov_b32 s16, m0
	s_mov_b32 m0, s15
	s_nop 0
	global_load_lds_dwordx4 v[16:17], off
	s_mov_b32 m0, s16
	v_lshl_add_u64 v[14:15], v[2:3], 0, v[14:15]
	s_add_i32 s15, s14, 0x1dd00
	s_mov_b32 s16, m0
	s_mov_b32 m0, s15
	s_nop 0
	global_load_lds_dwordx4 v[14:15], off
	s_mov_b32 m0, s16
	v_lshl_add_u64 v[14:15], v[14:15], 0, s[4:5]
	s_add_i32 s14, s14, 0x1e100
	s_mov_b32 m0, s14
	s_nop 0
	global_load_lds_dwordx4 v[14:15], off
	s_mov_b32 s13, s11
	s_and_saveexec_b64 s[4:5], vcc
	s_cbranch_execz .LBB0_707
	v_mov_b32_e32 v15, s13
	v_or_b32_e32 v14, s12, v5
	s_cmp_lg_u32 0, -1
	v_lshlrev_b64 v[14:15], 10, v[14:15]
	s_cselect_b32 s16, 0, 0
	v_lshl_add_u64 v[14:15], v[0:1], 0, v[14:15]
	s_add_i32 s14, s16, 0x1e500
	s_mov_b32 m0, s14
	s_nop 0
	global_load_lds_dwordx4 v[14:15], off
	s_mov_b64 s[14:15], 0x2000
	v_lshl_add_u64 v[14:15], v[14:15], 0, s[14:15]
	s_add_i32 s16, s16, 0x1e700
	s_mov_b32 m0, s16
	s_nop 0
	global_load_lds_dwordx4 v[14:15], off
.LBB0_707:
	s_or_b64 exec, exec, s[4:5]
	s_and_saveexec_b64 s[4:5], s[6:7]
	s_cbranch_execz .LBB0_709
	v_mov_b32_e32 v15, s13
	v_or_b32_e32 v14, s12, v148
	v_lshlrev_b64 v[14:15], 8, v[14:15]
	s_cmp_lg_u32 0, -1
	v_lshl_add_u64 v[14:15], s[52:53], 0, v[14:15]
	s_cselect_b32 s12, 0, 0
	v_lshl_add_u64 v[14:15], v[14:15], 0, s[8:9]
	s_add_i32 s12, s12, 0x1ed00
	s_mov_b32 m0, s12
	s_nop 0
	global_load_lds_dwordx4 v[14:15], off
.LBB0_709:
	s_or_b64 exec, exec, s[4:5]
	s_or_b32 s12, s10, 32
	v_mov_b32_e32 v15, s11
	v_or_b32_e32 v14, s12, v7
	s_cmp_lg_u32 0, -1
	v_lshlrev_b64 v[14:15], 11, v[14:15]
	s_cselect_b32 s14, 0, 0
	v_lshl_add_u64 v[16:17], v[10:11], 0, v[14:15]
	s_add_i32 s4, s14, 0x1ee00
	s_mov_b32 m0, s4
	s_nop 0
	global_load_lds_dwordx4 v[16:17], off
	s_mov_b64 s[4:5], 0x4000
	v_lshl_add_u64 v[16:17], v[16:17], 0, s[4:5]
	s_add_i32 s15, s14, 0x1f200
	s_mov_b32 s16, m0
	s_mov_b32 m0, s15
	s_nop 0
	global_load_lds_dwordx4 v[16:17], off
	s_mov_b32 m0, s16
	v_lshl_add_u64 v[16:17], v[12:13], 0, v[14:15]
	s_add_i32 s15, s14, 0x1f600
	s_mov_b32 s16, m0
	s_mov_b32 m0, s15
	s_nop 0
	global_load_lds_dwordx4 v[16:17], off
	s_mov_b32 m0, s16
	v_lshl_add_u64 v[16:17], v[16:17], 0, s[4:5]
	s_add_i32 s15, s14, 0x1fa00
	s_mov_b32 s16, m0
	s_mov_b32 m0, s15
	s_nop 0
	global_load_lds_dwordx4 v[16:17], off
	s_mov_b32 m0, s16
	v_lshl_add_u64 v[16:17], v[8:9], 0, v[14:15]
	s_add_i32 s15, s14, 0x1fe00
	s_mov_b32 s16, m0
	s_mov_b32 m0, s15
	s_nop 0
	global_load_lds_dwordx4 v[16:17], off
	s_mov_b32 m0, s16
	v_lshl_add_u64 v[16:17], v[16:17], 0, s[4:5]
	s_add_i32 s15, s14, 0x20200
	s_mov_b32 s16, m0
	s_mov_b32 m0, s15
	s_nop 0
	global_load_lds_dwordx4 v[16:17], off
	s_mov_b32 m0, s16
	v_lshl_add_u64 v[14:15], v[2:3], 0, v[14:15]
	s_add_i32 s15, s14, 0x20600
	s_mov_b32 s16, m0
	s_mov_b32 m0, s15
	s_nop 0
	global_load_lds_dwordx4 v[14:15], off
	s_mov_b32 m0, s16
	v_lshl_add_u64 v[14:15], v[14:15], 0, s[4:5]
	s_add_i32 s14, s14, 0x20a00
	s_mov_b32 m0, s14
	s_nop 0
	global_load_lds_dwordx4 v[14:15], off
	s_mov_b32 s13, s11
	s_and_saveexec_b64 s[4:5], vcc
	s_cbranch_execz .LBB0_711
	v_mov_b32_e32 v15, s13
	v_or_b32_e32 v14, s12, v5
	s_cmp_lg_u32 0, -1
	v_lshlrev_b64 v[14:15], 10, v[14:15]
	s_cselect_b32 s16, 0, 0
	v_lshl_add_u64 v[14:15], v[0:1], 0, v[14:15]
	s_add_i32 s14, s16, 0x20e00
	s_mov_b32 m0, s14
	s_nop 0
	global_load_lds_dwordx4 v[14:15], off
	s_mov_b64 s[14:15], 0x2000
	v_lshl_add_u64 v[14:15], v[14:15], 0, s[14:15]
	s_add_i32 s16, s16, 0x21000
	s_mov_b32 s14, m0
	s_mov_b32 m0, s16
	s_nop 0
	global_load_lds_dwordx4 v[14:15], off
	s_mov_b32 m0, s14
.LBB0_711:
	s_or_b64 exec, exec, s[4:5]
	s_and_saveexec_b64 s[4:5], s[6:7]
	s_cbranch_execz .LBB0_713
	v_mov_b32_e32 v15, s13
	v_or_b32_e32 v14, s12, v148
	v_lshlrev_b64 v[14:15], 8, v[14:15]
	s_cmp_lg_u32 0, -1
	v_lshl_add_u64 v[14:15], s[52:53], 0, v[14:15]
	s_cselect_b32 s12, 0, 0
	v_lshl_add_u64 v[14:15], v[14:15], 0, s[8:9]
	s_add_i32 s12, s12, 0x21600
	s_mov_b32 m0, s12
	s_nop 0
	global_load_lds_dwordx4 v[14:15], off
.LBB0_713:
	s_or_b64 exec, exec, s[4:5]
	s_or_b32 s10, s10, 48
	v_mov_b32_e32 v15, s11
	v_or_b32_e32 v14, s10, v7
	s_cmp_lg_u32 0, -1
	v_lshlrev_b64 v[14:15], 11, v[14:15]
	s_cselect_b32 s12, 0, 0
	v_lshl_add_u64 v[10:11], v[10:11], 0, v[14:15]
	s_add_i32 s4, s12, 0x21700
	s_mov_b32 m0, s4
	s_nop 0
	global_load_lds_dwordx4 v[10:11], off
	s_mov_b64 s[4:5], 0x4000
	v_lshl_add_u64 v[10:11], v[10:11], 0, s[4:5]
	s_add_i32 s13, s12, 0x21b00
	s_mov_b32 s14, m0
	s_mov_b32 m0, s13
	s_nop 0
	global_load_lds_dwordx4 v[10:11], off
	s_mov_b32 m0, s14
	v_lshl_add_u64 v[10:11], v[12:13], 0, v[14:15]
	s_add_i32 s13, s12, 0x21f00
	s_mov_b32 s14, m0
	s_mov_b32 m0, s13
	s_nop 0
	global_load_lds_dwordx4 v[10:11], off
	s_mov_b32 m0, s14
	v_lshl_add_u64 v[10:11], v[10:11], 0, s[4:5]
	s_add_i32 s13, s12, 0x22300
	s_mov_b32 s14, m0
	s_mov_b32 m0, s13
	s_nop 0
	global_load_lds_dwordx4 v[10:11], off
	s_mov_b32 m0, s14
	v_lshl_add_u64 v[8:9], v[8:9], 0, v[14:15]
	s_add_i32 s13, s12, 0x22700
	s_mov_b32 s14, m0
	s_mov_b32 m0, s13
	s_nop 0
	global_load_lds_dwordx4 v[8:9], off
	s_mov_b32 m0, s14
	v_lshl_add_u64 v[8:9], v[8:9], 0, s[4:5]
	s_add_i32 s13, s12, 0x22b00
	s_mov_b32 s14, m0
	s_mov_b32 m0, s13
	s_nop 0
	global_load_lds_dwordx4 v[8:9], off
	s_mov_b32 m0, s14
	v_lshl_add_u64 v[2:3], v[2:3], 0, v[14:15]
	s_add_i32 s13, s12, 0x22f00
	s_mov_b32 s14, m0
	s_mov_b32 m0, s13
	s_nop 0
	global_load_lds_dwordx4 v[2:3], off
	s_mov_b32 m0, s14
	v_lshl_add_u64 v[2:3], v[2:3], 0, s[4:5]
	s_add_i32 s12, s12, 0x23300
	s_mov_b32 m0, s12
	s_nop 0
	global_load_lds_dwordx4 v[2:3], off
	s_and_saveexec_b64 s[4:5], vcc
	s_cbranch_execz .LBB0_715
	v_mov_b32_e32 v3, s11
	v_or_b32_e32 v2, s10, v5
	s_cmp_lg_u32 0, -1
	v_lshlrev_b64 v[2:3], 10, v[2:3]
	s_cselect_b32 s14, 0, 0
	v_lshl_add_u64 v[0:1], v[0:1], 0, v[2:3]
	s_add_i32 s12, s14, 0x23700
	s_mov_b32 m0, s12
	s_nop 0
	global_load_lds_dwordx4 v[0:1], off
	s_mov_b64 s[12:13], 0x2000
	v_lshl_add_u64 v[0:1], v[0:1], 0, s[12:13]
	s_add_i32 s14, s14, 0x23900
	s_mov_b32 m0, s14
	s_nop 0
	global_load_lds_dwordx4 v[0:1], off
.LBB0_715:
	s_or_b64 exec, exec, s[4:5]
	s_and_saveexec_b64 s[4:5], s[6:7]
	s_cbranch_execz .LBB0_717
	v_mov_b32_e32 v1, s11
	v_or_b32_e32 v0, s10, v148
	v_lshlrev_b64 v[0:1], 8, v[0:1]
	s_cmp_lg_u32 0, -1
	v_lshl_add_u64 v[0:1], s[52:53], 0, v[0:1]
	s_cselect_b32 s6, 0, 0
	v_lshl_add_u64 v[0:1], v[0:1], 0, s[8:9]
	s_add_i32 s6, s6, 0x23f00
	s_mov_b32 m0, s6
	s_nop 0
	global_load_lds_dwordx4 v[0:1], off

.LBB0_826:
	s_mul_i32 s4, s33, 0xcccd
	s_lshr_b32 s4, s4, 18
	s_mul_i32 s4, s4, 5
	s_sub_i32 s4, s33, s4
	s_and_b32 s4, s4, 0xffff
	s_cmp_lg_u32 0, -1
	s_mulk_i32 s4, 0x2900
	s_cselect_b32 s5, 0, 0
	v_lshl_add_u64 v[0:1], v[72:73], 0, s[12:13]
	s_add_i32 s4, s5, s4
	v_lshl_add_u64 v[2:3], v[0:1], 0, s[14:15]
	s_add_i32 s36, s4, 0x19c00
	s_mov_b32 m0, s36
	s_nop 0
	global_load_lds_dwordx4 v[2:3], off
	v_lshl_add_u64 v[2:3], v[0:1], 0, s[16:17]
	s_add_i32 s4, s36, 0x400
	s_mov_b32 m0, s4
	s_nop 0
	global_load_lds_dwordx4 v[2:3], off
	v_lshl_add_u64 v[2:3], v[74:75], 0, s[12:13]
	v_lshl_add_u64 v[4:5], v[2:3], 0, s[18:19]
	s_add_i32 s4, s36, 0x800
	s_mov_b32 m0, s4
	s_nop 0
	global_load_lds_dwordx4 v[4:5], off
	v_lshl_add_u64 v[4:5], v[2:3], 0, s[20:21]
	s_add_i32 s4, s36, 0xc00
	s_mov_b32 m0, s4
	s_nop 0
	global_load_lds_dwordx4 v[4:5], off
	v_lshl_add_u64 v[4:5], v[2:3], 0, s[22:23]
	s_add_i32 s4, s36, 0x1000
	s_mov_b32 m0, s4
	s_nop 0
	global_load_lds_dwordx4 v[4:5], off
	v_lshl_add_u64 v[2:3], v[2:3], 0, s[24:25]
	s_add_i32 s4, s36, 0x1400
	s_mov_b32 m0, s4
	s_nop 0
	global_load_lds_dwordx4 v[2:3], off
	v_lshl_add_u64 v[2:3], v[0:1], 0, s[26:27]
	s_add_i32 s4, s36, 0x1800
	s_mov_b32 m0, s4
	s_nop 0
	global_load_lds_dwordx4 v[2:3], off
	v_lshl_add_u64 v[0:1], v[0:1], 0, s[28:29]
	s_add_i32 s4, s36, 0x1c00
	s_mov_b32 m0, s4
	s_nop 0
	global_load_lds_dwordx4 v[0:1], off
	s_and_saveexec_b64 s[4:5], s[6:7]
	s_cbranch_execz .LBB0_828
	s_add_i32 s37, s36, 0x2000
	s_mov_b32 m0, s37
	s_nop 0
	global_load_lds_dwordx4 v[70:71], off
	v_lshl_add_u64 v[0:1], v[70:71], 0, s[30:31]
	s_add_i32 s37, s36, 0x2200
	s_mov_b32 m0, s37
	s_nop 0
	global_load_lds_dwordx4 v[0:1], off
.LBB0_828:
	s_or_b64 exec, exec, s[4:5]
	s_and_saveexec_b64 s[4:5], s[8:9]
	s_cbranch_execz .LBB0_815
	v_lshl_add_u64 v[0:1], v[68:69], 0, s[0:1]
	v_lshl_add_u64 v[0:1], v[0:1], 0, s[10:11]
	s_addk_i32 s36, 0x2800
	s_mov_b32 m0, s36
	s_nop 0
	global_load_lds_dwordx4 v[0:1], off
	s_branch .LBB0_815

.LBB0_1328:
	s_lshl_b32 s4, s88, 1
	s_and_b32 s4, s4, 12
	s_or_b32 s4, s4, s33
	v_mov_b32_e32 v48, v226
	s_lshl_b32 s4, s4, 8
	v_readfirstlane_b32 s5, v48
	s_and_b32 s6, s88, 1
	s_ashr_i32 s74, s5, 6
	s_xor_b32 s7, s4, 0x1f00
	s_cmp_eq_u32 s6, 0
	s_cselect_b32 s68, s4, s7
	s_lshl_b32 s10, s74, 5
	s_or_b32 s71, s68, s40
	s_ashr_i32 s4, s10, 31
	s_add_u32 s6, s10, s71
	s_addc_u32 s7, s4, 0
	s_lshl_b64 s[6:7], s[6:7], 11
	v_and_b32_e32 v231, 63, v48
	s_add_u32 s6, s42, s6
	s_addc_u32 s7, s43, s7
	v_lshlrev_b32_e32 v212, 11, v231
	s_lshl_b32 s8, s74, 3
	v_lshl_add_u64 v[0:1], s[28:29], 0, v[212:213]
	s_ashr_i32 s9, s8, 31
	v_lshl_add_u64 v[214:215], s[8:9], 1, v[0:1]
	s_lshl_b32 s4, s74, 4
	v_bfe_u32 v0, v48, 2, 4
	v_and_or_b32 v0, s4, 48, v0
	s_ashr_i32 s4, s5, 3
	s_and_b32 s8, s4, 0xffffffe0
	v_lshlrev_b32_e32 v212, 11, v0
	s_ashr_i32 s9, s8, 31
	s_lshl_b32 s4, s74, 10
	v_lshl_add_u64 v[0:1], s[30:31], 0, v[212:213]
	v_lshlrev_b32_e32 v2, 3, v48
	s_cmp_lg_u32 0, -1
	v_lshl_add_u64 v[0:1], s[8:9], 1, v[0:1]
	v_and_b32_e32 v232, 24, v2
	s_cselect_b32 s8, 0, 0
	v_lshlrev_b32_e32 v212, 1, v232
	s_add_i32 s76, s4, s8
	s_mov_b32 m0, s76
	s_nop 0
	global_load_lds_dwordx4 v[214:215], off
	v_lshl_add_u64 v[216:217], v[0:1], 0, v[212:213]
	s_add_i32 s77, s76, 0x6000
	s_mov_b32 m0, s77
	s_nop 0
	global_load_lds_dwordx4 v[216:217], off
	v_and_b32_e32 v230, 31, v48
	v_lshl_add_u64 v[218:219], v[216:217], 0, s[12:13]
	s_add_i32 s8, s76, 0x8000
	s_mov_b32 m0, s8
	s_nop 0
	global_load_lds_dwordx4 v[218:219], off
	v_lshl_add_u64 v[0:1], v[214:215], 0, s[14:15]
	v_bfe_u32 v242, v48, 5, 1
	s_add_i32 s8, s76, 0x2000
	s_mov_b32 m0, s8
	s_nop 0
	global_load_lds_dwordx4 v[0:1], off
	v_lshlrev_b32_e32 v0, 11, v230
	v_lshl_or_b32 v0, v242, 4, v0
	global_load_dwordx4 v[172:175], v0, s[6:7]
	global_load_dwordx4 v[168:171], v0, s[6:7] offset:32
	global_load_dwordx4 v[160:163], v0, s[6:7] offset:64
	global_load_dwordx4 v[152:155], v0, s[6:7] offset:96
	v_lshlrev_b32_e32 v1, 10, v242
	v_lshlrev_b32_e32 v2, 4, v230
	v_mov_b32 v0, 0
	v_add3_u32 v238, 0, v1, v2
	v_mov_b32_e32 v14, v0
	v_mov_b32_e32 v15, v0
	v_mov_b32_e32 v1, v0
	v_mov_b32_e32 v2, v0
	v_mov_b32_e32 v3, v0
	v_mov_b32_e32 v4, v0
	v_mov_b32_e32 v5, v0
	v_mov_b32_e32 v6, v0
	v_mov_b32_e32 v7, v0
	v_mov_b32_e32 v8, v0
	v_mov_b32_e32 v9, v0
	v_mov_b32_e32 v10, v0
	v_mov_b32_e32 v11, v0
	v_mov_b32_e32 v12, v0
	v_mov_b32_e32 v13, v0
	v_mov_b64_e32 v[30:31], v[14:15]
	v_mov_b64_e32 v[28:29], v[12:13]
	v_mov_b64_e32 v[26:27], v[10:11]
	v_mov_b64_e32 v[24:25], v[8:9]
	v_mov_b64_e32 v[22:23], v[6:7]
	v_mov_b64_e32 v[20:21], v[4:5]
	v_mov_b64_e32 v[18:19], v[2:3]
	v_mov_b64_e32 v[16:17], v[0:1]
	v_lshl_add_u64 v[32:33], v[214:215], 0, s[16:17]
	s_add_i32 s8, s76, 0x4000
	s_mov_b32 m0, s8
	s_nop 0
	global_load_lds_dwordx4 v[32:33], off
	s_waitcnt vmcnt(3) lgkmcnt(0)
	s_barrier
	ds_read_b128 v[50:53], v238
	ds_read_b128 v[54:57], v238 offset:512
	s_cmp_eq_u32 s68, 0
	s_cselect_b64 s[34:35], -1, 0
	s_cmp_lg_u32 s68, 0
	s_cselect_b64 s[8:9], -1, 0
	v_lshlrev_b32_e32 v212, 2, v242
	v_or_b32_e32 v236, s10, v230
	s_and_b64 vcc, exec, s[8:9]
	s_waitcnt vmcnt(3) lgkmcnt(1)
	v_mfma_f32_32x32x16_bf16 v[32:47], v[50:53], v[172:175], v[16:31]
	s_waitcnt lgkmcnt(0)
	v_mfma_f32_32x32x16_bf16 v[16:31], v[54:57], v[172:175], v[16:31]
	ds_read_b128 v[50:53], v238 offset:2048
	ds_read_b128 v[54:57], v238 offset:2560
	s_waitcnt vmcnt(2) lgkmcnt(1)
	v_mfma_f32_32x32x16_bf16 v[32:47], v[50:53], v[168:171], v[32:47]
	s_waitcnt lgkmcnt(0)
	v_mfma_f32_32x32x16_bf16 v[16:31], v[54:57], v[168:171], v[16:31]
	ds_read_b128 v[50:53], v238 offset:4096
	ds_read_b128 v[54:57], v238 offset:4608
	s_waitcnt vmcnt(1) lgkmcnt(1)
	v_mfma_f32_32x32x16_bf16 v[32:47], v[50:53], v[160:163], v[32:47]
	s_waitcnt lgkmcnt(0)
	v_mfma_f32_32x32x16_bf16 v[16:31], v[54:57], v[160:163], v[16:31]
	ds_read_b128 v[50:53], v238 offset:6144
	ds_read_b128 v[54:57], v238 offset:6656
	s_waitcnt vmcnt(0) lgkmcnt(1)
	v_mfma_f32_32x32x16_bf16 v[32:47], v[50:53], v[152:155], v[32:47]
	s_waitcnt lgkmcnt(0)
	v_mfma_f32_32x32x16_bf16 v[16:31], v[54:57], v[152:155], v[16:31]
	s_nop 15
	s_nop 7
	s_cbranch_vccnz .LBB0_1330
	v_lshlrev_b32_e32 v49, 2, v242
	v_or_b32_e32 v50, 32, v49
	v_cmp_le_i32_e32 vcc, v50, v236
	v_or_b32_e32 v50, 33, v49
	s_nop 6
	v_cndmask_b32_e32 v16, v228, v16, vcc
	v_cmp_lt_i32_e32 vcc, v49, v236
	s_nop 1
	v_cndmask_b32_e32 v33, v228, v33, vcc
	v_cmp_le_i32_e32 vcc, v49, v236
	s_nop 1
	v_cndmask_b32_e32 v32, v228, v32, vcc
	v_cmp_le_i32_e32 vcc, v50, v236
	v_or_b32_e32 v50, 2, v49
	s_nop 0
	v_cndmask_b32_e32 v17, v228, v17, vcc
	v_cmp_le_i32_e32 vcc, v50, v236
	v_or_b32_e32 v50, 34, v49
	s_nop 0
	v_cndmask_b32_e32 v34, v228, v34, vcc
	v_cmp_le_i32_e32 vcc, v50, v236
	v_or_b32_e32 v50, 3, v49
	s_nop 0
	v_cndmask_b32_e32 v18, v228, v18, vcc
	v_cmp_le_i32_e32 vcc, v50, v236
	v_or_b32_e32 v50, 35, v49
	s_nop 0
	v_cndmask_b32_e32 v35, v228, v35, vcc
	v_cmp_le_i32_e32 vcc, v50, v236
	v_or_b32_e32 v50, 8, v49
	s_nop 0
	v_cndmask_b32_e32 v19, v228, v19, vcc
	v_cmp_le_i32_e32 vcc, v50, v236
	v_or_b32_e32 v50, 40, v49
	s_nop 0
	v_cndmask_b32_e32 v36, v228, v36, vcc
	v_cmp_le_i32_e32 vcc, v50, v236
	v_or_b32_e32 v50, 9, v49
	s_nop 0
	v_cndmask_b32_e32 v20, v228, v20, vcc
	v_cmp_le_i32_e32 vcc, v50, v236
	v_or_b32_e32 v50, 41, v49
	s_nop 0
	v_cndmask_b32_e32 v37, v228, v37, vcc
	v_cmp_le_i32_e32 vcc, v50, v236
	v_or_b32_e32 v50, 10, v49
	s_nop 0
	v_cndmask_b32_e32 v21, v228, v21, vcc
	v_cmp_le_i32_e32 vcc, v50, v236
	v_or_b32_e32 v50, 42, v49
	s_nop 0
	v_cndmask_b32_e32 v38, v228, v38, vcc
	v_cmp_le_i32_e32 vcc, v50, v236
	v_or_b32_e32 v50, 11, v49
	s_nop 0
	v_cndmask_b32_e32 v22, v228, v22, vcc
	v_cmp_le_i32_e32 vcc, v50, v236
	v_or_b32_e32 v50, 43, v49
	s_nop 0
	v_cndmask_b32_e32 v39, v228, v39, vcc
	v_cmp_le_i32_e32 vcc, v50, v236
	v_or_b32_e32 v50, 16, v49
	s_nop 0
	v_cndmask_b32_e32 v23, v228, v23, vcc
	v_cmp_le_i32_e32 vcc, v50, v236
	v_or_b32_e32 v50, 48, v49
	s_nop 0
	v_cndmask_b32_e32 v40, v228, v40, vcc
	v_cmp_le_i32_e32 vcc, v50, v236
	v_or_b32_e32 v50, 17, v49
	s_nop 0
	v_cndmask_b32_e32 v24, v228, v24, vcc
	v_cmp_le_i32_e32 vcc, v50, v236
	v_or_b32_e32 v50, 49, v49
	s_nop 0
	v_cndmask_b32_e32 v41, v228, v41, vcc
	v_cmp_le_i32_e32 vcc, v50, v236
	v_or_b32_e32 v50, 18, v49
	s_nop 0
	v_cndmask_b32_e32 v25, v228, v25, vcc
	v_cmp_le_i32_e32 vcc, v50, v236
	v_or_b32_e32 v50, 50, v49
	s_nop 0
	v_cndmask_b32_e32 v42, v228, v42, vcc
	v_cmp_le_i32_e32 vcc, v50, v236
	v_or_b32_e32 v50, 19, v49
	s_nop 0
	v_cndmask_b32_e32 v26, v228, v26, vcc
	v_cmp_le_i32_e32 vcc, v50, v236
	v_or_b32_e32 v50, 51, v49
	s_nop 0
	v_cndmask_b32_e32 v43, v228, v43, vcc
	v_cmp_le_i32_e32 vcc, v50, v236
	v_or_b32_e32 v50, 24, v49
	s_nop 0
	v_cndmask_b32_e32 v27, v228, v27, vcc
	v_cmp_le_i32_e32 vcc, v50, v236
	v_or_b32_e32 v50, 56, v49
	s_nop 0
	v_cndmask_b32_e32 v44, v228, v44, vcc
	v_cmp_le_i32_e32 vcc, v50, v236
	v_or_b32_e32 v50, 25, v49
	s_nop 0
	v_cndmask_b32_e32 v28, v228, v28, vcc
	v_cmp_le_i32_e32 vcc, v50, v236
	v_or_b32_e32 v50, 57, v49
	s_nop 0
	v_cndmask_b32_e32 v45, v228, v45, vcc
	v_cmp_le_i32_e32 vcc, v50, v236
	v_or_b32_e32 v50, 26, v49
	s_nop 0
	v_cndmask_b32_e32 v29, v228, v29, vcc
	v_cmp_le_i32_e32 vcc, v50, v236
	v_or_b32_e32 v50, 58, v49
	s_nop 0
	v_cndmask_b32_e32 v46, v228, v46, vcc
	v_cmp_le_i32_e32 vcc, v50, v236
	v_or_b32_e32 v50, 27, v49
	v_or_b32_e32 v49, 59, v49
	v_cndmask_b32_e32 v30, v228, v30, vcc
	v_cmp_le_i32_e32 vcc, v50, v236
	s_nop 1
	v_cndmask_b32_e32 v47, v228, v47, vcc
	v_cmp_le_i32_e32 vcc, v49, v236
	s_nop 1
	v_cndmask_b32_e32 v31, v228, v31, vcc
.LBB0_1330:
	v_lshlrev_b32_e32 v49, 1, v48
	v_lshlrev_b32_e32 v48, 4, v48
	v_and_b32_e32 v235, 32, v49
	v_and_b32_e32 v48, 0xc0, v48
	v_lshl_or_b32 v233, v242, 8, v48
	v_add_u32_e32 v48, 0, v235
	v_add3_u32 v239, v48, v232, v233
	v_max3_f32 v48, v32, v33, v16
	v_max3_f32 v49, v34, v35, v17
	s_and_b32 s5, s5, 0x3fffffc0
	v_max3_f32 v48, v48, v18, v19
	v_max3_f32 v49, v49, v38, v39
	s_lshl_b32 s5, s5, 2
	v_max3_f32 v48, v48, v36, v37
	v_max3_f32 v49, v49, v22, v23
	s_add_i32 s6, s68, 0x100
	v_max3_f32 v48, v48, v20, v21
	v_max3_f32 v49, v49, v42, v43
	s_add_i32 s75, s5, 0
	v_max3_f32 v48, v48, v40, v41
	v_max3_f32 v49, v49, v26, v27
	s_add_i32 s75, s75, 0x12000
	v_max3_f32 v48, v48, v24, v25
	v_max3_f32 v49, v49, v46, v47
	s_lshr_b32 s67, s6, 6
	v_max3_f32 v48, v48, v44, v45
	v_max3_f32 v49, v49, v30, v31
	s_cmp_lg_u32 0, -1
	v_max3_f32 v48, v48, v28, v29
	s_mov_b32 s10, 1
	v_max_f32_e32 v48, v48, v49
	s_mov_b32 s38, 0
	v_mov_b32_e32 v49, v48
	s_nop 1
	v_permlane32_swap_b32_e32 v48, v49
	v_max_f32_e32 v48, v48, v49
	v_lshlrev_b32_e32 v240, 4, v242
	v_add_f32_e32 v237, v213, v48
	v_sub_f32_e32 v16, v16, v48
	v_sub_f32_e32 v17, v17, v48
	v_sub_f32_e32 v32, v32, v48
	v_sub_f32_e32 v33, v33, v48
	v_sub_f32_e32 v34, v34, v48
	s_nop 0
	v_xor_b32_e32 v64, 0x80000000, v237
	v_mov_b32_e32 v65, v64
	v_mov_b32_e32 v66, v64
	v_mov_b32_e32 v67, v64
	v_mov_b32_e32 v68, v64
	v_mov_b32_e32 v69, v64
	v_mov_b32_e32 v70, v64
	v_mov_b32_e32 v71, v64
	v_mov_b32_e32 v72, v64
	v_mov_b32_e32 v73, v64
	v_mov_b32_e32 v74, v64
	v_mov_b32_e32 v75, v64
	v_mov_b32_e32 v76, v64
	v_mov_b32_e32 v77, v64
	v_mov_b32_e32 v78, v64
	v_mov_b32_e32 v79, v64
	s_waitcnt vmcnt(0) lgkmcnt(0)
	s_barrier
	v_exp_f32_e32 v80, v16
	v_exp_f32_e32 v81, v17
	v_lshl_add_u64 v[16:17], v[214:215], 0, s[18:19]
	s_mov_b32 m0, s76
	s_nop 0
	global_load_lds_dwordx4 v[16:17], off
	s_cselect_b32 s5, 0, 0
	s_add_i32 s4, s5, s4
	v_lshl_add_u64 v[16:17], v[216:217], 0, s[14:15]
	s_add_i32 s5, s4, 0xa000
	s_mov_b32 m0, s5
	s_nop 0
	global_load_lds_dwordx4 v[16:17], off
	v_lshl_add_u64 v[16:17], v[216:217], 0, s[20:21]
	s_add_i32 s4, s4, 0xc000
	s_mov_b32 m0, s4
	s_nop 0
	global_load_lds_dwordx4 v[16:17], off
	ds_read_b128 v[204:207], v238 offset:8192
	ds_read_b128 v[200:203], v238 offset:8704
	ds_read_b128 v[196:199], v238 offset:10240
	ds_read_b128 v[192:195], v238 offset:10752
	ds_read_b128 v[188:191], v238 offset:12288
	ds_read_b128 v[184:187], v238 offset:12800
	ds_read_b128 v[180:183], v238 offset:14336
	ds_read_b128 v[176:179], v238 offset:14848
	v_sub_f32_e32 v18, v18, v48
	v_sub_f32_e32 v35, v35, v48
	v_sub_f32_e32 v19, v19, v48
	v_sub_f32_e32 v36, v36, v48
	v_sub_f32_e32 v20, v20, v48
	v_sub_f32_e32 v37, v37, v48
	v_sub_f32_e32 v21, v21, v48
	v_sub_f32_e32 v38, v38, v48
	v_sub_f32_e32 v22, v22, v48
	v_sub_f32_e32 v39, v39, v48
	v_sub_f32_e32 v23, v23, v48
	v_sub_f32_e32 v40, v40, v48
	v_sub_f32_e32 v24, v24, v48
	v_sub_f32_e32 v41, v41, v48
	v_sub_f32_e32 v25, v25, v48
	v_sub_f32_e32 v42, v42, v48
	v_sub_f32_e32 v26, v26, v48
	v_sub_f32_e32 v43, v43, v48
	v_sub_f32_e32 v27, v27, v48
	v_sub_f32_e32 v44, v44, v48
	v_sub_f32_e32 v28, v28, v48
	v_sub_f32_e32 v45, v45, v48
	v_sub_f32_e32 v29, v29, v48
	v_sub_f32_e32 v46, v46, v48
	v_sub_f32_e32 v30, v30, v48
	v_sub_f32_e32 v47, v47, v48
	v_sub_f32_e32 v31, v31, v48
	v_exp_f32_e32 v96, v32
	v_exp_f32_e32 v97, v33
	v_exp_f32_e32 v98, v34
	v_exp_f32_e32 v99, v35
	v_exp_f32_e32 v100, v36
	v_exp_f32_e32 v101, v37
	v_exp_f32_e32 v102, v38
	v_exp_f32_e32 v103, v39
	v_exp_f32_e32 v104, v40
	v_exp_f32_e32 v105, v41
	v_exp_f32_e32 v106, v42
	v_exp_f32_e32 v107, v43
	v_exp_f32_e32 v108, v44
	v_exp_f32_e32 v109, v45
	v_exp_f32_e32 v110, v46
	v_exp_f32_e32 v111, v47
	v_exp_f32_e32 v82, v18
	v_exp_f32_e32 v83, v19
	v_exp_f32_e32 v84, v20
	v_exp_f32_e32 v85, v21
	v_exp_f32_e32 v86, v22
	v_exp_f32_e32 v87, v23
	v_exp_f32_e32 v88, v24
	v_exp_f32_e32 v89, v25
	v_exp_f32_e32 v90, v26
	v_exp_f32_e32 v91, v27
	v_exp_f32_e32 v92, v28
	v_exp_f32_e32 v93, v29
	v_exp_f32_e32 v94, v30
	v_exp_f32_e32 v95, v31
	s_waitcnt vmcnt(3) lgkmcnt(0)
	s_barrier
	v_cndmask_b32_e64 v16, 0, 1, s[8:9]
	s_add_i32 s70, s67, -5
	v_cmp_ne_u32_e64 s[6:7], 1, v16
	s_andn2_b64 vcc, exec, s[8:9]
	v_cmp_gt_u32_e64 s[8:9], 32, v231
	v_lshl_add_u32 v234, v230, 2, s75
	s_cbranch_vccnz .LBB0_1346
	v_mov_b64_e32 v[62:63], v[14:15]
	v_mov_b64_e32 v[46:47], v[14:15]
	v_mov_b64_e32 v[30:31], v[14:15]
	v_lshl_add_u64 v[220:221], v[218:219], 0, s[18:19]
	v_lshl_add_u64 v[222:223], v[216:217], 0, s[18:19]
	v_lshl_add_u64 v[224:225], v[214:215], 0, s[22:23]
	s_movk_i32 s38, 0x4000
	s_movk_i32 s11, 0x2000
	s_mov_b32 s4, 0
	v_mov_b32_e32 v241, 0
	v_mov_b64_e32 v[60:61], v[12:13]
	v_mov_b64_e32 v[58:59], v[10:11]
	v_mov_b64_e32 v[56:57], v[8:9]
	v_mov_b64_e32 v[54:55], v[6:7]
	v_mov_b64_e32 v[52:53], v[4:5]
	v_mov_b64_e32 v[50:51], v[2:3]
	v_mov_b64_e32 v[48:49], v[0:1]
	v_mov_b64_e32 v[44:45], v[12:13]
	v_mov_b64_e32 v[42:43], v[10:11]
	v_mov_b64_e32 v[40:41], v[8:9]
	v_mov_b64_e32 v[38:39], v[6:7]
	v_mov_b64_e32 v[36:37], v[4:5]
	v_mov_b64_e32 v[34:35], v[2:3]
	v_mov_b64_e32 v[32:33], v[0:1]
	v_mov_b64_e32 v[28:29], v[12:13]
	v_mov_b64_e32 v[26:27], v[10:11]
	v_mov_b64_e32 v[24:25], v[8:9]
	v_mov_b64_e32 v[22:23], v[6:7]
	v_mov_b64_e32 v[20:21], v[4:5]
	v_mov_b64_e32 v[18:19], v[2:3]
	v_mov_b64_e32 v[16:17], v[0:1]
.LBB0_1332:
	s_lshl_b32 s4, s4, 1
	v_add_u32_e32 v243, s4, v239
	ds_read_b64_tr_b16 v[208:209], v243 offset:24576
	ds_read_b64_tr_b16 v[210:211], v243 offset:25088
	s_waitcnt lgkmcnt(9)
	v_mfma_f32_32x32x16_bf16 v[128:143], v[204:207], v[172:175], v[64:79]
	v_add_f32_e32 v112, v96, v97
	v_add_f32_e32 v112, v98, v112
	v_add_f32_e32 v112, v99, v112
	v_add_f32_e32 v112, v100, v112
	v_add_f32_e32 v112, v101, v112
	v_cvt_pk_bf16_f32 v164, v96, v97
	v_cvt_pk_bf16_f32 v165, v98, v99
	ds_read_b64_tr_b16 v[96:97], v243 offset:28672
	ds_read_b64_tr_b16 v[98:99], v243 offset:29184
	v_add_f32_e32 v112, v102, v112
	v_add_f32_e32 v112, v103, v112
	v_add_f32_e32 v112, v104, v112
	v_add_f32_e32 v144, v105, v112
	s_waitcnt lgkmcnt(10)
	v_mfma_f32_32x32x16_bf16 v[112:127], v[200:203], v[172:175], v[64:79]
	v_cvt_pk_bf16_f32 v166, v100, v101
	v_cvt_pk_bf16_f32 v167, v102, v103
	ds_read_b64_tr_b16 v[100:101], v243 offset:25600
	ds_read_b64_tr_b16 v[102:103], v243 offset:26112
	s_waitcnt lgkmcnt(11)
	v_mfma_f32_32x32x16_bf16 v[128:143], v[196:199], v[168:171], v[128:143]
	v_add_f32_e32 v144, v106, v144
	v_add_f32_e32 v144, v107, v144
	v_add_f32_e32 v144, v108, v144
	v_add_f32_e32 v144, v109, v144
	v_cvt_pk_bf16_f32 v156, v104, v105
	v_cvt_pk_bf16_f32 v157, v106, v107
	ds_read_b64_tr_b16 v[104:105], v243 offset:29696
	ds_read_b64_tr_b16 v[106:107], v243 offset:30208
	s_waitcnt lgkmcnt(12)
	v_mfma_f32_32x32x16_bf16 v[112:127], v[192:195], v[168:171], v[112:127]
	v_add_f32_e32 v144, v110, v144
	v_add_f32_e32 v144, v111, v144
	v_add_f32_e32 v144, v80, v144
	v_add_f32_e32 v144, v81, v144
	v_cvt_pk_bf16_f32 v158, v108, v109
	v_cvt_pk_bf16_f32 v159, v110, v111
	ds_read_b64_tr_b16 v[108:109], v243 offset:26624
	ds_read_b64_tr_b16 v[110:111], v243 offset:27136
	s_waitcnt lgkmcnt(13)
	v_mfma_f32_32x32x16_bf16 v[128:143], v[188:191], v[160:163], v[128:143]
	v_add_f32_e32 v144, v82, v144
	v_add_f32_e32 v144, v83, v144
	v_add_f32_e32 v144, v84, v144
	v_add_f32_e32 v144, v85, v144
	v_cvt_pk_bf16_f32 v148, v80, v81
	v_cvt_pk_bf16_f32 v149, v82, v83
	ds_read_b64_tr_b16 v[80:81], v243 offset:30720
	ds_read_b64_tr_b16 v[82:83], v243 offset:31232
	s_waitcnt lgkmcnt(14)
	v_mfma_f32_32x32x16_bf16 v[112:127], v[184:187], v[160:163], v[112:127]
	v_add_f32_e32 v144, v86, v144
	v_add_f32_e32 v144, v87, v144
	v_add_f32_e32 v144, v88, v144
	v_add_f32_e32 v144, v89, v144
	v_cvt_pk_bf16_f32 v150, v84, v85
	v_cvt_pk_bf16_f32 v151, v86, v87
	ds_read_b64_tr_b16 v[84:85], v243 offset:27648
	ds_read_b64_tr_b16 v[86:87], v243 offset:28160
	s_waitcnt lgkmcnt(14)
	v_mfma_f32_32x32x16_bf16 v[128:143], v[180:183], v[152:155], v[128:143]
	v_add_f32_e32 v144, v90, v144
	v_add_f32_e32 v144, v91, v144
	v_add_f32_e32 v144, v92, v144
	v_add_f32_e32 v184, v93, v144
	v_cvt_pk_bf16_f32 v144, v88, v89
	v_cvt_pk_bf16_f32 v145, v90, v91
	ds_read_b64_tr_b16 v[88:89], v243 offset:31744
	ds_read_b64_tr_b16 v[90:91], v243 offset:32256
	v_mfma_f32_32x32x16_bf16 v[112:127], v[176:179], v[152:155], v[112:127]
	v_add_f32_e32 v146, v94, v184
	v_add_f32_e32 v146, v95, v146
	v_add_f32_e32 v180, 0, v146
	v_cvt_pk_bf16_f32 v146, v92, v93
	v_cvt_pk_bf16_f32 v147, v94, v95
	v_lshl_add_u64 v[92:93], v[224:225], 0, s[24:25]
	s_add_i32 s4, s11, s76
	s_mov_b32 m0, s4
	s_nop 0
	global_load_lds_dwordx4 v[92:93], off
	v_lshl_add_u64 v[92:93], v[222:223], 0, s[24:25]
	s_lshl_b32 s4, s38, 1
	s_add_i32 s4, s4, s77
	s_mov_b32 m0, s4
	s_nop 0
	global_load_lds_dwordx4 v[92:93], off
	v_lshl_add_u64 v[92:93], v[220:221], 0, s[24:25]
	s_addk_i32 s4, 0x2000
	s_mov_b32 m0, s4
	s_nop 0
	global_load_lds_dwordx4 v[92:93], off
	v_max_f32_e32 v92, v128, v129
	v_max3_f32 v93, v130, v131, v113
	v_max3_f32 v92, v92, v112, v114
	v_max3_f32 v92, v92, v115, v132
	v_max3_f32 v93, v93, v134, v135
	v_max3_f32 v92, v92, v133, v116
	v_max3_f32 v93, v93, v118, v119
	v_max3_f32 v92, v92, v117, v136
	v_max3_f32 v93, v93, v138, v139
	v_max3_f32 v92, v92, v137, v120
	v_max3_f32 v93, v93, v122, v123
	v_max3_f32 v92, v92, v121, v140
	v_max3_f32 v93, v93, v142, v143
	v_max3_f32 v92, v92, v141, v124
	v_max3_f32 v93, v93, v126, v127
	v_max3_f32 v92, v92, v125, v93
	v_mov_b32_e32 v93, v92
	s_nop 1
	v_permlane32_swap_b32_e32 v92, v93
	v_max_f32_e32 v92, v92, v93
	v_cmp_lt_f32_e32 vcc, s41, v92
	s_cmp_lg_u64 vcc, 0
	v_add_f32_e32 v241, v241, v180
	s_cselect_b64 s[36:37], -1, 0
	s_cbranch_vccnz .LBB0_1340

.LBB0_1335:
	s_add_i32 s4, s38, 0x2000
	s_cmpk_lg_i32 s38, 0x4000
	s_cselect_b32 s78, s4, 0
	s_lshl_b32 s4, s11, 1
	v_add_u32_e32 v209, s4, v239
	ds_read_b64_tr_b16 v[196:197], v209 offset:24576
	ds_read_b64_tr_b16 v[198:199], v209 offset:25088
	s_waitcnt lgkmcnt(9)
	v_mfma_f32_32x32x16_bf16 v[96:111], v[80:83], v[172:175], v[64:79]
	v_add_f32_e32 v84, v128, v129
	v_add_f32_e32 v84, v130, v84
	v_add_f32_e32 v84, v131, v84
	v_add_f32_e32 v84, v132, v84
	v_add_f32_e32 v84, v133, v84
	v_cvt_pk_bf16_f32 v164, v128, v129
	v_cvt_pk_bf16_f32 v165, v130, v131
	ds_read_b64_tr_b16 v[128:129], v209 offset:28672
	ds_read_b64_tr_b16 v[130:131], v209 offset:29184
	v_add_f32_e32 v80, v134, v84
	v_add_f32_e32 v80, v135, v80
	v_add_f32_e32 v80, v136, v80
	v_add_f32_e32 v144, v137, v80
	s_waitcnt lgkmcnt(10)
	v_mfma_f32_32x32x16_bf16 v[80:95], v[204:207], v[172:175], v[64:79]
	v_cvt_pk_bf16_f32 v166, v132, v133
	v_cvt_pk_bf16_f32 v167, v134, v135
	ds_read_b64_tr_b16 v[132:133], v209 offset:25600
	ds_read_b64_tr_b16 v[134:135], v209 offset:26112
	s_waitcnt lgkmcnt(11)
	v_mfma_f32_32x32x16_bf16 v[96:111], v[200:203], v[168:171], v[96:111]
	v_add_f32_e32 v144, v138, v144
	v_add_f32_e32 v144, v139, v144
	v_add_f32_e32 v144, v140, v144
	v_add_f32_e32 v144, v141, v144
	v_cvt_pk_bf16_f32 v156, v136, v137
	v_cvt_pk_bf16_f32 v157, v138, v139
	ds_read_b64_tr_b16 v[136:137], v209 offset:29696
	ds_read_b64_tr_b16 v[138:139], v209 offset:30208
	s_waitcnt lgkmcnt(12)
	v_mfma_f32_32x32x16_bf16 v[80:95], v[192:195], v[168:171], v[80:95]
	v_add_f32_e32 v144, v142, v144
	v_add_f32_e32 v144, v143, v144
	v_add_f32_e32 v144, v112, v144
	v_add_f32_e32 v144, v113, v144
	v_cvt_pk_bf16_f32 v158, v140, v141
	v_cvt_pk_bf16_f32 v159, v142, v143
	ds_read_b64_tr_b16 v[140:141], v209 offset:26624
	ds_read_b64_tr_b16 v[142:143], v209 offset:27136
	s_waitcnt lgkmcnt(13)
	v_mfma_f32_32x32x16_bf16 v[96:111], v[188:191], v[160:163], v[96:111]
	v_add_f32_e32 v144, v114, v144
	v_add_f32_e32 v144, v115, v144
	v_add_f32_e32 v144, v116, v144
	v_add_f32_e32 v144, v117, v144
	v_cvt_pk_bf16_f32 v148, v112, v113
	v_cvt_pk_bf16_f32 v149, v114, v115
	ds_read_b64_tr_b16 v[112:113], v209 offset:30720
	ds_read_b64_tr_b16 v[114:115], v209 offset:31232
	s_waitcnt lgkmcnt(14)
	v_mfma_f32_32x32x16_bf16 v[80:95], v[184:187], v[160:163], v[80:95]
	v_add_f32_e32 v144, v118, v144
	v_add_f32_e32 v144, v119, v144
	v_add_f32_e32 v144, v120, v144
	v_add_f32_e32 v144, v121, v144
	v_cvt_pk_bf16_f32 v150, v116, v117
	v_cvt_pk_bf16_f32 v151, v118, v119
	ds_read_b64_tr_b16 v[116:117], v209 offset:27648
	ds_read_b64_tr_b16 v[118:119], v209 offset:28160
	s_waitcnt lgkmcnt(14)
	v_mfma_f32_32x32x16_bf16 v[96:111], v[180:183], v[152:155], v[96:111]
	v_add_f32_e32 v144, v122, v144
	v_add_f32_e32 v144, v123, v144
	v_add_f32_e32 v144, v124, v144
	v_add_f32_e32 v184, v125, v144
	v_cvt_pk_bf16_f32 v144, v120, v121
	v_cvt_pk_bf16_f32 v145, v122, v123
	ds_read_b64_tr_b16 v[120:121], v209 offset:31744
	ds_read_b64_tr_b16 v[122:123], v209 offset:32256
	v_mfma_f32_32x32x16_bf16 v[80:95], v[176:179], v[152:155], v[80:95]
	v_add_f32_e32 v146, v126, v184
	v_add_f32_e32 v146, v127, v146
	v_add_f32_e32 v180, 0, v146
	v_cvt_pk_bf16_f32 v146, v124, v125
	v_cvt_pk_bf16_f32 v147, v126, v127
	v_max_f32_e32 v124, v96, v97
	s_nop 3
	s_nop 1
	v_max3_f32 v125, v98, v99, v81
	v_max3_f32 v124, v124, v80, v82
	v_max3_f32 v124, v124, v83, v100
	v_max3_f32 v125, v125, v102, v103
	v_max3_f32 v124, v124, v101, v84
	v_max3_f32 v125, v125, v86, v87
	v_max3_f32 v124, v124, v85, v104
	v_max3_f32 v125, v125, v106, v107
	v_max3_f32 v124, v124, v105, v88
	v_max3_f32 v125, v125, v90, v91
	v_max3_f32 v124, v124, v89, v108
	v_max3_f32 v125, v125, v110, v111
	v_max3_f32 v124, v124, v109, v92
	v_max3_f32 v125, v125, v94, v95
	v_max3_f32 v124, v124, v93, v125
	v_mov_b32_e32 v125, v124
	s_add_i32 s4, s38, s76
	s_nop 0
	v_permlane32_swap_b32_e32 v124, v125
	s_mov_b32 m0, s4
	s_nop 0
	global_load_lds_dwordx4 v[224:225], off
	s_lshl_b32 s4, s78, 1
	s_add_i32 s4, s4, s77
	s_mov_b32 m0, s4
	s_nop 0
	global_load_lds_dwordx4 v[222:223], off
	v_max_f32_e32 v124, v124, v125
	s_addk_i32 s4, 0x2000
	s_mov_b32 m0, s4
	s_nop 0
	global_load_lds_dwordx4 v[220:221], off
	v_cmp_lt_f32_e32 vcc, s41, v124
	s_cmp_lg_u64 vcc, 0
	v_add_f32_e32 v241, v241, v180
	s_cselect_b64 s[36:37], -1, 0
	s_cbranch_vccnz .LBB0_1343

.LBB0_1340:
	v_max_f32_e32 v92, 0, v92
	v_exp_f32_e64 v93, -v92
	v_add_f32_e32 v237, v237, v92
	v_xor_b32_e32 v64, 0x80000000, v237
	v_mov_b32_e32 v65, v64
	v_mov_b32_e32 v66, v64
	v_mov_b32_e32 v67, v64
	v_mov_b32_e32 v68, v64
	v_mov_b32_e32 v69, v64
	v_mov_b32_e32 v70, v64
	v_mov_b32_e32 v71, v64
	v_mov_b32_e32 v72, v64
	v_mov_b32_e32 v73, v64
	v_mov_b32_e32 v74, v64
	v_mov_b32_e32 v75, v64
	v_mov_b32_e32 v76, v64
	v_mov_b32_e32 v77, v64
	v_mov_b32_e32 v78, v64
	v_mov_b32_e32 v79, v64
	s_and_saveexec_b64 s[4:5], s[8:9]
	ds_write_b32 v234, v93
	s_or_b64 exec, exec, s[4:5]
	v_sub_f32_e32 v143, v143, v92
	v_sub_f32_e32 v142, v142, v92
	v_sub_f32_e32 v141, v141, v92
	v_sub_f32_e32 v140, v140, v92
	v_sub_f32_e32 v139, v139, v92
	v_sub_f32_e32 v138, v138, v92
	v_sub_f32_e32 v137, v137, v92
	v_sub_f32_e32 v136, v136, v92
	v_sub_f32_e32 v135, v135, v92
	v_sub_f32_e32 v134, v134, v92
	v_sub_f32_e32 v133, v133, v92
	v_sub_f32_e32 v132, v132, v92
	v_sub_f32_e32 v131, v131, v92
	v_sub_f32_e32 v130, v130, v92
	v_sub_f32_e32 v129, v129, v92
	v_sub_f32_e32 v128, v128, v92
	v_sub_f32_e32 v127, v127, v92
	v_sub_f32_e32 v126, v126, v92
	v_sub_f32_e32 v125, v125, v92
	v_sub_f32_e32 v124, v124, v92
	v_sub_f32_e32 v123, v123, v92
	v_sub_f32_e32 v122, v122, v92
	v_sub_f32_e32 v121, v121, v92
	v_sub_f32_e32 v120, v120, v92
	v_sub_f32_e32 v119, v119, v92
	v_sub_f32_e32 v118, v118, v92
	v_sub_f32_e32 v117, v117, v92
	v_sub_f32_e32 v116, v116, v92
	v_sub_f32_e32 v115, v115, v92
	v_sub_f32_e32 v114, v114, v92
	v_sub_f32_e32 v113, v113, v92
	v_sub_f32_e32 v112, v112, v92
	v_mul_f32_e32 v241, v241, v93
	s_branch .LBB0_1333
.LBB0_1343:
	v_max_f32_e32 v124, 0, v124
	v_exp_f32_e64 v125, -v124
	v_add_f32_e32 v237, v237, v124
	v_xor_b32_e32 v64, 0x80000000, v237
	v_mov_b32_e32 v65, v64
	v_mov_b32_e32 v66, v64
	v_mov_b32_e32 v67, v64
	v_mov_b32_e32 v68, v64
	v_mov_b32_e32 v69, v64
	v_mov_b32_e32 v70, v64
	v_mov_b32_e32 v71, v64
	v_mov_b32_e32 v72, v64
	v_mov_b32_e32 v73, v64
	v_mov_b32_e32 v74, v64
	v_mov_b32_e32 v75, v64
	v_mov_b32_e32 v76, v64
	v_mov_b32_e32 v77, v64
	v_mov_b32_e32 v78, v64
	v_mov_b32_e32 v79, v64
	s_and_saveexec_b64 s[4:5], s[8:9]
	ds_write_b32 v234, v125
	s_or_b64 exec, exec, s[4:5]
	v_sub_f32_e32 v111, v111, v124
	v_sub_f32_e32 v110, v110, v124
	v_sub_f32_e32 v109, v109, v124
	v_sub_f32_e32 v108, v108, v124
	v_sub_f32_e32 v107, v107, v124
	v_sub_f32_e32 v106, v106, v124
	v_sub_f32_e32 v105, v105, v124
	v_sub_f32_e32 v104, v104, v124
	v_sub_f32_e32 v103, v103, v124
	v_sub_f32_e32 v102, v102, v124
	v_sub_f32_e32 v101, v101, v124
	v_sub_f32_e32 v100, v100, v124
	v_sub_f32_e32 v99, v99, v124
	v_sub_f32_e32 v98, v98, v124
	v_sub_f32_e32 v97, v97, v124
	v_sub_f32_e32 v96, v96, v124
	v_sub_f32_e32 v95, v95, v124
	v_sub_f32_e32 v94, v94, v124
	v_sub_f32_e32 v93, v93, v124
	v_sub_f32_e32 v92, v92, v124
	v_sub_f32_e32 v91, v91, v124
	v_sub_f32_e32 v90, v90, v124
	v_sub_f32_e32 v89, v89, v124
	v_sub_f32_e32 v88, v88, v124
	v_sub_f32_e32 v87, v87, v124
	v_sub_f32_e32 v86, v86, v124
	v_sub_f32_e32 v85, v85, v124
	v_sub_f32_e32 v84, v84, v124
	v_sub_f32_e32 v83, v83, v124
	v_sub_f32_e32 v82, v82, v124
	v_sub_f32_e32 v81, v81, v124
	v_sub_f32_e32 v80, v80, v124
	v_mul_f32_e32 v241, v241, v125
	s_branch .LBB0_1336

.LBB0_1350:
	v_add_u32_e32 v208, s83, v239
	ds_read_b64_tr_b16 v[128:129], v208 offset:24576
	ds_read_b64_tr_b16 v[130:131], v208 offset:25088
	v_add_f32_e32 v112, v96, v97
	v_add_f32_e32 v112, v98, v112
	v_add_f32_e32 v112, v99, v112
	v_add_f32_e32 v112, v100, v112
	v_add_f32_e32 v136, v101, v112
	s_waitcnt lgkmcnt(9)
	v_mfma_f32_32x32x16_bf16 v[112:127], v[204:207], v[172:175], v[64:79]
	v_cvt_pk_bf16_f32 v164, v96, v97
	v_cvt_pk_bf16_f32 v165, v98, v99
	ds_read_b64_tr_b16 v[132:133], v208 offset:28672
	ds_read_b64_tr_b16 v[134:135], v208 offset:29184
	s_waitcnt lgkmcnt(10)
	v_mfma_f32_32x32x16_bf16 v[64:79], v[200:203], v[172:175], v[64:79]
	v_add_f32_e32 v96, v102, v136
	v_add_f32_e32 v96, v103, v96
	v_add_f32_e32 v96, v104, v96
	v_add_f32_e32 v96, v105, v96
	v_cvt_pk_bf16_f32 v166, v100, v101
	v_cvt_pk_bf16_f32 v167, v102, v103
	ds_read_b64_tr_b16 v[136:137], v208 offset:25600
	ds_read_b64_tr_b16 v[138:139], v208 offset:26112
	s_waitcnt lgkmcnt(11)
	v_mfma_f32_32x32x16_bf16 v[112:127], v[196:199], v[168:171], v[112:127]
	v_add_f32_e32 v96, v106, v96
	v_add_f32_e32 v96, v107, v96
	v_add_f32_e32 v96, v108, v96
	v_add_f32_e32 v96, v109, v96
	v_cvt_pk_bf16_f32 v156, v104, v105
	v_cvt_pk_bf16_f32 v157, v106, v107
	ds_read_b64_tr_b16 v[140:141], v208 offset:29696
	ds_read_b64_tr_b16 v[142:143], v208 offset:30208
	s_waitcnt lgkmcnt(12)
	v_mfma_f32_32x32x16_bf16 v[64:79], v[192:195], v[168:171], v[64:79]
	v_add_f32_e32 v96, v110, v96
	v_add_f32_e32 v96, v111, v96
	v_add_f32_e32 v96, v80, v96
	v_add_f32_e32 v96, v81, v96
	v_cvt_pk_bf16_f32 v158, v108, v109
	v_cvt_pk_bf16_f32 v159, v110, v111
	ds_read_b64_tr_b16 v[168:169], v208 offset:26624
	ds_read_b64_tr_b16 v[170:171], v208 offset:27136
	s_waitcnt lgkmcnt(13)
	v_mfma_f32_32x32x16_bf16 v[112:127], v[188:191], v[160:163], v[112:127]
	v_add_f32_e32 v96, v82, v96
	v_add_f32_e32 v96, v83, v96
	v_add_f32_e32 v96, v84, v96
	v_add_f32_e32 v96, v85, v96
	v_cvt_pk_bf16_f32 v148, v80, v81
	v_cvt_pk_bf16_f32 v149, v82, v83
	ds_read_b64_tr_b16 v[172:173], v208 offset:30720
	ds_read_b64_tr_b16 v[174:175], v208 offset:31232
	s_waitcnt lgkmcnt(14)
	v_mfma_f32_32x32x16_bf16 v[64:79], v[184:187], v[160:163], v[64:79]
	v_add_f32_e32 v80, v86, v96
	v_add_f32_e32 v80, v87, v80
	v_add_f32_e32 v80, v88, v80
	v_add_f32_e32 v80, v89, v80
	v_cvt_pk_bf16_f32 v150, v84, v85
	v_cvt_pk_bf16_f32 v151, v86, v87
	ds_read_b64_tr_b16 v[160:161], v208 offset:27648
	ds_read_b64_tr_b16 v[162:163], v208 offset:28160
	s_waitcnt lgkmcnt(14)
	v_mfma_f32_32x32x16_bf16 v[112:127], v[180:183], v[152:155], v[112:127]
	v_add_f32_e32 v80, v90, v80
	v_add_f32_e32 v80, v91, v80
	v_add_f32_e32 v80, v92, v80
	v_add_f32_e32 v80, v93, v80
	v_cvt_pk_bf16_f32 v144, v88, v89
	v_cvt_pk_bf16_f32 v145, v90, v91
	ds_read_b64_tr_b16 v[180:181], v208 offset:31744
	ds_read_b64_tr_b16 v[182:183], v208 offset:32256
	v_mfma_f32_32x32x16_bf16 v[64:79], v[176:179], v[152:155], v[64:79]
	v_add_f32_e32 v80, v94, v80
	v_add_f32_e32 v80, v95, v80
	v_add_f32_e32 v96, 0, v80
	v_cvt_pk_bf16_f32 v146, v92, v93
	v_cvt_pk_bf16_f32 v147, v94, v95
	v_or_b32_e32 v81, 0xe0, v212
	v_or_b32_e32 v80, 0xc0, v212
	v_cmp_le_i32_e32 vcc, v81, v236
	v_or_b32_e32 v82, 0xe1, v212
	v_or_b32_e32 v83, 0xe2, v212
	s_nop 1
	v_cndmask_b32_e32 v64, v228, v64, vcc
	v_cmp_lt_i32_e32 vcc, v80, v236
	v_or_b32_e32 v84, 0xe3, v212
	v_or_b32_e32 v85, 0xe8, v212
	v_cndmask_b32_e32 v81, v228, v113, vcc
	v_cmp_le_i32_e32 vcc, v80, v236
	v_or_b32_e32 v86, 0xe9, v212
	v_or_b32_e32 v87, 0xea, v212
	v_cndmask_b32_e32 v80, v228, v112, vcc
	v_cmp_le_i32_e32 vcc, v82, v236
	v_or_b32_e32 v82, 0xc2, v212
	v_or_b32_e32 v88, 0xeb, v212
	v_cndmask_b32_e32 v65, v228, v65, vcc
	v_cmp_le_i32_e32 vcc, v82, v236
	v_or_b32_e32 v89, 0xf0, v212
	v_or_b32_e32 v90, 0xf1, v212
	v_cndmask_b32_e32 v82, v228, v114, vcc
	v_cmp_le_i32_e32 vcc, v83, v236
	v_or_b32_e32 v83, 0xc3, v212
	v_or_b32_e32 v91, 0xf2, v212
	v_cndmask_b32_e32 v66, v228, v66, vcc
	v_cmp_le_i32_e32 vcc, v83, v236
	v_or_b32_e32 v92, 0xf3, v212
	v_or_b32_e32 v93, 0xf8, v212
	v_cndmask_b32_e32 v83, v228, v115, vcc
	v_cmp_le_i32_e32 vcc, v84, v236
	v_or_b32_e32 v84, 0xc8, v212
	v_or_b32_e32 v94, 0xf9, v212
	v_cndmask_b32_e32 v67, v228, v67, vcc
	v_cmp_le_i32_e32 vcc, v84, v236
	v_or_b32_e32 v95, 0xfa, v212
	v_or_b32_e32 v97, 0xfb, v212
	v_cndmask_b32_e32 v84, v228, v116, vcc
	v_cmp_le_i32_e32 vcc, v85, v236
	v_or_b32_e32 v85, 0xc9, v212
	s_nop 0
	v_cndmask_b32_e32 v68, v228, v68, vcc
	v_cmp_le_i32_e32 vcc, v85, v236
	v_add_f32_e32 v112, v241, v96
	s_nop 0
	v_cndmask_b32_e32 v85, v228, v117, vcc
	v_cmp_le_i32_e32 vcc, v86, v236
	v_or_b32_e32 v86, 0xca, v212
	s_nop 0
	v_cndmask_b32_e32 v69, v228, v69, vcc
	v_cmp_le_i32_e32 vcc, v86, v236
	s_nop 1
	v_cndmask_b32_e32 v86, v228, v118, vcc
	v_cmp_le_i32_e32 vcc, v87, v236
	v_or_b32_e32 v87, 0xcb, v212
	s_nop 0
	v_cndmask_b32_e32 v70, v228, v70, vcc
	v_cmp_le_i32_e32 vcc, v87, v236
	s_nop 1
	v_cndmask_b32_e32 v87, v228, v119, vcc
	v_cmp_le_i32_e32 vcc, v88, v236
	v_or_b32_e32 v88, 0xd0, v212
	s_nop 0
	v_cndmask_b32_e32 v71, v228, v71, vcc
	v_cmp_le_i32_e32 vcc, v88, v236
	s_nop 1
	v_cndmask_b32_e32 v88, v228, v120, vcc
	v_cmp_le_i32_e32 vcc, v89, v236
	v_or_b32_e32 v89, 0xd1, v212
	s_nop 0
	v_cndmask_b32_e32 v72, v228, v72, vcc
	v_cmp_le_i32_e32 vcc, v89, v236
	s_nop 1
	v_cndmask_b32_e32 v89, v228, v121, vcc
	v_cmp_le_i32_e32 vcc, v90, v236
	v_or_b32_e32 v90, 0xd2, v212
	s_nop 0
	v_cndmask_b32_e32 v73, v228, v73, vcc
	v_cmp_le_i32_e32 vcc, v90, v236
	s_nop 1
	v_cndmask_b32_e32 v90, v228, v122, vcc
	v_cmp_le_i32_e32 vcc, v91, v236
	v_or_b32_e32 v91, 0xd3, v212
	s_nop 0
	v_cndmask_b32_e32 v74, v228, v74, vcc
	v_cmp_le_i32_e32 vcc, v91, v236
	s_nop 1
	v_cndmask_b32_e32 v91, v228, v123, vcc
	v_cmp_le_i32_e32 vcc, v92, v236
	v_or_b32_e32 v92, 0xd8, v212
	s_nop 0
	v_cndmask_b32_e32 v75, v228, v75, vcc
	v_cmp_le_i32_e32 vcc, v92, v236
	s_nop 1
	v_cndmask_b32_e32 v92, v228, v124, vcc
	v_cmp_le_i32_e32 vcc, v93, v236
	v_or_b32_e32 v93, 0xd9, v212
	s_nop 0
	v_cndmask_b32_e32 v76, v228, v76, vcc
	v_cmp_le_i32_e32 vcc, v93, v236
	s_nop 1
	v_cndmask_b32_e32 v93, v228, v125, vcc
	v_cmp_le_i32_e32 vcc, v94, v236
	v_or_b32_e32 v94, 0xda, v212
	s_nop 0
	v_cndmask_b32_e32 v77, v228, v77, vcc
	v_cmp_le_i32_e32 vcc, v94, v236
	s_nop 1
	v_cndmask_b32_e32 v94, v228, v126, vcc
	v_cmp_le_i32_e32 vcc, v95, v236
	v_or_b32_e32 v95, 0xdb, v212
	s_nop 0
	v_cndmask_b32_e32 v78, v228, v78, vcc
	v_cmp_le_i32_e32 vcc, v95, v236
	s_nop 1
	v_cndmask_b32_e32 v95, v228, v127, vcc
	v_cmp_le_i32_e32 vcc, v97, v236
	v_max_f32_e32 v97, v80, v81
	v_max3_f32 v98, v82, v83, v65
	v_max3_f32 v97, v97, v64, v66
	v_max3_f32 v97, v97, v67, v84
	v_max3_f32 v98, v98, v86, v87
	v_max3_f32 v97, v97, v85, v68
	v_max3_f32 v98, v98, v70, v71
	v_max3_f32 v97, v97, v69, v88
	v_max3_f32 v98, v98, v90, v91
	v_max3_f32 v97, v97, v89, v72
	v_max3_f32 v98, v98, v74, v75
	v_cndmask_b32_e32 v79, v228, v79, vcc
	v_max3_f32 v97, v97, v73, v92
	v_max3_f32 v98, v98, v94, v95
	v_max3_f32 v97, v97, v93, v76
	v_max3_f32 v98, v98, v78, v79
	v_max3_f32 v96, v97, v77, v98
	v_mov_b32_e32 v97, v96
	s_nop 1
	v_permlane32_swap_b32_e32 v96, v97
	v_max_f32_e32 v96, v96, v97
	v_cmp_lt_f32_e32 vcc, s41, v96
	s_cmp_lg_u64 vcc, 0
	s_cselect_b64 s[8:9], -1, 0
	s_cbranch_vccnz .LBB0_1482

.LBB0_1353:
	v_add_f32_e32 v97, v80, v81
	v_add_f32_e32 v97, v82, v97
	v_add_f32_e32 v97, v83, v97
	v_add_f32_e32 v97, v84, v97
	v_add_f32_e32 v97, v85, v97
	v_add_f32_e32 v97, v86, v97
	v_add_f32_e32 v97, v87, v97
	v_add_f32_e32 v97, v88, v97
	v_add_f32_e32 v97, v89, v97
	v_add_f32_e32 v97, v90, v97
	v_add_f32_e32 v97, v91, v97
	v_add_f32_e32 v97, v92, v97
	v_add_f32_e32 v97, v93, v97
	v_add_f32_e32 v97, v94, v97
	v_add_f32_e32 v97, v95, v97
	v_add_f32_e32 v97, v97, v64
	v_add_f32_e32 v97, v65, v97
	v_add_f32_e32 v97, v66, v97
	v_add_f32_e32 v97, v67, v97
	v_add_f32_e32 v97, v68, v97
	v_add_f32_e32 v97, v69, v97
	v_add_f32_e32 v97, v70, v97
	v_add_f32_e32 v97, v71, v97
	v_add_f32_e32 v97, v72, v97
	v_add_f32_e32 v97, v73, v97
	v_add_f32_e32 v97, v74, v97
	v_add_f32_e32 v97, v75, v97
	v_add_f32_e32 v97, v76, v97
	v_add_f32_e32 v97, v77, v97
	s_cmp_lg_u32 0, -1
	v_add_f32_e32 v97, v78, v97
	s_cselect_b32 s4, 0, 0
	v_add_f32_e32 v97, v79, v97
	s_addk_i32 s4, 0x6000
	v_add_f32_e32 v97, v112, v97
	v_cvt_pk_bf16_f32 v64, v64, v65
	v_add3_u32 v98, v235, s4, v232
	v_cvt_pk_bf16_f32 v80, v80, v81
	v_cvt_pk_bf16_f32 v81, v82, v83
	v_cvt_pk_bf16_f32 v82, v84, v85
	v_cvt_pk_bf16_f32 v83, v86, v87
	v_cvt_pk_bf16_f32 v84, v88, v89
	v_cvt_pk_bf16_f32 v85, v90, v91
	v_cvt_pk_bf16_f32 v86, v92, v93
	v_cvt_pk_bf16_f32 v87, v94, v95
	v_cvt_pk_bf16_f32 v65, v66, v67
	v_cvt_pk_bf16_f32 v66, v68, v69
	v_cvt_pk_bf16_f32 v67, v70, v71
	v_cvt_pk_bf16_f32 v68, v72, v73
	v_cvt_pk_bf16_f32 v69, v74, v75
	v_cvt_pk_bf16_f32 v70, v76, v77
	v_cvt_pk_bf16_f32 v71, v78, v79
	s_lshl_b32 s4, s78, 1
	v_add3_u32 v102, v98, v233, s4
	ds_read_b64_tr_b16 v[72:73],v102 offset:0
	ds_read_b64_tr_b16 v[74:75],v102 offset:512
	ds_read_b64_tr_b16 v[76:77],v102 offset:1024
	ds_read_b64_tr_b16 v[78:79],v102 offset:1536
	ds_read_b64_tr_b16 v[88:89],v102 offset:2048
	ds_read_b64_tr_b16 v[90:91],v102 offset:2560
	ds_read_b64_tr_b16 v[92:93],v102 offset:3072
	ds_read_b64_tr_b16 v[94:95],v102 offset:3584
	s_waitcnt lgkmcnt(0)
	s_nop 0
	v_mfma_f32_32x32x16_bf16 v[48:63], v[80:83], v[72:75], v[48:63]
	ds_read_b64_tr_b16 v[72:73],v102 offset:4096
	ds_read_b64_tr_b16 v[74:75],v102 offset:4608
	v_mfma_f32_32x32x16_bf16 v[48:63], v[84:87], v[76:79], v[48:63]
	ds_read_b64_tr_b16 v[76:77],v102 offset:5120
	ds_read_b64_tr_b16 v[78:79],v102 offset:5632
	v_mfma_f32_32x32x16_bf16 v[48:63], v[64:67], v[88:91], v[48:63]
	ds_read_b64_tr_b16 v[88:89],v102 offset:6144
	ds_read_b64_tr_b16 v[90:91],v102 offset:6656
	ds_read_b64_tr_b16 v[98:99],v102 offset:7168
	ds_read_b64_tr_b16 v[100:101],v102 offset:7680
	s_waitcnt lgkmcnt(0)
	v_mfma_f32_32x32x16_bf16 v[48:63], v[68:71], v[92:95], v[48:63]
	v_mfma_f32_32x32x16_bf16 v[32:47], v[80:83], v[72:75], v[32:47]
	ds_read_b64_tr_b16 v[72:73],v102 offset:8192
	ds_read_b64_tr_b16 v[74:75],v102 offset:8704
	v_mfma_f32_32x32x16_bf16 v[32:47], v[84:87], v[76:79], v[32:47]
	ds_read_b64_tr_b16 v[76:77],v102 offset:9216
	ds_read_b64_tr_b16 v[78:79],v102 offset:9728
	v_mfma_f32_32x32x16_bf16 v[32:47], v[64:67], v[88:91], v[32:47]
	ds_read_b64_tr_b16 v[88:89],v102 offset:10240
	ds_read_b64_tr_b16 v[90:91],v102 offset:10752
	ds_read_b64_tr_b16 v[92:93],v102 offset:11264
	ds_read_b64_tr_b16 v[94:95],v102 offset:11776
	s_waitcnt lgkmcnt(0)
	v_mfma_f32_32x32x16_bf16 v[32:47], v[68:71], v[98:101], v[32:47]
	v_mfma_f32_32x32x16_bf16 v[16:31], v[80:83], v[72:75], v[16:31]
	ds_read_b64_tr_b16 v[72:73],v102 offset:12288
	ds_read_b64_tr_b16 v[74:75],v102 offset:12800
	v_mfma_f32_32x32x16_bf16 v[16:31], v[84:87], v[76:79], v[16:31]
	ds_read_b64_tr_b16 v[76:77],v102 offset:13312
	ds_read_b64_tr_b16 v[78:79],v102 offset:13824
	v_mfma_f32_32x32x16_bf16 v[16:31], v[64:67], v[88:91], v[16:31]
	ds_read_b64_tr_b16 v[88:89],v102 offset:14336
	ds_read_b64_tr_b16 v[90:91],v102 offset:14848
	ds_read_b64_tr_b16 v[98:99],v102 offset:15360
	ds_read_b64_tr_b16 v[100:101],v102 offset:15872
	s_waitcnt lgkmcnt(0)
	v_mfma_f32_32x32x16_bf16 v[16:31], v[68:71], v[92:95], v[16:31]
	v_mfma_f32_32x32x16_bf16 v[0:15], v[80:83], v[72:75], v[0:15]
	v_cmp_gt_u32_e32 vcc, 32, v231
	v_mfma_f32_32x32x16_bf16 v[0:15], v[84:87], v[76:79], v[0:15]
	v_mfma_f32_32x32x16_bf16 v[0:15], v[64:67], v[88:91], v[0:15]
	v_mov_b32_e32 v64, v97
	s_nop 1
	v_permlane32_swap_b32_e32 v97, v64
	v_mfma_f32_32x32x16_bf16 v[0:15], v[68:71], v[98:101], v[0:15]
	s_and_saveexec_b64 s[4:5], vcc
	v_add_f32_e32 v64, v97, v64
	ds_write_b32 v234, v64 offset:128
	s_or_b64 exec, exec, s[4:5]
	s_waitcnt lgkmcnt(0)
	ds_read_b128 v[64:67], v96 offset:128
	ds_read_b128 v[68:71], v96 offset:160
	s_lshl_b32 s4, s74, 13
	s_add_i32 s4, s4, 0
	s_add_i32 s4, s4, 0x12800
	s_waitcnt lgkmcnt(1)
	v_rcp_f32_e32 v72, v64
	v_rcp_f32_e32 v73, v65
	v_lshl_add_u32 v80, v230, 1, s4
	v_lshlrev_b32_e32 v81, 8, v212
	v_mul_f32_e32 v0, v0, v72
	v_add_u32_e32 v82, v80, v81
	v_cvt_pk_bf16_f32 v0, v0, s0
	v_rcp_f32_e32 v74, v66
	v_rcp_f32_e32 v75, v67
	s_waitcnt lgkmcnt(0)
	v_rcp_f32_e32 v76, v68
	ds_read_b128 v[64:67], v96 offset:192
	v_rcp_f32_e32 v77, v69
	v_rcp_f32_e32 v78, v70
	v_rcp_f32_e32 v79, v71
	ds_read_b128 v[68:71], v96 offset:224
	ds_write_b16 v82, v0 offset:192
	v_mul_f32_e32 v0, v49, v73
	v_cvt_pk_bf16_f32 v0, v0, s0
	ds_write_b16 v82, v0 offset:256
	v_mul_f32_e32 v0, v33, v73
	v_cvt_pk_bf16_f32 v0, v0, s0
	ds_write_b16 v82, v0 offset:320
	v_mul_f32_e32 v0, v17, v73
	v_cvt_pk_bf16_f32 v0, v0, s0
	ds_write_b16 v82, v0 offset:384
	v_mul_f32_e32 v0, v1, v73
	v_cvt_pk_bf16_f32 v0, v0, s0
	ds_write_b16 v82, v0 offset:448
	v_mul_f32_e32 v0, v50, v74
	v_cvt_pk_bf16_f32 v0, v0, s0
	ds_write_b16 v82, v0 offset:512
	v_mul_f32_e32 v0, v34, v74
	v_cvt_pk_bf16_f32 v0, v0, s0
	ds_write_b16 v82, v0 offset:576
	v_mul_f32_e32 v0, v18, v74
	v_cvt_pk_bf16_f32 v0, v0, s0
	ds_write_b16 v82, v0 offset:640
	v_mul_f32_e32 v0, v2, v74
	v_cvt_pk_bf16_f32 v0, v0, s0
	ds_write_b16 v82, v0 offset:704
	v_mul_f32_e32 v0, v51, v75
	v_cvt_pk_bf16_f32 v0, v0, s0
	ds_write_b16 v82, v0 offset:768
	v_mul_f32_e32 v0, v35, v75
	v_cvt_pk_bf16_f32 v0, v0, s0
	ds_write_b16 v82, v0 offset:832
	v_mul_f32_e32 v0, v19, v75
	v_cvt_pk_bf16_f32 v0, v0, s0
	ds_write_b16 v82, v0 offset:896
	v_mul_f32_e32 v0, v3, v75
	v_cvt_pk_bf16_f32 v0, v0, s0
	v_mul_f32_e32 v48, v48, v72
	v_mul_f32_e32 v32, v32, v72
	v_mul_f32_e32 v16, v16, v72
	ds_write_b16 v82, v0 offset:960
	v_or_b32_e32 v0, 0x800, v81
	v_mul_f32_e32 v1, v52, v76
	v_cvt_pk_bf16_f32 v48, v48, s0
	v_cvt_pk_bf16_f32 v32, v32, s0
	v_cvt_pk_bf16_f32 v16, v16, s0
	v_add_u32_e32 v0, v80, v0
	v_cvt_pk_bf16_f32 v1, v1, s0
	ds_write_b16 v82, v48
	ds_write_b16 v82, v32 offset:64
	ds_write_b16 v82, v16 offset:128
	ds_write_b16 v0, v1
	v_mul_f32_e32 v1, v36, v76
	v_cvt_pk_bf16_f32 v1, v1, s0
	ds_write_b16 v0, v1 offset:64
	v_mul_f32_e32 v1, v20, v76
	v_cvt_pk_bf16_f32 v1, v1, s0
	ds_write_b16 v0, v1 offset:128
	v_mul_f32_e32 v1, v4, v76
	v_cvt_pk_bf16_f32 v1, v1, s0
	ds_write_b16 v0, v1 offset:192
	v_or_b32_e32 v0, 0x900, v81
	v_mul_f32_e32 v1, v53, v77
	v_add_u32_e32 v0, v80, v0
	v_cvt_pk_bf16_f32 v1, v1, s0
	ds_write_b16 v0, v1
	v_mul_f32_e32 v1, v37, v77
	v_cvt_pk_bf16_f32 v1, v1, s0
	ds_write_b16 v0, v1 offset:64
	v_mul_f32_e32 v1, v21, v77
	v_cvt_pk_bf16_f32 v1, v1, s0
	ds_write_b16 v0, v1 offset:128
	v_mul_f32_e32 v1, v5, v77
	v_cvt_pk_bf16_f32 v1, v1, s0
	ds_write_b16 v0, v1 offset:192
	v_or_b32_e32 v0, 0xa00, v81
	v_mul_f32_e32 v1, v54, v78
	v_add_u32_e32 v0, v80, v0
	v_cvt_pk_bf16_f32 v1, v1, s0
	ds_write_b16 v0, v1
	v_mul_f32_e32 v1, v38, v78
	v_cvt_pk_bf16_f32 v1, v1, s0
	ds_write_b16 v0, v1 offset:64
	v_mul_f32_e32 v1, v22, v78
	v_cvt_pk_bf16_f32 v1, v1, s0
	ds_write_b16 v0, v1 offset:128
	v_mul_f32_e32 v1, v6, v78
	v_cvt_pk_bf16_f32 v1, v1, s0
	ds_write_b16 v0, v1 offset:192
	v_or_b32_e32 v0, 0xb00, v81
	v_mul_f32_e32 v1, v55, v79
	v_add_u32_e32 v0, v80, v0
	v_cvt_pk_bf16_f32 v1, v1, s0
	ds_write_b16 v0, v1
	v_mul_f32_e32 v1, v39, v79
	v_cvt_pk_bf16_f32 v1, v1, s0
	s_waitcnt lgkmcnt(14)
	v_rcp_f32_e32 v64, v64
	ds_write_b16 v0, v1 offset:64
	v_mul_f32_e32 v1, v23, v79
	v_cvt_pk_bf16_f32 v1, v1, s0
	ds_write_b16 v0, v1 offset:128
	v_mul_f32_e32 v1, v7, v79
	v_cvt_pk_bf16_f32 v1, v1, s0
	ds_write_b16 v0, v1 offset:192
	v_or_b32_e32 v0, 0x1000, v81
	v_mul_f32_e32 v1, v56, v64
	v_add_u32_e32 v0, v80, v0
	v_cvt_pk_bf16_f32 v1, v1, s0
	ds_write_b16 v0, v1
	v_mul_f32_e32 v1, v40, v64
	v_cvt_pk_bf16_f32 v1, v1, s0
	v_rcp_f32_e32 v65, v65
	ds_write_b16 v0, v1 offset:64
	v_mul_f32_e32 v1, v24, v64
	v_cvt_pk_bf16_f32 v1, v1, s0
	ds_write_b16 v0, v1 offset:128
	v_mul_f32_e32 v1, v8, v64
	v_cvt_pk_bf16_f32 v1, v1, s0
	ds_write_b16 v0, v1 offset:192
	v_or_b32_e32 v0, 0x1100, v81
	v_mul_f32_e32 v1, v57, v65
	v_add_u32_e32 v0, v80, v0
	v_cvt_pk_bf16_f32 v1, v1, s0
	ds_write_b16 v0, v1
	v_mul_f32_e32 v1, v41, v65
	v_cvt_pk_bf16_f32 v1, v1, s0
	v_rcp_f32_e32 v66, v66
	ds_write_b16 v0, v1 offset:64
	v_mul_f32_e32 v1, v25, v65
	v_cvt_pk_bf16_f32 v1, v1, s0
	ds_write_b16 v0, v1 offset:128
	v_mul_f32_e32 v1, v9, v65
	v_cvt_pk_bf16_f32 v1, v1, s0
	ds_write_b16 v0, v1 offset:192
	v_or_b32_e32 v0, 0x1200, v81
	v_mul_f32_e32 v1, v58, v66
	v_add_u32_e32 v0, v80, v0
	v_cvt_pk_bf16_f32 v1, v1, s0
	ds_write_b16 v0, v1
	v_mul_f32_e32 v1, v42, v66
	v_cvt_pk_bf16_f32 v1, v1, s0
	v_rcp_f32_e32 v67, v67
	ds_write_b16 v0, v1 offset:64
	v_mul_f32_e32 v1, v26, v66
	v_cvt_pk_bf16_f32 v1, v1, s0
	ds_write_b16 v0, v1 offset:128
	v_mul_f32_e32 v1, v10, v66
	v_cvt_pk_bf16_f32 v1, v1, s0
	ds_write_b16 v0, v1 offset:192
	v_or_b32_e32 v0, 0x1300, v81
	v_mul_f32_e32 v1, v59, v67
	v_add_u32_e32 v0, v80, v0
	v_cvt_pk_bf16_f32 v1, v1, s0
	ds_write_b16 v0, v1
	v_mul_f32_e32 v1, v43, v67
	v_cvt_pk_bf16_f32 v1, v1, s0
	v_rcp_f32_e32 v68, v68
	ds_write_b16 v0, v1 offset:64
	v_mul_f32_e32 v1, v27, v67
	v_cvt_pk_bf16_f32 v1, v1, s0
	ds_write_b16 v0, v1 offset:128
	v_mul_f32_e32 v1, v11, v67
	v_cvt_pk_bf16_f32 v1, v1, s0
	ds_write_b16 v0, v1 offset:192
	v_or_b32_e32 v0, 0x1800, v81
	v_mul_f32_e32 v1, v60, v68
	v_add_u32_e32 v0, v80, v0
	v_cvt_pk_bf16_f32 v1, v1, s0
	ds_write_b16 v0, v1
	v_mul_f32_e32 v1, v44, v68
	v_cvt_pk_bf16_f32 v1, v1, s0
	v_rcp_f32_e32 v69, v69
	ds_write_b16 v0, v1 offset:64
	v_mul_f32_e32 v1, v28, v68
	v_cvt_pk_bf16_f32 v1, v1, s0
	ds_write_b16 v0, v1 offset:128
	v_mul_f32_e32 v1, v12, v68
	v_cvt_pk_bf16_f32 v1, v1, s0
	ds_write_b16 v0, v1 offset:192
	v_or_b32_e32 v0, 0x1900, v81
	v_mul_f32_e32 v1, v61, v69
	v_add_u32_e32 v0, v80, v0
	v_cvt_pk_bf16_f32 v1, v1, s0
	ds_write_b16 v0, v1
	v_mul_f32_e32 v1, v45, v69
	v_cvt_pk_bf16_f32 v1, v1, s0
	v_rcp_f32_e32 v70, v70
	ds_write_b16 v0, v1 offset:64
	v_mul_f32_e32 v1, v29, v69
	v_cvt_pk_bf16_f32 v1, v1, s0
	ds_write_b16 v0, v1 offset:128
	v_mul_f32_e32 v1, v13, v69
	v_cvt_pk_bf16_f32 v1, v1, s0
	ds_write_b16 v0, v1 offset:192
	v_or_b32_e32 v0, 0x1a00, v81
	v_mul_f32_e32 v1, v62, v70
	v_add_u32_e32 v0, v80, v0
	v_cvt_pk_bf16_f32 v1, v1, s0
	ds_write_b16 v0, v1
	v_mul_f32_e32 v1, v46, v70
	v_cvt_pk_bf16_f32 v1, v1, s0
	v_rcp_f32_e32 v71, v71
	ds_write_b16 v0, v1 offset:64
	v_mul_f32_e32 v1, v30, v70
	v_cvt_pk_bf16_f32 v1, v1, s0
	ds_write_b16 v0, v1 offset:128
	v_mul_f32_e32 v1, v14, v70
	v_cvt_pk_bf16_f32 v1, v1, s0
	ds_write_b16 v0, v1 offset:192
	v_or_b32_e32 v0, 0x1b00, v81
	v_mul_f32_e32 v1, v63, v71
	v_add_u32_e32 v0, v80, v0
	v_cvt_pk_bf16_f32 v1, v1, s0
	ds_write_b16 v0, v1
	v_mul_f32_e32 v1, v47, v71
	v_cvt_pk_bf16_f32 v1, v1, s0
	ds_write_b16 v0, v1 offset:64
	v_mul_f32_e32 v1, v31, v71
	v_cvt_pk_bf16_f32 v1, v1, s0
	ds_write_b16 v0, v1 offset:128
	v_mul_f32_e32 v1, v15, v71
	v_cvt_pk_bf16_f32 v1, v1, s0
	ds_write_b16 v0, v1 offset:192
	v_mov_b32_e32 v241, v226
	s_waitcnt lgkmcnt(0)
	s_barrier
	s_nop 0
	v_readfirstlane_b32 s5, v241
	s_ashr_i32 s48, s5, 6
	s_lshl_b32 s38, s48, 5
	s_ashr_i32 s4, s38, 31
	s_add_u32 s8, s38, s71
	s_addc_u32 s9, s4, 0
	s_lshl_b64 s[10:11], s[8:9], 11
	v_and_b32_e32 v231, 63, v241
	s_add_u32 s10, s80, s10
	s_addc_u32 s11, s81, s11
	v_lshlrev_b32_e32 v212, 11, v231
	s_lshl_b32 s36, s48, 3
	v_lshl_add_u64 v[0:1], s[28:29], 0, v[212:213]
	s_ashr_i32 s37, s36, 31
	v_lshl_add_u64 v[32:33], s[36:37], 1, v[0:1]
	s_lshl_b32 s4, s48, 4
	v_bfe_u32 v0, v241, 2, 4
	v_and_or_b32 v0, s4, 48, v0
	s_ashr_i32 s4, s5, 3
	s_and_b32 s36, s4, 0xffffffe0
	v_lshlrev_b32_e32 v212, 11, v0
	s_ashr_i32 s37, s36, 31
	s_lshl_b32 s4, s48, 10
	v_lshl_add_u64 v[0:1], s[30:31], 0, v[212:213]
	v_lshlrev_b32_e32 v2, 3, v241
	s_cmp_lg_u32 0, -1
	v_lshl_add_u64 v[0:1], s[36:37], 1, v[0:1]
	v_and_b32_e32 v232, 24, v2
	s_cselect_b32 s36, 0, 0
	v_lshl_add_u64 v[214:215], v[32:33], 0, s[12:13]
	v_lshlrev_b32_e32 v212, 1, v232
	s_add_i32 s71, s4, s36
	s_mov_b32 m0, s71
	s_nop 0
	global_load_lds_dwordx4 v[214:215], off
	v_lshl_add_u64 v[216:217], v[0:1], 0, v[212:213]
	s_add_i32 s74, s71, 0x6000
	s_mov_b32 m0, s74
	s_nop 0
	global_load_lds_dwordx4 v[216:217], off
	v_and_b32_e32 v230, 31, v241
	v_lshl_add_u64 v[218:219], v[216:217], 0, s[12:13]
	s_add_i32 s36, s71, 0x8000
	s_mov_b32 m0, s36
	s_nop 0
	global_load_lds_dwordx4 v[218:219], off
	v_lshl_add_u64 v[0:1], v[32:33], 0, s[20:21]
	v_bfe_u32 v244, v241, 5, 1
	s_add_i32 s36, s71, 0x2000
	s_mov_b32 m0, s36
	s_nop 0
	global_load_lds_dwordx4 v[0:1], off
	v_lshlrev_b32_e32 v0, 11, v230
	v_lshl_or_b32 v212, v244, 4, v0
	v_lshl_add_u64 v[0:1], s[10:11], 0, v[212:213]
	v_lshl_add_u64 v[0:1], v[0:1], 0, s[0:1]
	global_load_dwordx4 v[172:175], v[0:1], off
	global_load_dwordx4 v[168:171], v[0:1], off offset:32
	global_load_dwordx4 v[164:167], v[0:1], off offset:64
	global_load_dwordx4 v[152:155], v[0:1], off offset:96
	v_lshlrev_b32_e32 v16, 10, v244
	v_lshlrev_b32_e32 v17, 4, v230
	v_mov_b32 v0, 0
	v_add3_u32 v239, 0, v16, v17
	v_mov_b32_e32 v14, v0
	v_mov_b32_e32 v15, v0
	v_mov_b32_e32 v1, v0
	v_mov_b32_e32 v2, v0
	v_mov_b32_e32 v3, v0
	v_mov_b32_e32 v4, v0
	v_mov_b32_e32 v5, v0
	v_mov_b32_e32 v6, v0
	v_mov_b32_e32 v7, v0
	v_mov_b32_e32 v8, v0
	v_mov_b32_e32 v9, v0
	v_mov_b32_e32 v10, v0
	v_mov_b32_e32 v11, v0
	v_mov_b32_e32 v12, v0
	v_mov_b32_e32 v13, v0
	v_mov_b64_e32 v[30:31], v[14:15]
	v_mov_b64_e32 v[28:29], v[12:13]
	v_mov_b64_e32 v[26:27], v[10:11]
	v_mov_b64_e32 v[24:25], v[8:9]
	v_mov_b64_e32 v[22:23], v[6:7]
	v_mov_b64_e32 v[20:21], v[4:5]
	v_mov_b64_e32 v[18:19], v[2:3]
	v_mov_b64_e32 v[16:17], v[0:1]
	s_mov_b64 s[10:11], 0x40080
	v_lshl_add_u64 v[32:33], v[32:33], 0, s[10:11]
	s_add_i32 s10, s71, 0x4000
	s_mov_b32 m0, s10
	s_nop 0
	global_load_lds_dwordx4 v[32:33], off
	s_waitcnt vmcnt(3) lgkmcnt(0)
	s_barrier
	ds_read_b128 v[48:51], v239
	ds_read_b128 v[52:55], v239 offset:512
	s_waitcnt vmcnt(3) lgkmcnt(1)
	v_mfma_f32_32x32x16_bf16 v[32:47], v[48:51], v[172:175], v[16:31]
	v_or_b32_e32 v237, s38, v230
	s_andn2_b64 vcc, exec, s[34:35]
	v_lshlrev_b32_e32 v212, 2, v244
	s_waitcnt lgkmcnt(0)
	v_mfma_f32_32x32x16_bf16 v[16:31], v[52:55], v[172:175], v[16:31]
	ds_read_b128 v[48:51], v239 offset:2048
	ds_read_b128 v[52:55], v239 offset:2560
	s_waitcnt vmcnt(2) lgkmcnt(1)
	v_mfma_f32_32x32x16_bf16 v[32:47], v[48:51], v[168:171], v[32:47]
	s_waitcnt lgkmcnt(0)
	v_mfma_f32_32x32x16_bf16 v[16:31], v[52:55], v[168:171], v[16:31]
	ds_read_b128 v[48:51], v239 offset:4096
	ds_read_b128 v[52:55], v239 offset:4608
	s_waitcnt vmcnt(1) lgkmcnt(1)
	v_mfma_f32_32x32x16_bf16 v[32:47], v[48:51], v[164:167], v[32:47]
	s_waitcnt lgkmcnt(0)
	v_mfma_f32_32x32x16_bf16 v[16:31], v[52:55], v[164:167], v[16:31]
	ds_read_b128 v[48:51], v239 offset:6144
	ds_read_b128 v[52:55], v239 offset:6656
	s_waitcnt vmcnt(0) lgkmcnt(1)
	v_mfma_f32_32x32x16_bf16 v[32:47], v[48:51], v[152:155], v[32:47]
	s_waitcnt lgkmcnt(0)
	v_mfma_f32_32x32x16_bf16 v[16:31], v[52:55], v[152:155], v[16:31]
	s_nop 15
	s_nop 7
	s_cbranch_vccnz .LBB0_1357
	v_lshlrev_b32_e32 v48, 2, v244
	v_or_b32_e32 v49, 32, v48
	v_cmp_le_i32_e32 vcc, v49, v237
	v_or_b32_e32 v49, 33, v48
	s_nop 6
	v_cndmask_b32_e32 v16, v228, v16, vcc
	v_cmp_lt_i32_e32 vcc, v48, v237
	s_nop 1
	v_cndmask_b32_e32 v33, v228, v33, vcc
	v_cmp_le_i32_e32 vcc, v48, v237
	s_nop 1
	v_cndmask_b32_e32 v32, v228, v32, vcc
	v_cmp_le_i32_e32 vcc, v49, v237
	v_or_b32_e32 v49, 2, v48
	s_nop 0
	v_cndmask_b32_e32 v17, v228, v17, vcc
	v_cmp_le_i32_e32 vcc, v49, v237
	v_or_b32_e32 v49, 34, v48
	s_nop 0
	v_cndmask_b32_e32 v34, v228, v34, vcc
	v_cmp_le_i32_e32 vcc, v49, v237
	v_or_b32_e32 v49, 3, v48
	s_nop 0
	v_cndmask_b32_e32 v18, v228, v18, vcc
	v_cmp_le_i32_e32 vcc, v49, v237
	v_or_b32_e32 v49, 35, v48
	s_nop 0
	v_cndmask_b32_e32 v35, v228, v35, vcc
	v_cmp_le_i32_e32 vcc, v49, v237
	v_or_b32_e32 v49, 8, v48
	s_nop 0
	v_cndmask_b32_e32 v19, v228, v19, vcc
	v_cmp_le_i32_e32 vcc, v49, v237
	v_or_b32_e32 v49, 40, v48
	s_nop 0
	v_cndmask_b32_e32 v36, v228, v36, vcc
	v_cmp_le_i32_e32 vcc, v49, v237
	v_or_b32_e32 v49, 9, v48
	s_nop 0
	v_cndmask_b32_e32 v20, v228, v20, vcc
	v_cmp_le_i32_e32 vcc, v49, v237
	v_or_b32_e32 v49, 41, v48
	s_nop 0
	v_cndmask_b32_e32 v37, v228, v37, vcc
	v_cmp_le_i32_e32 vcc, v49, v237
	v_or_b32_e32 v49, 10, v48
	s_nop 0
	v_cndmask_b32_e32 v21, v228, v21, vcc
	v_cmp_le_i32_e32 vcc, v49, v237
	v_or_b32_e32 v49, 42, v48
	s_nop 0
	v_cndmask_b32_e32 v38, v228, v38, vcc
	v_cmp_le_i32_e32 vcc, v49, v237
	v_or_b32_e32 v49, 11, v48
	s_nop 0
	v_cndmask_b32_e32 v22, v228, v22, vcc
	v_cmp_le_i32_e32 vcc, v49, v237
	v_or_b32_e32 v49, 43, v48
	s_nop 0
	v_cndmask_b32_e32 v39, v228, v39, vcc
	v_cmp_le_i32_e32 vcc, v49, v237
	v_or_b32_e32 v49, 16, v48
	s_nop 0
	v_cndmask_b32_e32 v23, v228, v23, vcc
	v_cmp_le_i32_e32 vcc, v49, v237
	v_or_b32_e32 v49, 48, v48
	s_nop 0
	v_cndmask_b32_e32 v40, v228, v40, vcc
	v_cmp_le_i32_e32 vcc, v49, v237
	v_or_b32_e32 v49, 17, v48
	s_nop 0
	v_cndmask_b32_e32 v24, v228, v24, vcc
	v_cmp_le_i32_e32 vcc, v49, v237
	v_or_b32_e32 v49, 49, v48
	s_nop 0
	v_cndmask_b32_e32 v41, v228, v41, vcc
	v_cmp_le_i32_e32 vcc, v49, v237
	v_or_b32_e32 v49, 18, v48
	s_nop 0
	v_cndmask_b32_e32 v25, v228, v25, vcc
	v_cmp_le_i32_e32 vcc, v49, v237
	v_or_b32_e32 v49, 50, v48
	s_nop 0
	v_cndmask_b32_e32 v42, v228, v42, vcc
	v_cmp_le_i32_e32 vcc, v49, v237
	v_or_b32_e32 v49, 19, v48
	s_nop 0
	v_cndmask_b32_e32 v26, v228, v26, vcc
	v_cmp_le_i32_e32 vcc, v49, v237
	v_or_b32_e32 v49, 51, v48
	s_nop 0
	v_cndmask_b32_e32 v43, v228, v43, vcc
	v_cmp_le_i32_e32 vcc, v49, v237
	v_or_b32_e32 v49, 24, v48
	s_nop 0
	v_cndmask_b32_e32 v27, v228, v27, vcc
	v_cmp_le_i32_e32 vcc, v49, v237
	v_or_b32_e32 v49, 56, v48
	s_nop 0
	v_cndmask_b32_e32 v44, v228, v44, vcc
	v_cmp_le_i32_e32 vcc, v49, v237
	v_or_b32_e32 v49, 25, v48
	s_nop 0
	v_cndmask_b32_e32 v28, v228, v28, vcc
	v_cmp_le_i32_e32 vcc, v49, v237
	v_or_b32_e32 v49, 57, v48
	s_nop 0
	v_cndmask_b32_e32 v45, v228, v45, vcc
	v_cmp_le_i32_e32 vcc, v49, v237
	v_or_b32_e32 v49, 26, v48
	s_nop 0
	v_cndmask_b32_e32 v29, v228, v29, vcc
	v_cmp_le_i32_e32 vcc, v49, v237
	v_or_b32_e32 v49, 58, v48
	s_nop 0
	v_cndmask_b32_e32 v46, v228, v46, vcc
	v_cmp_le_i32_e32 vcc, v49, v237
	v_or_b32_e32 v49, 27, v48
	v_or_b32_e32 v48, 59, v48
	v_cndmask_b32_e32 v30, v228, v30, vcc
	v_cmp_le_i32_e32 vcc, v49, v237
	s_nop 1
	v_cndmask_b32_e32 v47, v228, v47, vcc
	v_cmp_le_i32_e32 vcc, v48, v237
	s_nop 1
	v_cndmask_b32_e32 v31, v228, v31, vcc
.LBB0_1357:
	v_lshlrev_b32_e32 v48, 1, v231
	v_and_b32_e32 v234, 32, v48
	v_lshlrev_b32_e32 v48, 4, v241
	v_and_b32_e32 v48, 0xc0, v48
	v_add_u32_e32 v49, 0, v234
	v_lshl_or_b32 v235, v244, 8, v48
	v_max3_f32 v48, v32, v33, v16
	v_add3_u32 v240, v49, v232, v235
	v_max3_f32 v49, v34, v35, v17
	v_max3_f32 v48, v48, v18, v19
	s_and_b32 s5, s5, 0x3fffffc0
	v_max3_f32 v48, v48, v36, v37
	v_max3_f32 v49, v49, v38, v39
	s_lshl_b32 s5, s5, 2
	v_max3_f32 v48, v48, v20, v21
	v_max3_f32 v49, v49, v22, v23
	s_add_i32 s49, s5, 0
	v_max3_f32 v48, v48, v40, v41
	v_max3_f32 v49, v49, v42, v43
	s_add_i32 s49, s49, 0x12000
	v_max3_f32 v48, v48, v24, v25
	v_max3_f32 v49, v49, v26, v27
	s_cmp_lg_u32 0, -1
	v_max3_f32 v48, v48, v44, v45
	v_max3_f32 v49, v49, v46, v47
	s_mov_b32 s34, 1
	v_max3_f32 v48, v48, v28, v29
	v_max3_f32 v49, v49, v30, v31
	s_mov_b32 s36, 0
	v_max_f32_e32 v48, v48, v49
	v_lshlrev_b32_e32 v242, 4, v244
	v_mov_b32_e32 v49, v48
	s_nop 1
	v_permlane32_swap_b32_e32 v48, v49
	v_max_f32_e32 v48, v48, v49
	v_lshl_add_u32 v236, v230, 2, s49
	v_add_f32_e32 v238, v213, v48
	v_sub_f32_e32 v16, v16, v48
	v_sub_f32_e32 v17, v17, v48
	v_sub_f32_e32 v32, v32, v48
	v_sub_f32_e32 v33, v33, v48
	v_sub_f32_e32 v34, v34, v48
	s_nop 0
	v_xor_b32_e32 v64, 0x80000000, v238
	v_mov_b32_e32 v65, v64
	v_mov_b32_e32 v66, v64
	v_mov_b32_e32 v67, v64
	v_mov_b32_e32 v68, v64
	v_mov_b32_e32 v69, v64
	v_mov_b32_e32 v70, v64
	v_mov_b32_e32 v71, v64
	v_mov_b32_e32 v72, v64
	v_mov_b32_e32 v73, v64
	v_mov_b32_e32 v74, v64
	v_mov_b32_e32 v75, v64
	v_mov_b32_e32 v76, v64
	v_mov_b32_e32 v77, v64
	v_mov_b32_e32 v78, v64
	v_mov_b32_e32 v79, v64
	s_waitcnt vmcnt(0) lgkmcnt(0)
	s_barrier
	v_exp_f32_e32 v80, v16
	v_exp_f32_e32 v81, v17
	v_lshl_add_u64 v[16:17], v[214:215], 0, s[18:19]
	s_mov_b32 m0, s71
	s_nop 0
	global_load_lds_dwordx4 v[16:17], off
	s_cselect_b32 s5, 0, 0
	s_add_i32 s4, s5, s4
	v_lshl_add_u64 v[16:17], v[216:217], 0, s[14:15]
	s_add_i32 s5, s4, 0xa000
	s_mov_b32 m0, s5
	s_nop 0
	global_load_lds_dwordx4 v[16:17], off
	v_lshl_add_u64 v[16:17], v[216:217], 0, s[20:21]
	s_add_i32 s4, s4, 0xc000
	s_mov_b32 m0, s4
	s_nop 0
	global_load_lds_dwordx4 v[16:17], off
	ds_read_b128 v[204:207], v239 offset:8192
	ds_read_b128 v[200:203], v239 offset:8704
	ds_read_b128 v[196:199], v239 offset:10240
	ds_read_b128 v[192:195], v239 offset:10752
	ds_read_b128 v[188:191], v239 offset:12288
	ds_read_b128 v[184:187], v239 offset:12800
	ds_read_b128 v[180:183], v239 offset:14336
	ds_read_b128 v[176:179], v239 offset:14848
	v_sub_f32_e32 v18, v18, v48
	v_sub_f32_e32 v35, v35, v48
	v_sub_f32_e32 v19, v19, v48
	v_sub_f32_e32 v36, v36, v48
	v_sub_f32_e32 v20, v20, v48
	v_sub_f32_e32 v37, v37, v48
	v_sub_f32_e32 v21, v21, v48
	v_sub_f32_e32 v38, v38, v48
	v_sub_f32_e32 v22, v22, v48
	v_sub_f32_e32 v39, v39, v48
	v_sub_f32_e32 v23, v23, v48
	v_sub_f32_e32 v40, v40, v48
	v_sub_f32_e32 v24, v24, v48
	v_sub_f32_e32 v41, v41, v48
	v_sub_f32_e32 v25, v25, v48
	v_sub_f32_e32 v42, v42, v48
	v_sub_f32_e32 v26, v26, v48
	v_sub_f32_e32 v43, v43, v48
	v_sub_f32_e32 v27, v27, v48
	v_sub_f32_e32 v44, v44, v48
	v_sub_f32_e32 v28, v28, v48
	v_sub_f32_e32 v45, v45, v48
	v_sub_f32_e32 v29, v29, v48
	v_sub_f32_e32 v46, v46, v48
	v_sub_f32_e32 v30, v30, v48
	v_sub_f32_e32 v47, v47, v48
	v_sub_f32_e32 v31, v31, v48
	v_exp_f32_e32 v96, v32
	v_exp_f32_e32 v97, v33
	v_exp_f32_e32 v98, v34
	v_exp_f32_e32 v99, v35
	v_exp_f32_e32 v100, v36
	v_exp_f32_e32 v101, v37
	v_exp_f32_e32 v102, v38
	v_exp_f32_e32 v103, v39
	v_exp_f32_e32 v104, v40
	v_exp_f32_e32 v105, v41
	v_exp_f32_e32 v106, v42
	v_exp_f32_e32 v107, v43
	v_exp_f32_e32 v108, v44
	v_exp_f32_e32 v109, v45
	v_exp_f32_e32 v110, v46
	v_exp_f32_e32 v111, v47
	v_exp_f32_e32 v82, v18
	v_exp_f32_e32 v83, v19
	v_exp_f32_e32 v84, v20
	v_exp_f32_e32 v85, v21
	v_exp_f32_e32 v86, v22
	v_exp_f32_e32 v87, v23
	v_exp_f32_e32 v88, v24
	v_exp_f32_e32 v89, v25
	v_exp_f32_e32 v90, v26
	v_exp_f32_e32 v91, v27
	v_exp_f32_e32 v92, v28
	v_exp_f32_e32 v93, v29
	v_exp_f32_e32 v94, v30
	v_exp_f32_e32 v95, v31
	s_waitcnt vmcnt(3) lgkmcnt(0)
	s_barrier
	s_and_b64 vcc, exec, s[6:7]
	v_cmp_gt_u32_e64 s[6:7], 32, v231
	s_cbranch_vccnz .LBB0_1423
	v_mov_b64_e32 v[62:63], v[14:15]
	v_mov_b64_e32 v[46:47], v[14:15]
	v_mov_b64_e32 v[30:31], v[14:15]
	v_lshl_add_u64 v[220:221], v[218:219], 0, s[18:19]
	v_lshl_add_u64 v[222:223], v[216:217], 0, s[18:19]
	v_lshl_add_u64 v[224:225], v[214:215], 0, s[22:23]
	s_movk_i32 s36, 0x4000
	s_movk_i32 s35, 0x2000
	s_mov_b32 s4, 0
	v_mov_b32_e32 v243, 0
	v_mov_b64_e32 v[60:61], v[12:13]
	v_mov_b64_e32 v[58:59], v[10:11]
	v_mov_b64_e32 v[56:57], v[8:9]
	v_mov_b64_e32 v[54:55], v[6:7]
	v_mov_b64_e32 v[52:53], v[4:5]
	v_mov_b64_e32 v[50:51], v[2:3]
	v_mov_b64_e32 v[48:49], v[0:1]
	v_mov_b64_e32 v[44:45], v[12:13]
	v_mov_b64_e32 v[42:43], v[10:11]
	v_mov_b64_e32 v[40:41], v[8:9]
	v_mov_b64_e32 v[38:39], v[6:7]
	v_mov_b64_e32 v[36:37], v[4:5]
	v_mov_b64_e32 v[34:35], v[2:3]
	v_mov_b64_e32 v[32:33], v[0:1]
	v_mov_b64_e32 v[28:29], v[12:13]
	v_mov_b64_e32 v[26:27], v[10:11]
	v_mov_b64_e32 v[24:25], v[8:9]
	v_mov_b64_e32 v[22:23], v[6:7]
	v_mov_b64_e32 v[20:21], v[4:5]
	v_mov_b64_e32 v[18:19], v[2:3]
	v_mov_b64_e32 v[16:17], v[0:1]
.LBB0_1359:
	s_lshl_b32 s4, s4, 1
	v_add_u32_e32 v245, s4, v240
	ds_read_b64_tr_b16 v[208:209], v245 offset:24576
	ds_read_b64_tr_b16 v[210:211], v245 offset:25088
	s_waitcnt lgkmcnt(9)
	v_mfma_f32_32x32x16_bf16 v[128:143], v[204:207], v[172:175], v[64:79]
	v_add_f32_e32 v112, v96, v97
	v_add_f32_e32 v112, v98, v112
	v_add_f32_e32 v112, v99, v112
	v_add_f32_e32 v112, v100, v112
	v_add_f32_e32 v112, v101, v112
	v_cvt_pk_bf16_f32 v160, v96, v97
	v_cvt_pk_bf16_f32 v161, v98, v99
	ds_read_b64_tr_b16 v[96:97], v245 offset:28672
	ds_read_b64_tr_b16 v[98:99], v245 offset:29184
	v_add_f32_e32 v112, v102, v112
	v_add_f32_e32 v112, v103, v112
	v_add_f32_e32 v112, v104, v112
	v_add_f32_e32 v144, v105, v112
	s_waitcnt lgkmcnt(10)
	v_mfma_f32_32x32x16_bf16 v[112:127], v[200:203], v[172:175], v[64:79]
	v_cvt_pk_bf16_f32 v162, v100, v101
	v_cvt_pk_bf16_f32 v163, v102, v103
	ds_read_b64_tr_b16 v[100:101], v245 offset:25600
	ds_read_b64_tr_b16 v[102:103], v245 offset:26112
	s_waitcnt lgkmcnt(11)
	v_mfma_f32_32x32x16_bf16 v[128:143], v[196:199], v[168:171], v[128:143]
	v_add_f32_e32 v144, v106, v144
	v_add_f32_e32 v144, v107, v144
	v_add_f32_e32 v144, v108, v144
	v_add_f32_e32 v144, v109, v144
	v_cvt_pk_bf16_f32 v156, v104, v105
	v_cvt_pk_bf16_f32 v157, v106, v107
	ds_read_b64_tr_b16 v[104:105], v245 offset:29696
	ds_read_b64_tr_b16 v[106:107], v245 offset:30208
	s_waitcnt lgkmcnt(12)
	v_mfma_f32_32x32x16_bf16 v[112:127], v[192:195], v[168:171], v[112:127]
	v_add_f32_e32 v144, v110, v144
	v_add_f32_e32 v144, v111, v144
	v_add_f32_e32 v144, v80, v144
	v_add_f32_e32 v144, v81, v144
	v_cvt_pk_bf16_f32 v158, v108, v109
	v_cvt_pk_bf16_f32 v159, v110, v111
	ds_read_b64_tr_b16 v[108:109], v245 offset:26624
	ds_read_b64_tr_b16 v[110:111], v245 offset:27136
	s_waitcnt lgkmcnt(13)
	v_mfma_f32_32x32x16_bf16 v[128:143], v[188:191], v[164:167], v[128:143]
	v_add_f32_e32 v144, v82, v144
	v_add_f32_e32 v144, v83, v144
	v_add_f32_e32 v144, v84, v144
	v_add_f32_e32 v144, v85, v144
	v_cvt_pk_bf16_f32 v148, v80, v81
	v_cvt_pk_bf16_f32 v149, v82, v83
	ds_read_b64_tr_b16 v[80:81], v245 offset:30720
	ds_read_b64_tr_b16 v[82:83], v245 offset:31232
	s_waitcnt lgkmcnt(14)
	v_mfma_f32_32x32x16_bf16 v[112:127], v[184:187], v[164:167], v[112:127]
	v_add_f32_e32 v144, v86, v144
	v_add_f32_e32 v144, v87, v144
	v_add_f32_e32 v144, v88, v144
	v_add_f32_e32 v144, v89, v144
	v_cvt_pk_bf16_f32 v150, v84, v85
	v_cvt_pk_bf16_f32 v151, v86, v87
	ds_read_b64_tr_b16 v[84:85], v245 offset:27648
	ds_read_b64_tr_b16 v[86:87], v245 offset:28160
	s_waitcnt lgkmcnt(14)
	v_mfma_f32_32x32x16_bf16 v[128:143], v[180:183], v[152:155], v[128:143]
	v_add_f32_e32 v144, v90, v144
	v_add_f32_e32 v144, v91, v144
	v_add_f32_e32 v144, v92, v144
	v_add_f32_e32 v184, v93, v144
	v_cvt_pk_bf16_f32 v144, v88, v89
	v_cvt_pk_bf16_f32 v145, v90, v91
	ds_read_b64_tr_b16 v[88:89], v245 offset:31744
	ds_read_b64_tr_b16 v[90:91], v245 offset:32256
	v_mfma_f32_32x32x16_bf16 v[112:127], v[176:179], v[152:155], v[112:127]
	v_add_f32_e32 v146, v94, v184
	v_add_f32_e32 v146, v95, v146
	v_add_f32_e32 v180, 0, v146
	v_cvt_pk_bf16_f32 v146, v92, v93
	v_cvt_pk_bf16_f32 v147, v94, v95
	v_lshl_add_u64 v[92:93], v[224:225], 0, s[24:25]
	s_add_i32 s4, s35, s71
	s_mov_b32 m0, s4
	s_nop 0
	global_load_lds_dwordx4 v[92:93], off
	v_lshl_add_u64 v[92:93], v[222:223], 0, s[24:25]
	s_lshl_b32 s4, s36, 1
	s_add_i32 s4, s4, s74
	s_mov_b32 m0, s4
	s_nop 0
	global_load_lds_dwordx4 v[92:93], off
	v_lshl_add_u64 v[92:93], v[220:221], 0, s[24:25]
	s_addk_i32 s4, 0x2000
	s_mov_b32 m0, s4
	s_nop 0
	global_load_lds_dwordx4 v[92:93], off
	v_max_f32_e32 v92, v128, v129
	v_max3_f32 v93, v130, v131, v113
	v_max3_f32 v92, v92, v112, v114
	v_max3_f32 v92, v92, v115, v132
	v_max3_f32 v93, v93, v134, v135
	v_max3_f32 v92, v92, v133, v116
	v_max3_f32 v93, v93, v118, v119
	v_max3_f32 v92, v92, v117, v136
	v_max3_f32 v93, v93, v138, v139
	v_max3_f32 v92, v92, v137, v120
	v_max3_f32 v93, v93, v122, v123
	v_max3_f32 v92, v92, v121, v140
	v_max3_f32 v93, v93, v142, v143
	v_max3_f32 v92, v92, v141, v124
	v_max3_f32 v93, v93, v126, v127
	v_max3_f32 v92, v92, v125, v93
	v_mov_b32_e32 v93, v92
	s_nop 1
	v_permlane32_swap_b32_e32 v92, v93
	v_max_f32_e32 v92, v92, v93
	v_cmp_lt_f32_e32 vcc, s41, v92
	s_cmp_lg_u64 vcc, 0
	v_add_f32_e32 v233, v243, v180
	s_cselect_b64 s[10:11], -1, 0
	s_cbranch_vccnz .LBB0_1367

.LBB0_1362:
	s_add_i32 s4, s36, 0x2000
	s_cmpk_lg_i32 s36, 0x4000
	s_cselect_b32 s75, s4, 0
	s_lshl_b32 s4, s35, 1
	v_add_u32_e32 v209, s4, v240
	ds_read_b64_tr_b16 v[196:197], v209 offset:24576
	ds_read_b64_tr_b16 v[198:199], v209 offset:25088
	s_waitcnt lgkmcnt(9)
	v_mfma_f32_32x32x16_bf16 v[96:111], v[80:83], v[172:175], v[64:79]
	v_add_f32_e32 v84, v128, v129
	v_add_f32_e32 v84, v130, v84
	v_add_f32_e32 v84, v131, v84
	v_add_f32_e32 v84, v132, v84
	v_add_f32_e32 v84, v133, v84
	v_cvt_pk_bf16_f32 v160, v128, v129
	v_cvt_pk_bf16_f32 v161, v130, v131
	ds_read_b64_tr_b16 v[128:129], v209 offset:28672
	ds_read_b64_tr_b16 v[130:131], v209 offset:29184
	v_add_f32_e32 v80, v134, v84
	v_add_f32_e32 v80, v135, v80
	v_add_f32_e32 v80, v136, v80
	v_add_f32_e32 v144, v137, v80
	s_waitcnt lgkmcnt(10)
	v_mfma_f32_32x32x16_bf16 v[80:95], v[204:207], v[172:175], v[64:79]
	v_cvt_pk_bf16_f32 v162, v132, v133
	v_cvt_pk_bf16_f32 v163, v134, v135
	ds_read_b64_tr_b16 v[132:133], v209 offset:25600
	ds_read_b64_tr_b16 v[134:135], v209 offset:26112
	s_waitcnt lgkmcnt(11)
	v_mfma_f32_32x32x16_bf16 v[96:111], v[200:203], v[168:171], v[96:111]
	v_add_f32_e32 v144, v138, v144
	v_add_f32_e32 v144, v139, v144
	v_add_f32_e32 v144, v140, v144
	v_add_f32_e32 v144, v141, v144
	v_cvt_pk_bf16_f32 v156, v136, v137
	v_cvt_pk_bf16_f32 v157, v138, v139
	ds_read_b64_tr_b16 v[136:137], v209 offset:29696
	ds_read_b64_tr_b16 v[138:139], v209 offset:30208
	s_waitcnt lgkmcnt(12)
	v_mfma_f32_32x32x16_bf16 v[80:95], v[192:195], v[168:171], v[80:95]
	v_add_f32_e32 v144, v142, v144
	v_add_f32_e32 v144, v143, v144
	v_add_f32_e32 v144, v112, v144
	v_add_f32_e32 v144, v113, v144
	v_cvt_pk_bf16_f32 v158, v140, v141
	v_cvt_pk_bf16_f32 v159, v142, v143
	ds_read_b64_tr_b16 v[140:141], v209 offset:26624
	ds_read_b64_tr_b16 v[142:143], v209 offset:27136
	s_waitcnt lgkmcnt(13)
	v_mfma_f32_32x32x16_bf16 v[96:111], v[188:191], v[164:167], v[96:111]
	v_add_f32_e32 v144, v114, v144
	v_add_f32_e32 v144, v115, v144
	v_add_f32_e32 v144, v116, v144
	v_add_f32_e32 v144, v117, v144
	v_cvt_pk_bf16_f32 v148, v112, v113
	v_cvt_pk_bf16_f32 v149, v114, v115
	ds_read_b64_tr_b16 v[112:113], v209 offset:30720
	ds_read_b64_tr_b16 v[114:115], v209 offset:31232
	s_waitcnt lgkmcnt(14)
	v_mfma_f32_32x32x16_bf16 v[80:95], v[184:187], v[164:167], v[80:95]
	v_add_f32_e32 v144, v118, v144
	v_add_f32_e32 v144, v119, v144
	v_add_f32_e32 v144, v120, v144
	v_add_f32_e32 v144, v121, v144
	v_cvt_pk_bf16_f32 v150, v116, v117
	v_cvt_pk_bf16_f32 v151, v118, v119
	ds_read_b64_tr_b16 v[116:117], v209 offset:27648
	ds_read_b64_tr_b16 v[118:119], v209 offset:28160
	s_waitcnt lgkmcnt(14)
	v_mfma_f32_32x32x16_bf16 v[96:111], v[180:183], v[152:155], v[96:111]
	v_add_f32_e32 v144, v122, v144
	v_add_f32_e32 v144, v123, v144
	v_add_f32_e32 v144, v124, v144
	v_add_f32_e32 v184, v125, v144
	v_cvt_pk_bf16_f32 v144, v120, v121
	v_cvt_pk_bf16_f32 v145, v122, v123
	ds_read_b64_tr_b16 v[120:121], v209 offset:31744
	ds_read_b64_tr_b16 v[122:123], v209 offset:32256
	v_mfma_f32_32x32x16_bf16 v[80:95], v[176:179], v[152:155], v[80:95]
	v_add_f32_e32 v146, v126, v184
	v_add_f32_e32 v146, v127, v146
	v_add_f32_e32 v180, 0, v146
	v_cvt_pk_bf16_f32 v146, v124, v125
	v_cvt_pk_bf16_f32 v147, v126, v127
	v_max_f32_e32 v124, v96, v97
	s_nop 3
	s_nop 1
	v_max3_f32 v125, v98, v99, v81
	v_max3_f32 v124, v124, v80, v82
	v_max3_f32 v124, v124, v83, v100
	v_max3_f32 v125, v125, v102, v103
	v_max3_f32 v124, v124, v101, v84
	v_max3_f32 v125, v125, v86, v87
	v_max3_f32 v124, v124, v85, v104
	v_max3_f32 v125, v125, v106, v107
	v_max3_f32 v124, v124, v105, v88
	v_max3_f32 v125, v125, v90, v91
	v_max3_f32 v124, v124, v89, v108
	v_max3_f32 v125, v125, v110, v111
	v_max3_f32 v124, v124, v109, v92
	v_max3_f32 v125, v125, v94, v95
	v_max3_f32 v124, v124, v93, v125
	v_mov_b32_e32 v125, v124
	s_add_i32 s4, s36, s71
	s_nop 0
	v_permlane32_swap_b32_e32 v124, v125
	s_mov_b32 m0, s4
	s_nop 0
	global_load_lds_dwordx4 v[224:225], off
	s_lshl_b32 s4, s75, 1
	s_add_i32 s4, s4, s74
	s_mov_b32 m0, s4
	s_nop 0
	global_load_lds_dwordx4 v[222:223], off
	v_max_f32_e32 v124, v124, v125
	s_addk_i32 s4, 0x2000
	s_mov_b32 m0, s4
	s_nop 0
	global_load_lds_dwordx4 v[220:221], off
	v_cmp_lt_f32_e32 vcc, s41, v124
	s_cmp_lg_u64 vcc, 0
	v_add_f32_e32 v243, v233, v180
	s_cselect_b64 s[10:11], -1, 0
	s_cbranch_vccnz .LBB0_1370

.LBB0_1367:
	v_max_f32_e32 v92, 0, v92
	v_exp_f32_e64 v93, -v92
	v_add_f32_e32 v238, v238, v92
	v_xor_b32_e32 v64, 0x80000000, v238
	v_mov_b32_e32 v65, v64
	v_mov_b32_e32 v66, v64
	v_mov_b32_e32 v67, v64
	v_mov_b32_e32 v68, v64
	v_mov_b32_e32 v69, v64
	v_mov_b32_e32 v70, v64
	v_mov_b32_e32 v71, v64
	v_mov_b32_e32 v72, v64
	v_mov_b32_e32 v73, v64
	v_mov_b32_e32 v74, v64
	v_mov_b32_e32 v75, v64
	v_mov_b32_e32 v76, v64
	v_mov_b32_e32 v77, v64
	v_mov_b32_e32 v78, v64
	v_mov_b32_e32 v79, v64
	s_and_saveexec_b64 s[4:5], s[6:7]
	ds_write_b32 v236, v93
	s_or_b64 exec, exec, s[4:5]
	v_sub_f32_e32 v143, v143, v92
	v_sub_f32_e32 v142, v142, v92
	v_sub_f32_e32 v141, v141, v92
	v_sub_f32_e32 v140, v140, v92
	v_sub_f32_e32 v139, v139, v92
	v_sub_f32_e32 v138, v138, v92
	v_sub_f32_e32 v137, v137, v92
	v_sub_f32_e32 v136, v136, v92
	v_sub_f32_e32 v135, v135, v92
	v_sub_f32_e32 v134, v134, v92
	v_sub_f32_e32 v133, v133, v92
	v_sub_f32_e32 v132, v132, v92
	v_sub_f32_e32 v131, v131, v92
	v_sub_f32_e32 v130, v130, v92
	v_sub_f32_e32 v129, v129, v92
	v_sub_f32_e32 v128, v128, v92
	v_sub_f32_e32 v127, v127, v92
	v_sub_f32_e32 v126, v126, v92
	v_sub_f32_e32 v125, v125, v92
	v_sub_f32_e32 v124, v124, v92
	v_sub_f32_e32 v123, v123, v92
	v_sub_f32_e32 v122, v122, v92
	v_sub_f32_e32 v121, v121, v92
	v_sub_f32_e32 v120, v120, v92
	v_sub_f32_e32 v119, v119, v92
	v_sub_f32_e32 v118, v118, v92
	v_sub_f32_e32 v117, v117, v92
	v_sub_f32_e32 v116, v116, v92
	v_sub_f32_e32 v115, v115, v92
	v_sub_f32_e32 v114, v114, v92
	v_sub_f32_e32 v113, v113, v92
	v_sub_f32_e32 v112, v112, v92
	v_mul_f32_e32 v233, v233, v93
	s_branch .LBB0_1360
.LBB0_1370:
	v_max_f32_e32 v124, 0, v124
	v_exp_f32_e64 v125, -v124
	v_add_f32_e32 v238, v238, v124
	v_xor_b32_e32 v64, 0x80000000, v238
	v_mov_b32_e32 v65, v64
	v_mov_b32_e32 v66, v64
	v_mov_b32_e32 v67, v64
	v_mov_b32_e32 v68, v64
	v_mov_b32_e32 v69, v64
	v_mov_b32_e32 v70, v64
	v_mov_b32_e32 v71, v64
	v_mov_b32_e32 v72, v64
	v_mov_b32_e32 v73, v64
	v_mov_b32_e32 v74, v64
	v_mov_b32_e32 v75, v64
	v_mov_b32_e32 v76, v64
	v_mov_b32_e32 v77, v64
	v_mov_b32_e32 v78, v64
	v_mov_b32_e32 v79, v64
	s_and_saveexec_b64 s[4:5], s[6:7]
	ds_write_b32 v236, v125
	s_or_b64 exec, exec, s[4:5]
	v_sub_f32_e32 v111, v111, v124
	v_sub_f32_e32 v110, v110, v124
	v_sub_f32_e32 v109, v109, v124
	v_sub_f32_e32 v108, v108, v124
	v_sub_f32_e32 v107, v107, v124
	v_sub_f32_e32 v106, v106, v124
	v_sub_f32_e32 v105, v105, v124
	v_sub_f32_e32 v104, v104, v124
	v_sub_f32_e32 v103, v103, v124
	v_sub_f32_e32 v102, v102, v124
	v_sub_f32_e32 v101, v101, v124
	v_sub_f32_e32 v100, v100, v124
	v_sub_f32_e32 v99, v99, v124
	v_sub_f32_e32 v98, v98, v124
	v_sub_f32_e32 v97, v97, v124
	v_sub_f32_e32 v96, v96, v124
	v_sub_f32_e32 v95, v95, v124
	v_sub_f32_e32 v94, v94, v124
	v_sub_f32_e32 v93, v93, v124
	v_sub_f32_e32 v92, v92, v124
	v_sub_f32_e32 v91, v91, v124
	v_sub_f32_e32 v90, v90, v124
	v_sub_f32_e32 v89, v89, v124
	v_sub_f32_e32 v88, v88, v124
	v_sub_f32_e32 v87, v87, v124
	v_sub_f32_e32 v86, v86, v124
	v_sub_f32_e32 v85, v85, v124
	v_sub_f32_e32 v84, v84, v124
	v_sub_f32_e32 v83, v83, v124
	v_sub_f32_e32 v82, v82, v124
	v_sub_f32_e32 v81, v81, v124
	v_sub_f32_e32 v80, v80, v124
	v_mul_f32_e32 v243, v243, v125
	s_branch .LBB0_1363

.LBB0_1375:
	s_lshl_b32 s4, s38, 1
	v_add_u32_e32 v243, s4, v239
	ds_read_b64_tr_b16 v[208:209], v243 offset:24576
	ds_read_b64_tr_b16 v[210:211], v243 offset:25088
	s_waitcnt lgkmcnt(9)
	v_mfma_f32_32x32x16_bf16 v[128:143], v[204:207], v[172:175], v[64:79]
	v_add_f32_e32 v112, v96, v97
	v_add_f32_e32 v112, v98, v112
	v_add_f32_e32 v112, v99, v112
	v_add_f32_e32 v112, v100, v112
	v_add_f32_e32 v112, v101, v112
	v_cvt_pk_bf16_f32 v164, v96, v97
	v_cvt_pk_bf16_f32 v165, v98, v99
	ds_read_b64_tr_b16 v[96:97], v243 offset:28672
	ds_read_b64_tr_b16 v[98:99], v243 offset:29184
	v_add_f32_e32 v112, v102, v112
	v_add_f32_e32 v112, v103, v112
	v_add_f32_e32 v112, v104, v112
	v_add_f32_e32 v144, v105, v112
	s_waitcnt lgkmcnt(10)
	v_mfma_f32_32x32x16_bf16 v[112:127], v[200:203], v[172:175], v[64:79]
	v_cvt_pk_bf16_f32 v166, v100, v101
	v_cvt_pk_bf16_f32 v167, v102, v103
	ds_read_b64_tr_b16 v[100:101], v243 offset:25600
	ds_read_b64_tr_b16 v[102:103], v243 offset:26112
	s_waitcnt lgkmcnt(11)
	v_mfma_f32_32x32x16_bf16 v[128:143], v[196:199], v[168:171], v[128:143]
	v_add_f32_e32 v144, v106, v144
	v_add_f32_e32 v144, v107, v144
	v_add_f32_e32 v144, v108, v144
	v_add_f32_e32 v144, v109, v144
	v_cvt_pk_bf16_f32 v156, v104, v105
	v_cvt_pk_bf16_f32 v157, v106, v107
	ds_read_b64_tr_b16 v[104:105], v243 offset:29696
	ds_read_b64_tr_b16 v[106:107], v243 offset:30208
	s_waitcnt lgkmcnt(12)
	v_mfma_f32_32x32x16_bf16 v[112:127], v[192:195], v[168:171], v[112:127]
	v_add_f32_e32 v144, v110, v144
	v_add_f32_e32 v144, v111, v144
	v_add_f32_e32 v144, v80, v144
	v_add_f32_e32 v144, v81, v144
	v_cvt_pk_bf16_f32 v158, v108, v109
	v_cvt_pk_bf16_f32 v159, v110, v111
	ds_read_b64_tr_b16 v[108:109], v243 offset:26624
	ds_read_b64_tr_b16 v[110:111], v243 offset:27136
	s_waitcnt lgkmcnt(13)
	v_mfma_f32_32x32x16_bf16 v[128:143], v[188:191], v[160:163], v[128:143]
	v_add_f32_e32 v144, v82, v144
	v_add_f32_e32 v144, v83, v144
	v_add_f32_e32 v144, v84, v144
	v_add_f32_e32 v144, v85, v144
	v_cvt_pk_bf16_f32 v148, v80, v81
	v_cvt_pk_bf16_f32 v149, v82, v83
	ds_read_b64_tr_b16 v[80:81], v243 offset:30720
	ds_read_b64_tr_b16 v[82:83], v243 offset:31232
	s_waitcnt lgkmcnt(14)
	v_mfma_f32_32x32x16_bf16 v[112:127], v[184:187], v[160:163], v[112:127]
	v_add_f32_e32 v144, v86, v144
	v_add_f32_e32 v144, v87, v144
	v_add_f32_e32 v144, v88, v144
	v_add_f32_e32 v144, v89, v144
	v_cvt_pk_bf16_f32 v150, v84, v85
	v_cvt_pk_bf16_f32 v151, v86, v87
	ds_read_b64_tr_b16 v[84:85], v243 offset:27648
	ds_read_b64_tr_b16 v[86:87], v243 offset:28160
	s_waitcnt lgkmcnt(14)
	v_mfma_f32_32x32x16_bf16 v[128:143], v[180:183], v[152:155], v[128:143]
	v_add_f32_e32 v144, v90, v144
	v_add_f32_e32 v144, v91, v144
	v_add_f32_e32 v144, v92, v144
	v_add_f32_e32 v184, v93, v144
	v_cvt_pk_bf16_f32 v144, v88, v89
	v_cvt_pk_bf16_f32 v145, v90, v91
	ds_read_b64_tr_b16 v[88:89], v243 offset:31744
	ds_read_b64_tr_b16 v[90:91], v243 offset:32256
	v_mfma_f32_32x32x16_bf16 v[112:127], v[176:179], v[152:155], v[112:127]
	v_add_f32_e32 v146, v94, v184
	v_add_f32_e32 v146, v95, v146
	v_add_f32_e32 v180, 0, v146
	v_cvt_pk_bf16_f32 v146, v92, v93
	v_cvt_pk_bf16_f32 v147, v94, v95
	s_add_i32 s4, s46, 1
	s_cmp_ge_u32 s4, s67
	s_cselect_b64 s[38:39], -1, 0
	s_and_b64 vcc, exec, s[38:39]
	v_lshl_add_u64 v[224:225], v[214:215], 0, s[36:37]
	s_cbranch_vccnz .LBB0_1377
	v_lshl_add_u64 v[92:93], v[224:225], 0, s[18:19]
	s_add_i32 s4, s78, s76
	s_mov_b32 m0, s4
	s_nop 0
	global_load_lds_dwordx4 v[92:93], off
.LBB0_1377:
	v_lshl_add_u64 v[220:221], v[216:217], 0, s[36:37]
	s_lshl_b32 s83, s79, 1
	v_lshl_add_u64 v[92:93], v[220:221], 0, s[14:15]
	s_add_i32 s4, s83, s77
	s_mov_b32 m0, s4
	s_nop 0
	global_load_lds_dwordx4 v[92:93], off
	v_lshl_add_u64 v[222:223], v[218:219], 0, s[36:37]
	v_lshl_add_u64 v[92:93], v[222:223], 0, s[14:15]
	s_addk_i32 s4, 0x2000
	s_mov_b32 m0, s4
	s_nop 0
	global_load_lds_dwordx4 v[92:93], off
	s_add_i32 s47, s82, s46
	s_add_i32 s4, s47, 2
	s_cmp_lt_i32 s4, 0
	s_cbranch_scc1 .LBB0_1379
	v_add_u32_e32 v93, 0xffffffa5, v242
	v_add_u32_e32 v92, 0xffffff85, v242
	v_cmp_le_i32_e32 vcc, v93, v236
	s_nop 1
	v_cndmask_b32_e32 v112, v228, v112, vcc
	v_cmp_lt_i32_e32 vcc, v92, v236
	s_nop 1
	v_cndmask_b32_e32 v129, v228, v129, vcc
	v_cmp_le_i32_e32 vcc, v92, v236
	v_add_u32_e32 v92, 0xffffffa6, v242
	s_nop 0
	v_cndmask_b32_e32 v128, v228, v128, vcc
	v_cmp_le_i32_e32 vcc, v92, v236
	v_add_u32_e32 v92, 0xffffff87, v242
	s_nop 0
	v_cndmask_b32_e32 v113, v228, v113, vcc
	v_cmp_le_i32_e32 vcc, v92, v236
	v_add_u32_e32 v92, 0xffffffa7, v242
	s_nop 0
	v_cndmask_b32_e32 v130, v228, v130, vcc
	v_cmp_le_i32_e32 vcc, v92, v236
	v_add_u32_e32 v92, 0xffffff88, v242
	s_nop 0
	v_cndmask_b32_e32 v114, v228, v114, vcc
	v_cmp_le_i32_e32 vcc, v92, v236
	v_add_u32_e32 v92, 0xffffffa8, v242
	s_nop 0
	v_cndmask_b32_e32 v131, v228, v131, vcc
	v_cmp_le_i32_e32 vcc, v92, v236
	v_add_u32_e32 v92, 0xffffff8d, v242
	s_nop 0
	v_cndmask_b32_e32 v115, v228, v115, vcc
	v_cmp_le_i32_e32 vcc, v92, v236
	v_add_u32_e32 v92, 0xffffffad, v242
	s_nop 0
	v_cndmask_b32_e32 v132, v228, v132, vcc
	v_cmp_le_i32_e32 vcc, v92, v236
	v_add_u32_e32 v92, 0xffffff8e, v242
	s_nop 0
	v_cndmask_b32_e32 v116, v228, v116, vcc
	v_cmp_le_i32_e32 vcc, v92, v236
	v_add_u32_e32 v92, 0xffffffae, v242
	s_nop 0
	v_cndmask_b32_e32 v133, v228, v133, vcc
	v_cmp_le_i32_e32 vcc, v92, v236
	v_add_u32_e32 v92, 0xffffff8f, v242
	s_nop 0
	v_cndmask_b32_e32 v117, v228, v117, vcc
	v_cmp_le_i32_e32 vcc, v92, v236
	v_add_u32_e32 v92, 0xffffffaf, v242
	s_nop 0
	v_cndmask_b32_e32 v134, v228, v134, vcc
	v_cmp_le_i32_e32 vcc, v92, v236
	v_add_u32_e32 v92, 0xffffff90, v242
	s_nop 0
	v_cndmask_b32_e32 v118, v228, v118, vcc
	v_cmp_le_i32_e32 vcc, v92, v236
	v_add_u32_e32 v92, 0xffffffb0, v242
	s_nop 0
	v_cndmask_b32_e32 v135, v228, v135, vcc
	v_cmp_le_i32_e32 vcc, v92, v236
	v_add_u32_e32 v92, 0xffffff95, v242
	s_nop 0
	v_cndmask_b32_e32 v119, v228, v119, vcc
	v_cmp_le_i32_e32 vcc, v92, v236
	v_add_u32_e32 v92, 0xffffffb5, v242
	s_nop 0
	v_cndmask_b32_e32 v136, v228, v136, vcc
	v_cmp_le_i32_e32 vcc, v92, v236
	v_add_u32_e32 v92, 0xffffff96, v242
	s_nop 0
	v_cndmask_b32_e32 v120, v228, v120, vcc
	v_cmp_le_i32_e32 vcc, v92, v236
	v_add_u32_e32 v92, 0xffffffb6, v242
	s_nop 0
	v_cndmask_b32_e32 v137, v228, v137, vcc
	v_cmp_le_i32_e32 vcc, v92, v236
	v_add_u32_e32 v92, 0xffffff97, v242
	s_nop 0
	v_cndmask_b32_e32 v121, v228, v121, vcc
	v_cmp_le_i32_e32 vcc, v92, v236
	v_add_u32_e32 v92, 0xffffffb7, v242
	s_nop 0
	v_cndmask_b32_e32 v138, v228, v138, vcc
	v_cmp_le_i32_e32 vcc, v92, v236
	v_add_u32_e32 v92, 0xffffff98, v242
	s_nop 0
	v_cndmask_b32_e32 v122, v228, v122, vcc
	v_cmp_le_i32_e32 vcc, v92, v236
	v_add_u32_e32 v92, 0xffffffb8, v242
	s_nop 0
	v_cndmask_b32_e32 v139, v228, v139, vcc
	v_cmp_le_i32_e32 vcc, v92, v236
	v_add_u32_e32 v92, 0xffffff9d, v242
	s_nop 0
	v_cndmask_b32_e32 v123, v228, v123, vcc
	v_cmp_le_i32_e32 vcc, v92, v236
	v_add_u32_e32 v92, 0xffffffbd, v242
	s_nop 0
	v_cndmask_b32_e32 v140, v228, v140, vcc
	v_cmp_le_i32_e32 vcc, v92, v236
	v_add_u32_e32 v92, 0xffffff9e, v242
	s_nop 0
	v_cndmask_b32_e32 v124, v228, v124, vcc
	v_cmp_le_i32_e32 vcc, v92, v236
	v_add_u32_e32 v92, 0xffffffbe, v242
	s_nop 0
	v_cndmask_b32_e32 v141, v228, v141, vcc
	v_cmp_le_i32_e32 vcc, v92, v236
	v_add_u32_e32 v92, 0xffffff9f, v242
	s_nop 0
	v_cndmask_b32_e32 v125, v228, v125, vcc
	v_cmp_le_i32_e32 vcc, v92, v236
	v_add_u32_e32 v92, 0xffffffbf, v242
	s_nop 0
	v_cndmask_b32_e32 v142, v228, v142, vcc
	v_cmp_le_i32_e32 vcc, v92, v236
	v_add_u32_e32 v92, 0xffffffa0, v242
	s_nop 0
	v_cndmask_b32_e32 v126, v228, v126, vcc
	v_cmp_le_i32_e32 vcc, v92, v236
	v_subrev_u32_e32 v92, 64, v242
	s_nop 0
	v_cndmask_b32_e32 v143, v228, v143, vcc
	v_cmp_le_i32_e32 vcc, v92, v236
	s_nop 1
	v_cndmask_b32_e32 v127, v228, v127, vcc
.LBB0_1379:
	v_max_f32_e32 v92, v128, v129
	v_max3_f32 v93, v130, v131, v113
	v_max3_f32 v92, v92, v112, v114
	v_max3_f32 v92, v92, v115, v132
	v_max3_f32 v93, v93, v134, v135
	v_max3_f32 v92, v92, v133, v116
	v_max3_f32 v93, v93, v118, v119
	v_max3_f32 v92, v92, v117, v136
	v_max3_f32 v93, v93, v138, v139
	v_max3_f32 v92, v92, v137, v120
	v_max3_f32 v93, v93, v122, v123
	v_max3_f32 v92, v92, v121, v140
	v_max3_f32 v93, v93, v142, v143
	v_max3_f32 v92, v92, v141, v124
	v_max3_f32 v93, v93, v126, v127
	v_max3_f32 v92, v92, v125, v93
	v_mov_b32_e32 v93, v92
	s_nop 1
	v_permlane32_swap_b32_e32 v92, v93
	v_max_f32_e32 v92, v92, v93
	v_cmp_lt_f32_e32 vcc, s41, v92
	s_cmp_lg_u64 vcc, 0
	v_add_f32_e32 v241, v241, v180
	s_cselect_b64 s[10:11], -1, 0
	s_cbranch_vccnz .LBB0_1417

.LBB0_1384:
	s_lshl_b32 s4, s78, 1
	v_add_u32_e32 v244, s4, v239
	ds_read_b64_tr_b16 v[208:209], v244 offset:24576
	ds_read_b64_tr_b16 v[210:211], v244 offset:25088
	s_waitcnt lgkmcnt(9)
	v_mfma_f32_32x32x16_bf16 v[96:111], v[204:207], v[172:175], v[64:79]
	v_add_f32_e32 v80, v128, v129
	v_add_f32_e32 v80, v130, v80
	v_add_f32_e32 v80, v131, v80
	v_add_f32_e32 v80, v132, v80
	v_add_f32_e32 v80, v133, v80
	v_cvt_pk_bf16_f32 v164, v128, v129
	v_cvt_pk_bf16_f32 v165, v130, v131
	ds_read_b64_tr_b16 v[128:129], v244 offset:28672
	ds_read_b64_tr_b16 v[130:131], v244 offset:29184
	v_add_f32_e32 v80, v134, v80
	v_add_f32_e32 v80, v135, v80
	v_add_f32_e32 v80, v136, v80
	v_add_f32_e32 v144, v137, v80
	s_waitcnt lgkmcnt(10)
	v_mfma_f32_32x32x16_bf16 v[80:95], v[200:203], v[172:175], v[64:79]
	v_cvt_pk_bf16_f32 v166, v132, v133
	v_cvt_pk_bf16_f32 v167, v134, v135
	ds_read_b64_tr_b16 v[132:133], v244 offset:25600
	ds_read_b64_tr_b16 v[134:135], v244 offset:26112
	s_waitcnt lgkmcnt(11)
	v_mfma_f32_32x32x16_bf16 v[96:111], v[196:199], v[168:171], v[96:111]
	v_add_f32_e32 v144, v138, v144
	v_add_f32_e32 v144, v139, v144
	v_add_f32_e32 v144, v140, v144
	v_add_f32_e32 v144, v141, v144
	v_cvt_pk_bf16_f32 v156, v136, v137
	v_cvt_pk_bf16_f32 v157, v138, v139
	ds_read_b64_tr_b16 v[136:137], v244 offset:29696
	ds_read_b64_tr_b16 v[138:139], v244 offset:30208
	s_waitcnt lgkmcnt(12)
	v_mfma_f32_32x32x16_bf16 v[80:95], v[192:195], v[168:171], v[80:95]
	v_add_f32_e32 v144, v142, v144
	v_add_f32_e32 v144, v143, v144
	v_add_f32_e32 v144, v112, v144
	v_add_f32_e32 v144, v113, v144
	v_cvt_pk_bf16_f32 v158, v140, v141
	v_cvt_pk_bf16_f32 v159, v142, v143
	ds_read_b64_tr_b16 v[140:141], v244 offset:26624
	ds_read_b64_tr_b16 v[142:143], v244 offset:27136
	s_waitcnt lgkmcnt(13)
	v_mfma_f32_32x32x16_bf16 v[96:111], v[188:191], v[160:163], v[96:111]
	v_add_f32_e32 v144, v114, v144
	v_add_f32_e32 v144, v115, v144
	v_add_f32_e32 v144, v116, v144
	v_add_f32_e32 v144, v117, v144
	v_cvt_pk_bf16_f32 v148, v112, v113
	v_cvt_pk_bf16_f32 v149, v114, v115
	ds_read_b64_tr_b16 v[112:113], v244 offset:30720
	ds_read_b64_tr_b16 v[114:115], v244 offset:31232
	s_waitcnt lgkmcnt(14)
	v_mfma_f32_32x32x16_bf16 v[80:95], v[184:187], v[160:163], v[80:95]
	v_add_f32_e32 v144, v118, v144
	v_add_f32_e32 v144, v119, v144
	v_add_f32_e32 v144, v120, v144
	v_add_f32_e32 v144, v121, v144
	v_cvt_pk_bf16_f32 v150, v116, v117
	v_cvt_pk_bf16_f32 v151, v118, v119
	ds_read_b64_tr_b16 v[116:117], v244 offset:27648
	ds_read_b64_tr_b16 v[118:119], v244 offset:28160
	s_waitcnt lgkmcnt(14)
	v_mfma_f32_32x32x16_bf16 v[96:111], v[180:183], v[152:155], v[96:111]
	v_add_f32_e32 v144, v122, v144
	v_add_f32_e32 v144, v123, v144
	v_add_f32_e32 v144, v124, v144
	v_add_f32_e32 v245, v125, v144
	v_cvt_pk_bf16_f32 v144, v120, v121
	v_cvt_pk_bf16_f32 v145, v122, v123
	ds_read_b64_tr_b16 v[120:121], v244 offset:31744
	ds_read_b64_tr_b16 v[122:123], v244 offset:32256
	v_mfma_f32_32x32x16_bf16 v[80:95], v[176:179], v[152:155], v[80:95]
	v_add_f32_e32 v146, v126, v245
	v_add_f32_e32 v146, v127, v146
	v_add_f32_e32 v245, 0, v146
	v_cvt_pk_bf16_f32 v146, v124, v125
	v_cvt_pk_bf16_f32 v147, v126, v127
	s_add_i32 s84, s46, 2
	s_cmp_ge_u32 s84, s67
	s_cselect_b64 s[44:45], -1, 0
	s_and_b64 vcc, exec, s[44:45]
	s_cbranch_vccnz .LBB0_1386
	v_lshl_add_u64 v[124:125], v[224:225], 0, s[26:27]
	s_add_i32 s4, s79, s76
	s_mov_b32 m0, s4
	s_nop 0
	global_load_lds_dwordx4 v[124:125], off
.LBB0_1386:
	s_add_i32 s4, s79, 0x2000
	s_cmpk_lg_i32 s79, 0x4000
	s_cselect_b32 s78, s4, 0
	s_cmp_lt_u32 s46, s67
	s_cselect_b64 s[48:49], -1, 0
	s_cmp_ge_u32 s46, s67
	s_cbranch_scc1 .LBB0_1388
	s_lshl_b32 s4, s78, 1
	v_lshl_add_u64 v[124:125], v[220:221], 0, s[16:17]
	s_add_i32 s4, s4, s77
	s_mov_b32 m0, s4
	s_nop 0
	global_load_lds_dwordx4 v[124:125], off
	v_lshl_add_u64 v[126:127], v[222:223], 0, s[16:17]
	s_addk_i32 s4, 0x2000
	s_mov_b32 m0, s4
	s_nop 0
	global_load_lds_dwordx4 v[126:127], off

.LBB0_1390:
	v_max_f32_e32 v124, v96, v97
	v_max3_f32 v125, v98, v99, v81
	v_max3_f32 v124, v124, v80, v82
	v_max3_f32 v124, v124, v83, v100
	v_max3_f32 v125, v125, v102, v103
	v_max3_f32 v124, v124, v101, v84
	v_max3_f32 v125, v125, v86, v87
	v_max3_f32 v124, v124, v85, v104
	v_max3_f32 v125, v125, v106, v107
	v_max3_f32 v124, v124, v105, v88
	v_max3_f32 v125, v125, v90, v91
	v_max3_f32 v124, v124, v89, v108
	v_max3_f32 v125, v125, v110, v111
	v_max3_f32 v124, v124, v109, v92
	v_max3_f32 v125, v125, v94, v95
	v_max3_f32 v124, v124, v93, v125
	v_mov_b32_e32 v125, v124
	s_nop 1
	v_permlane32_swap_b32_e32 v124, v125
	v_max_f32_e32 v124, v124, v125
	v_cmp_lt_f32_e32 vcc, s41, v124
	s_cmp_lg_u64 vcc, 0
	v_add_f32_e32 v241, v241, v245
	s_cselect_b64 s[46:47], -1, 0
	s_cbranch_vccnz .LBB0_1420

.LBB0_1427:
	v_add_u32_e32 v208, s70, v240
	ds_read_b64_tr_b16 v[128:129], v208 offset:24576
	ds_read_b64_tr_b16 v[130:131], v208 offset:25088
	v_add_f32_e32 v112, v96, v97
	v_add_f32_e32 v112, v98, v112
	v_add_f32_e32 v112, v99, v112
	v_add_f32_e32 v112, v100, v112
	v_add_f32_e32 v136, v101, v112
	s_waitcnt lgkmcnt(9)
	v_mfma_f32_32x32x16_bf16 v[112:127], v[204:207], v[172:175], v[64:79]
	v_cvt_pk_bf16_f32 v160, v96, v97
	v_cvt_pk_bf16_f32 v161, v98, v99
	ds_read_b64_tr_b16 v[132:133], v208 offset:28672
	ds_read_b64_tr_b16 v[134:135], v208 offset:29184
	s_waitcnt lgkmcnt(10)
	v_mfma_f32_32x32x16_bf16 v[64:79], v[200:203], v[172:175], v[64:79]
	v_add_f32_e32 v96, v102, v136
	v_add_f32_e32 v96, v103, v96
	v_add_f32_e32 v96, v104, v96
	v_add_f32_e32 v96, v105, v96
	v_cvt_pk_bf16_f32 v162, v100, v101
	v_cvt_pk_bf16_f32 v163, v102, v103
	ds_read_b64_tr_b16 v[136:137], v208 offset:25600
	ds_read_b64_tr_b16 v[138:139], v208 offset:26112
	s_waitcnt lgkmcnt(11)
	v_mfma_f32_32x32x16_bf16 v[112:127], v[196:199], v[168:171], v[112:127]
	v_add_f32_e32 v96, v106, v96
	v_add_f32_e32 v96, v107, v96
	v_add_f32_e32 v96, v108, v96
	v_add_f32_e32 v96, v109, v96
	v_cvt_pk_bf16_f32 v156, v104, v105
	v_cvt_pk_bf16_f32 v157, v106, v107
	ds_read_b64_tr_b16 v[140:141], v208 offset:29696
	ds_read_b64_tr_b16 v[142:143], v208 offset:30208
	s_waitcnt lgkmcnt(12)
	v_mfma_f32_32x32x16_bf16 v[64:79], v[192:195], v[168:171], v[64:79]
	v_add_f32_e32 v96, v110, v96
	v_add_f32_e32 v96, v111, v96
	v_add_f32_e32 v96, v80, v96
	v_add_f32_e32 v96, v81, v96
	v_cvt_pk_bf16_f32 v158, v108, v109
	v_cvt_pk_bf16_f32 v159, v110, v111
	ds_read_b64_tr_b16 v[168:169], v208 offset:26624
	ds_read_b64_tr_b16 v[170:171], v208 offset:27136
	s_waitcnt lgkmcnt(13)
	v_mfma_f32_32x32x16_bf16 v[112:127], v[188:191], v[164:167], v[112:127]
	v_add_f32_e32 v96, v82, v96
	v_add_f32_e32 v96, v83, v96
	v_add_f32_e32 v96, v84, v96
	v_add_f32_e32 v96, v85, v96
	v_cvt_pk_bf16_f32 v148, v80, v81
	v_cvt_pk_bf16_f32 v149, v82, v83
	ds_read_b64_tr_b16 v[172:173], v208 offset:30720
	ds_read_b64_tr_b16 v[174:175], v208 offset:31232
	s_waitcnt lgkmcnt(14)
	v_mfma_f32_32x32x16_bf16 v[64:79], v[184:187], v[164:167], v[64:79]
	v_add_f32_e32 v80, v86, v96
	v_add_f32_e32 v80, v87, v80
	v_add_f32_e32 v80, v88, v80
	v_add_f32_e32 v80, v89, v80
	v_cvt_pk_bf16_f32 v150, v84, v85
	v_cvt_pk_bf16_f32 v151, v86, v87
	ds_read_b64_tr_b16 v[164:165], v208 offset:27648
	ds_read_b64_tr_b16 v[166:167], v208 offset:28160
	s_waitcnt lgkmcnt(14)
	v_mfma_f32_32x32x16_bf16 v[112:127], v[180:183], v[152:155], v[112:127]
	v_add_f32_e32 v80, v90, v80
	v_add_f32_e32 v80, v91, v80
	v_add_f32_e32 v80, v92, v80
	v_add_f32_e32 v80, v93, v80
	v_cvt_pk_bf16_f32 v144, v88, v89
	v_cvt_pk_bf16_f32 v145, v90, v91
	ds_read_b64_tr_b16 v[180:181], v208 offset:31744
	ds_read_b64_tr_b16 v[182:183], v208 offset:32256
	v_mfma_f32_32x32x16_bf16 v[64:79], v[176:179], v[152:155], v[64:79]
	v_add_f32_e32 v80, v94, v80
	v_add_f32_e32 v80, v95, v80
	v_add_f32_e32 v96, 0, v80
	v_cvt_pk_bf16_f32 v146, v92, v93
	v_cvt_pk_bf16_f32 v147, v94, v95
	v_or_b32_e32 v81, 0xe0, v212
	v_or_b32_e32 v80, 0xc0, v212
	v_cmp_le_i32_e32 vcc, v81, v237
	v_or_b32_e32 v82, 0xe1, v212
	v_or_b32_e32 v83, 0xe2, v212
	s_nop 1
	v_cndmask_b32_e32 v64, v228, v64, vcc
	v_cmp_lt_i32_e32 vcc, v80, v237
	v_or_b32_e32 v84, 0xe3, v212
	v_or_b32_e32 v85, 0xe8, v212
	v_cndmask_b32_e32 v81, v228, v113, vcc
	v_cmp_le_i32_e32 vcc, v80, v237
	v_or_b32_e32 v86, 0xe9, v212
	v_or_b32_e32 v87, 0xea, v212
	v_cndmask_b32_e32 v80, v228, v112, vcc
	v_cmp_le_i32_e32 vcc, v82, v237
	v_or_b32_e32 v82, 0xc2, v212
	v_or_b32_e32 v88, 0xeb, v212
	v_cndmask_b32_e32 v65, v228, v65, vcc
	v_cmp_le_i32_e32 vcc, v82, v237
	v_or_b32_e32 v89, 0xf0, v212
	v_or_b32_e32 v90, 0xf1, v212
	v_cndmask_b32_e32 v82, v228, v114, vcc
	v_cmp_le_i32_e32 vcc, v83, v237
	v_or_b32_e32 v83, 0xc3, v212
	v_or_b32_e32 v91, 0xf2, v212
	v_cndmask_b32_e32 v66, v228, v66, vcc
	v_cmp_le_i32_e32 vcc, v83, v237
	v_or_b32_e32 v92, 0xf3, v212
	v_or_b32_e32 v93, 0xf8, v212
	v_cndmask_b32_e32 v83, v228, v115, vcc
	v_cmp_le_i32_e32 vcc, v84, v237
	v_or_b32_e32 v84, 0xc8, v212
	v_or_b32_e32 v94, 0xf9, v212
	v_cndmask_b32_e32 v67, v228, v67, vcc
	v_cmp_le_i32_e32 vcc, v84, v237
	v_or_b32_e32 v95, 0xfa, v212
	v_or_b32_e32 v97, 0xfb, v212
	v_cndmask_b32_e32 v84, v228, v116, vcc
	v_cmp_le_i32_e32 vcc, v85, v237
	v_or_b32_e32 v85, 0xc9, v212
	s_nop 0
	v_cndmask_b32_e32 v68, v228, v68, vcc
	v_cmp_le_i32_e32 vcc, v85, v237
	v_add_f32_e32 v112, v243, v96
	s_nop 0
	v_cndmask_b32_e32 v85, v228, v117, vcc
	v_cmp_le_i32_e32 vcc, v86, v237
	v_or_b32_e32 v86, 0xca, v212
	s_nop 0
	v_cndmask_b32_e32 v69, v228, v69, vcc
	v_cmp_le_i32_e32 vcc, v86, v237
	s_nop 1
	v_cndmask_b32_e32 v86, v228, v118, vcc
	v_cmp_le_i32_e32 vcc, v87, v237
	v_or_b32_e32 v87, 0xcb, v212
	s_nop 0
	v_cndmask_b32_e32 v70, v228, v70, vcc
	v_cmp_le_i32_e32 vcc, v87, v237
	s_nop 1
	v_cndmask_b32_e32 v87, v228, v119, vcc
	v_cmp_le_i32_e32 vcc, v88, v237
	v_or_b32_e32 v88, 0xd0, v212
	s_nop 0
	v_cndmask_b32_e32 v71, v228, v71, vcc
	v_cmp_le_i32_e32 vcc, v88, v237
	s_nop 1
	v_cndmask_b32_e32 v88, v228, v120, vcc
	v_cmp_le_i32_e32 vcc, v89, v237
	v_or_b32_e32 v89, 0xd1, v212
	s_nop 0
	v_cndmask_b32_e32 v72, v228, v72, vcc
	v_cmp_le_i32_e32 vcc, v89, v237
	s_nop 1
	v_cndmask_b32_e32 v89, v228, v121, vcc
	v_cmp_le_i32_e32 vcc, v90, v237
	v_or_b32_e32 v90, 0xd2, v212
	s_nop 0
	v_cndmask_b32_e32 v73, v228, v73, vcc
	v_cmp_le_i32_e32 vcc, v90, v237
	s_nop 1
	v_cndmask_b32_e32 v90, v228, v122, vcc
	v_cmp_le_i32_e32 vcc, v91, v237
	v_or_b32_e32 v91, 0xd3, v212
	s_nop 0
	v_cndmask_b32_e32 v74, v228, v74, vcc
	v_cmp_le_i32_e32 vcc, v91, v237
	s_nop 1
	v_cndmask_b32_e32 v91, v228, v123, vcc
	v_cmp_le_i32_e32 vcc, v92, v237
	v_or_b32_e32 v92, 0xd8, v212
	s_nop 0
	v_cndmask_b32_e32 v75, v228, v75, vcc
	v_cmp_le_i32_e32 vcc, v92, v237
	s_nop 1
	v_cndmask_b32_e32 v92, v228, v124, vcc
	v_cmp_le_i32_e32 vcc, v93, v237
	v_or_b32_e32 v93, 0xd9, v212
	s_nop 0
	v_cndmask_b32_e32 v76, v228, v76, vcc
	v_cmp_le_i32_e32 vcc, v93, v237
	s_nop 1
	v_cndmask_b32_e32 v93, v228, v125, vcc
	v_cmp_le_i32_e32 vcc, v94, v237
	v_or_b32_e32 v94, 0xda, v212
	s_nop 0
	v_cndmask_b32_e32 v77, v228, v77, vcc
	v_cmp_le_i32_e32 vcc, v94, v237
	s_nop 1
	v_cndmask_b32_e32 v94, v228, v126, vcc
	v_cmp_le_i32_e32 vcc, v95, v237
	v_or_b32_e32 v95, 0xdb, v212
	s_nop 0
	v_cndmask_b32_e32 v78, v228, v78, vcc
	v_cmp_le_i32_e32 vcc, v95, v237
	s_nop 1
	v_cndmask_b32_e32 v95, v228, v127, vcc
	v_cmp_le_i32_e32 vcc, v97, v237
	v_max_f32_e32 v97, v80, v81
	v_max3_f32 v98, v82, v83, v65
	v_max3_f32 v97, v97, v64, v66
	v_max3_f32 v97, v97, v67, v84
	v_max3_f32 v98, v98, v86, v87
	v_max3_f32 v97, v97, v85, v68
	v_max3_f32 v98, v98, v70, v71
	v_max3_f32 v97, v97, v69, v88
	v_max3_f32 v98, v98, v90, v91
	v_max3_f32 v97, v97, v89, v72
	v_max3_f32 v98, v98, v74, v75
	v_cndmask_b32_e32 v79, v228, v79, vcc
	v_max3_f32 v97, v97, v73, v92
	v_max3_f32 v98, v98, v94, v95
	v_max3_f32 v97, v97, v93, v76
	v_max3_f32 v98, v98, v78, v79
	v_max3_f32 v96, v97, v77, v98
	v_mov_b32_e32 v97, v96
	s_nop 1
	v_permlane32_swap_b32_e32 v96, v97
	v_max_f32_e32 v96, v96, v97
	v_cmp_lt_f32_e32 vcc, s41, v96
	s_cmp_lg_u64 vcc, 0
	s_cselect_b64 s[6:7], -1, 0
	s_cbranch_vccnz .LBB0_1485

.LBB0_1434:
	s_lshl_b32 s4, s36, 1
	v_add_u32_e32 v245, s4, v240
	ds_read_b64_tr_b16 v[208:209], v245 offset:24576
	ds_read_b64_tr_b16 v[210:211], v245 offset:25088
	s_waitcnt lgkmcnt(9)
	v_mfma_f32_32x32x16_bf16 v[128:143], v[204:207], v[172:175], v[64:79]
	v_add_f32_e32 v112, v96, v97
	v_add_f32_e32 v112, v98, v112
	v_add_f32_e32 v112, v99, v112
	v_add_f32_e32 v112, v100, v112
	v_add_f32_e32 v112, v101, v112
	v_cvt_pk_bf16_f32 v160, v96, v97
	v_cvt_pk_bf16_f32 v161, v98, v99
	ds_read_b64_tr_b16 v[96:97], v245 offset:28672
	ds_read_b64_tr_b16 v[98:99], v245 offset:29184
	v_add_f32_e32 v112, v102, v112
	v_add_f32_e32 v112, v103, v112
	v_add_f32_e32 v112, v104, v112
	v_add_f32_e32 v144, v105, v112
	s_waitcnt lgkmcnt(10)
	v_mfma_f32_32x32x16_bf16 v[112:127], v[200:203], v[172:175], v[64:79]
	v_cvt_pk_bf16_f32 v162, v100, v101
	v_cvt_pk_bf16_f32 v163, v102, v103
	ds_read_b64_tr_b16 v[100:101], v245 offset:25600
	ds_read_b64_tr_b16 v[102:103], v245 offset:26112
	s_waitcnt lgkmcnt(11)
	v_mfma_f32_32x32x16_bf16 v[128:143], v[196:199], v[168:171], v[128:143]
	v_add_f32_e32 v144, v106, v144
	v_add_f32_e32 v144, v107, v144
	v_add_f32_e32 v144, v108, v144
	v_add_f32_e32 v144, v109, v144
	v_cvt_pk_bf16_f32 v156, v104, v105
	v_cvt_pk_bf16_f32 v157, v106, v107
	ds_read_b64_tr_b16 v[104:105], v245 offset:29696
	ds_read_b64_tr_b16 v[106:107], v245 offset:30208
	s_waitcnt lgkmcnt(12)
	v_mfma_f32_32x32x16_bf16 v[112:127], v[192:195], v[168:171], v[112:127]
	v_add_f32_e32 v144, v110, v144
	v_add_f32_e32 v144, v111, v144
	v_add_f32_e32 v144, v80, v144
	v_add_f32_e32 v144, v81, v144
	v_cvt_pk_bf16_f32 v158, v108, v109
	v_cvt_pk_bf16_f32 v159, v110, v111
	ds_read_b64_tr_b16 v[108:109], v245 offset:26624
	ds_read_b64_tr_b16 v[110:111], v245 offset:27136
	s_waitcnt lgkmcnt(13)
	v_mfma_f32_32x32x16_bf16 v[128:143], v[188:191], v[164:167], v[128:143]
	v_add_f32_e32 v144, v82, v144
	v_add_f32_e32 v144, v83, v144
	v_add_f32_e32 v144, v84, v144
	v_add_f32_e32 v144, v85, v144
	v_cvt_pk_bf16_f32 v148, v80, v81
	v_cvt_pk_bf16_f32 v149, v82, v83
	ds_read_b64_tr_b16 v[80:81], v245 offset:30720
	ds_read_b64_tr_b16 v[82:83], v245 offset:31232
	s_waitcnt lgkmcnt(14)
	v_mfma_f32_32x32x16_bf16 v[112:127], v[184:187], v[164:167], v[112:127]
	v_add_f32_e32 v144, v86, v144
	v_add_f32_e32 v144, v87, v144
	v_add_f32_e32 v144, v88, v144
	v_add_f32_e32 v144, v89, v144
	v_cvt_pk_bf16_f32 v150, v84, v85
	v_cvt_pk_bf16_f32 v151, v86, v87
	ds_read_b64_tr_b16 v[84:85], v245 offset:27648
	ds_read_b64_tr_b16 v[86:87], v245 offset:28160
	s_waitcnt lgkmcnt(14)
	v_mfma_f32_32x32x16_bf16 v[128:143], v[180:183], v[152:155], v[128:143]
	v_add_f32_e32 v144, v90, v144
	v_add_f32_e32 v144, v91, v144
	v_add_f32_e32 v144, v92, v144
	v_add_f32_e32 v184, v93, v144
	v_cvt_pk_bf16_f32 v144, v88, v89
	v_cvt_pk_bf16_f32 v145, v90, v91
	ds_read_b64_tr_b16 v[88:89], v245 offset:31744
	ds_read_b64_tr_b16 v[90:91], v245 offset:32256
	v_mfma_f32_32x32x16_bf16 v[112:127], v[176:179], v[152:155], v[112:127]
	v_add_f32_e32 v146, v94, v184
	v_add_f32_e32 v146, v95, v146
	v_add_f32_e32 v180, 0, v146
	v_cvt_pk_bf16_f32 v146, v92, v93
	v_cvt_pk_bf16_f32 v147, v94, v95
	s_add_i32 s4, s44, 1
	s_cmp_ge_u32 s4, s67
	s_cselect_b64 s[36:37], -1, 0
	s_and_b64 vcc, exec, s[36:37]
	v_lshl_add_u64 v[224:225], v[214:215], 0, s[34:35]
	s_cbranch_vccnz .LBB0_1436
	v_lshl_add_u64 v[92:93], v[224:225], 0, s[18:19]
	s_add_i32 s4, s75, s71
	s_mov_b32 m0, s4
	s_nop 0
	global_load_lds_dwordx4 v[92:93], off
.LBB0_1436:
	v_lshl_add_u64 v[220:221], v[216:217], 0, s[34:35]
	s_lshl_b32 s70, s76, 1
	v_lshl_add_u64 v[92:93], v[220:221], 0, s[14:15]
	s_add_i32 s4, s70, s74
	s_mov_b32 m0, s4
	s_nop 0
	global_load_lds_dwordx4 v[92:93], off
	s_add_i32 s45, s68, s44
	v_lshl_add_u64 v[222:223], v[218:219], 0, s[34:35]
	s_addk_i32 s4, 0x2000
	s_add_i32 s5, s45, 2
	v_lshl_add_u64 v[92:93], v[222:223], 0, s[14:15]
	s_cmp_lt_i32 s5, 0
	s_mov_b32 m0, s4
	s_nop 0
	global_load_lds_dwordx4 v[92:93], off
	s_cbranch_scc1 .LBB0_1438
	v_add_u32_e32 v93, 0xffffffa5, v244
	v_add_u32_e32 v92, 0xffffff85, v244
	v_cmp_le_i32_e32 vcc, v93, v237
	s_nop 1
	v_cndmask_b32_e32 v112, v228, v112, vcc
	v_cmp_lt_i32_e32 vcc, v92, v237
	s_nop 1
	v_cndmask_b32_e32 v129, v228, v129, vcc
	v_cmp_le_i32_e32 vcc, v92, v237
	v_add_u32_e32 v92, 0xffffffa6, v244
	s_nop 0
	v_cndmask_b32_e32 v128, v228, v128, vcc
	v_cmp_le_i32_e32 vcc, v92, v237
	v_add_u32_e32 v92, 0xffffff87, v244
	s_nop 0
	v_cndmask_b32_e32 v113, v228, v113, vcc
	v_cmp_le_i32_e32 vcc, v92, v237
	v_add_u32_e32 v92, 0xffffffa7, v244
	s_nop 0
	v_cndmask_b32_e32 v130, v228, v130, vcc
	v_cmp_le_i32_e32 vcc, v92, v237
	v_add_u32_e32 v92, 0xffffff88, v244
	s_nop 0
	v_cndmask_b32_e32 v114, v228, v114, vcc
	v_cmp_le_i32_e32 vcc, v92, v237
	v_add_u32_e32 v92, 0xffffffa8, v244
	s_nop 0
	v_cndmask_b32_e32 v131, v228, v131, vcc
	v_cmp_le_i32_e32 vcc, v92, v237
	v_add_u32_e32 v92, 0xffffff8d, v244
	s_nop 0
	v_cndmask_b32_e32 v115, v228, v115, vcc
	v_cmp_le_i32_e32 vcc, v92, v237
	v_add_u32_e32 v92, 0xffffffad, v244
	s_nop 0
	v_cndmask_b32_e32 v132, v228, v132, vcc
	v_cmp_le_i32_e32 vcc, v92, v237
	v_add_u32_e32 v92, 0xffffff8e, v244
	s_nop 0
	v_cndmask_b32_e32 v116, v228, v116, vcc
	v_cmp_le_i32_e32 vcc, v92, v237
	v_add_u32_e32 v92, 0xffffffae, v244
	s_nop 0
	v_cndmask_b32_e32 v133, v228, v133, vcc
	v_cmp_le_i32_e32 vcc, v92, v237
	v_add_u32_e32 v92, 0xffffff8f, v244
	s_nop 0
	v_cndmask_b32_e32 v117, v228, v117, vcc
	v_cmp_le_i32_e32 vcc, v92, v237
	v_add_u32_e32 v92, 0xffffffaf, v244
	s_nop 0
	v_cndmask_b32_e32 v134, v228, v134, vcc
	v_cmp_le_i32_e32 vcc, v92, v237
	v_add_u32_e32 v92, 0xffffff90, v244
	s_nop 0
	v_cndmask_b32_e32 v118, v228, v118, vcc
	v_cmp_le_i32_e32 vcc, v92, v237
	v_add_u32_e32 v92, 0xffffffb0, v244
	s_nop 0
	v_cndmask_b32_e32 v135, v228, v135, vcc
	v_cmp_le_i32_e32 vcc, v92, v237
	v_add_u32_e32 v92, 0xffffff95, v244
	s_nop 0
	v_cndmask_b32_e32 v119, v228, v119, vcc
	v_cmp_le_i32_e32 vcc, v92, v237
	v_add_u32_e32 v92, 0xffffffb5, v244
	s_nop 0
	v_cndmask_b32_e32 v136, v228, v136, vcc
	v_cmp_le_i32_e32 vcc, v92, v237
	v_add_u32_e32 v92, 0xffffff96, v244
	s_nop 0
	v_cndmask_b32_e32 v120, v228, v120, vcc
	v_cmp_le_i32_e32 vcc, v92, v237
	v_add_u32_e32 v92, 0xffffffb6, v244
	s_nop 0
	v_cndmask_b32_e32 v137, v228, v137, vcc
	v_cmp_le_i32_e32 vcc, v92, v237
	v_add_u32_e32 v92, 0xffffff97, v244
	s_nop 0
	v_cndmask_b32_e32 v121, v228, v121, vcc
	v_cmp_le_i32_e32 vcc, v92, v237
	v_add_u32_e32 v92, 0xffffffb7, v244
	s_nop 0
	v_cndmask_b32_e32 v138, v228, v138, vcc
	v_cmp_le_i32_e32 vcc, v92, v237
	v_add_u32_e32 v92, 0xffffff98, v244
	s_nop 0
	v_cndmask_b32_e32 v122, v228, v122, vcc
	v_cmp_le_i32_e32 vcc, v92, v237
	v_add_u32_e32 v92, 0xffffffb8, v244
	s_nop 0
	v_cndmask_b32_e32 v139, v228, v139, vcc
	v_cmp_le_i32_e32 vcc, v92, v237
	v_add_u32_e32 v92, 0xffffff9d, v244
	s_nop 0
	v_cndmask_b32_e32 v123, v228, v123, vcc
	v_cmp_le_i32_e32 vcc, v92, v237
	v_add_u32_e32 v92, 0xffffffbd, v244
	s_nop 0
	v_cndmask_b32_e32 v140, v228, v140, vcc
	v_cmp_le_i32_e32 vcc, v92, v237
	v_add_u32_e32 v92, 0xffffff9e, v244
	s_nop 0
	v_cndmask_b32_e32 v124, v228, v124, vcc
	v_cmp_le_i32_e32 vcc, v92, v237
	v_add_u32_e32 v92, 0xffffffbe, v244
	s_nop 0
	v_cndmask_b32_e32 v141, v228, v141, vcc
	v_cmp_le_i32_e32 vcc, v92, v237
	v_add_u32_e32 v92, 0xffffff9f, v244
	s_nop 0
	v_cndmask_b32_e32 v125, v228, v125, vcc
	v_cmp_le_i32_e32 vcc, v92, v237
	v_add_u32_e32 v92, 0xffffffbf, v244
	s_nop 0
	v_cndmask_b32_e32 v142, v228, v142, vcc
	v_cmp_le_i32_e32 vcc, v92, v237
	v_add_u32_e32 v92, 0xffffffa0, v244
	s_nop 0
	v_cndmask_b32_e32 v126, v228, v126, vcc
	v_cmp_le_i32_e32 vcc, v92, v237
	v_subrev_u32_e32 v92, 64, v244
	s_nop 0
	v_cndmask_b32_e32 v143, v228, v143, vcc
	v_cmp_le_i32_e32 vcc, v92, v237
	s_nop 1
	v_cndmask_b32_e32 v127, v228, v127, vcc
.LBB0_1438:
	v_max_f32_e32 v92, v128, v129
	v_max3_f32 v93, v130, v131, v113
	v_max3_f32 v92, v92, v112, v114
	v_max3_f32 v92, v92, v115, v132
	v_max3_f32 v93, v93, v134, v135
	v_max3_f32 v92, v92, v133, v116
	v_max3_f32 v93, v93, v118, v119
	v_max3_f32 v92, v92, v117, v136
	v_max3_f32 v93, v93, v138, v139
	v_max3_f32 v92, v92, v137, v120
	v_max3_f32 v93, v93, v122, v123
	v_max3_f32 v92, v92, v121, v140
	v_max3_f32 v93, v93, v142, v143
	v_max3_f32 v92, v92, v141, v124
	v_max3_f32 v93, v93, v126, v127
	v_max3_f32 v92, v92, v125, v93
	v_mov_b32_e32 v93, v92
	s_nop 1
	v_permlane32_swap_b32_e32 v92, v93
	v_max_f32_e32 v92, v92, v93
	v_cmp_lt_f32_e32 vcc, s41, v92
	s_cmp_lg_u64 vcc, 0
	v_add_f32_e32 v243, v243, v180
	s_cselect_b64 s[8:9], -1, 0
	s_cbranch_vccnz .LBB0_1476

.LBB0_1443:
	s_lshl_b32 s4, s75, 1
	v_add_u32_e32 v246, s4, v240
	ds_read_b64_tr_b16 v[208:209], v246 offset:24576
	ds_read_b64_tr_b16 v[210:211], v246 offset:25088
	s_waitcnt lgkmcnt(9)
	v_mfma_f32_32x32x16_bf16 v[96:111], v[204:207], v[172:175], v[64:79]
	v_add_f32_e32 v80, v128, v129
	v_add_f32_e32 v80, v130, v80
	v_add_f32_e32 v80, v131, v80
	v_add_f32_e32 v80, v132, v80
	v_add_f32_e32 v80, v133, v80
	v_cvt_pk_bf16_f32 v160, v128, v129
	v_cvt_pk_bf16_f32 v161, v130, v131
	ds_read_b64_tr_b16 v[128:129], v246 offset:28672
	ds_read_b64_tr_b16 v[130:131], v246 offset:29184
	v_add_f32_e32 v80, v134, v80
	v_add_f32_e32 v80, v135, v80
	v_add_f32_e32 v80, v136, v80
	v_add_f32_e32 v144, v137, v80
	s_waitcnt lgkmcnt(10)
	v_mfma_f32_32x32x16_bf16 v[80:95], v[200:203], v[172:175], v[64:79]
	v_cvt_pk_bf16_f32 v162, v132, v133
	v_cvt_pk_bf16_f32 v163, v134, v135
	ds_read_b64_tr_b16 v[132:133], v246 offset:25600
	ds_read_b64_tr_b16 v[134:135], v246 offset:26112
	s_waitcnt lgkmcnt(11)
	v_mfma_f32_32x32x16_bf16 v[96:111], v[196:199], v[168:171], v[96:111]
	v_add_f32_e32 v144, v138, v144
	v_add_f32_e32 v144, v139, v144
	v_add_f32_e32 v144, v140, v144
	v_add_f32_e32 v144, v141, v144
	v_cvt_pk_bf16_f32 v156, v136, v137
	v_cvt_pk_bf16_f32 v157, v138, v139
	ds_read_b64_tr_b16 v[136:137], v246 offset:29696
	ds_read_b64_tr_b16 v[138:139], v246 offset:30208
	s_waitcnt lgkmcnt(12)
	v_mfma_f32_32x32x16_bf16 v[80:95], v[192:195], v[168:171], v[80:95]
	v_add_f32_e32 v144, v142, v144
	v_add_f32_e32 v144, v143, v144
	v_add_f32_e32 v144, v112, v144
	v_add_f32_e32 v144, v113, v144
	v_cvt_pk_bf16_f32 v158, v140, v141
	v_cvt_pk_bf16_f32 v159, v142, v143
	ds_read_b64_tr_b16 v[140:141], v246 offset:26624
	ds_read_b64_tr_b16 v[142:143], v246 offset:27136
	s_waitcnt lgkmcnt(13)
	v_mfma_f32_32x32x16_bf16 v[96:111], v[188:191], v[164:167], v[96:111]
	v_add_f32_e32 v144, v114, v144
	v_add_f32_e32 v144, v115, v144
	v_add_f32_e32 v144, v116, v144
	v_add_f32_e32 v144, v117, v144
	v_cvt_pk_bf16_f32 v148, v112, v113
	v_cvt_pk_bf16_f32 v149, v114, v115
	ds_read_b64_tr_b16 v[112:113], v246 offset:30720
	ds_read_b64_tr_b16 v[114:115], v246 offset:31232
	s_waitcnt lgkmcnt(14)
	v_mfma_f32_32x32x16_bf16 v[80:95], v[184:187], v[164:167], v[80:95]
	v_add_f32_e32 v144, v118, v144
	v_add_f32_e32 v144, v119, v144
	v_add_f32_e32 v144, v120, v144
	v_add_f32_e32 v144, v121, v144
	v_cvt_pk_bf16_f32 v150, v116, v117
	v_cvt_pk_bf16_f32 v151, v118, v119
	ds_read_b64_tr_b16 v[116:117], v246 offset:27648
	ds_read_b64_tr_b16 v[118:119], v246 offset:28160
	s_waitcnt lgkmcnt(14)
	v_mfma_f32_32x32x16_bf16 v[96:111], v[180:183], v[152:155], v[96:111]
	v_add_f32_e32 v144, v122, v144
	v_add_f32_e32 v144, v123, v144
	v_add_f32_e32 v144, v124, v144
	v_add_f32_e32 v247, v125, v144
	v_cvt_pk_bf16_f32 v144, v120, v121
	v_cvt_pk_bf16_f32 v145, v122, v123
	ds_read_b64_tr_b16 v[120:121], v246 offset:31744
	ds_read_b64_tr_b16 v[122:123], v246 offset:32256
	v_mfma_f32_32x32x16_bf16 v[80:95], v[176:179], v[152:155], v[80:95]
	v_add_f32_e32 v146, v126, v247
	v_add_f32_e32 v146, v127, v146
	v_add_f32_e32 v247, 0, v146
	v_cvt_pk_bf16_f32 v146, v124, v125
	v_cvt_pk_bf16_f32 v147, v126, v127
	s_add_i32 s77, s44, 2
	s_cmp_ge_u32 s77, s67
	s_cselect_b64 s[38:39], -1, 0
	s_and_b64 vcc, exec, s[38:39]
	s_cbranch_vccnz .LBB0_1445
	v_lshl_add_u64 v[124:125], v[224:225], 0, s[26:27]
	s_add_i32 s4, s76, s71
	s_mov_b32 m0, s4
	s_nop 0
	global_load_lds_dwordx4 v[124:125], off
.LBB0_1445:
	s_add_i32 s4, s76, 0x2000
	s_cmpk_lg_i32 s76, 0x4000
	s_cselect_b32 s75, s4, 0
	s_cmp_lt_u32 s44, s67
	s_cselect_b64 s[46:47], -1, 0
	s_cmp_ge_u32 s44, s67
	s_cbranch_scc1 .LBB0_1447
	s_lshl_b32 s4, s75, 1
	v_lshl_add_u64 v[124:125], v[220:221], 0, s[16:17]
	s_add_i32 s4, s4, s74
	s_mov_b32 m0, s4
	s_nop 0
	global_load_lds_dwordx4 v[124:125], off
	v_lshl_add_u64 v[126:127], v[222:223], 0, s[16:17]
	s_addk_i32 s4, 0x2000
	s_mov_b32 m0, s4
	s_nop 0
	global_load_lds_dwordx4 v[126:127], off

.LBB0_1449:
	v_max_f32_e32 v124, v96, v97
	v_max3_f32 v125, v98, v99, v81
	v_max3_f32 v124, v124, v80, v82
	v_max3_f32 v124, v124, v83, v100
	v_max3_f32 v125, v125, v102, v103
	v_max3_f32 v124, v124, v101, v84
	v_max3_f32 v125, v125, v86, v87
	v_max3_f32 v124, v124, v85, v104
	v_max3_f32 v125, v125, v106, v107
	v_max3_f32 v124, v124, v105, v88
	v_max3_f32 v125, v125, v90, v91
	v_max3_f32 v124, v124, v89, v108
	v_max3_f32 v125, v125, v110, v111
	v_max3_f32 v124, v124, v109, v92
	v_max3_f32 v125, v125, v94, v95
	v_max3_f32 v124, v124, v93, v125
	v_mov_b32_e32 v125, v124
	s_nop 1
	v_permlane32_swap_b32_e32 v124, v125
	v_max_f32_e32 v124, v124, v125
	v_cmp_lt_f32_e32 vcc, s41, v124
	s_cmp_lg_u64 vcc, 0
	v_add_f32_e32 v243, v243, v247
	s_cselect_b64 s[44:45], -1, 0
	s_cbranch_vccnz .LBB0_1479

.LBB0_1476:
	v_max_f32_e32 v92, 0, v92
	v_exp_f32_e64 v93, -v92
	v_add_f32_e32 v238, v238, v92
	v_xor_b32_e32 v64, 0x80000000, v238
	v_mov_b32_e32 v65, v64
	v_mov_b32_e32 v66, v64
	v_mov_b32_e32 v67, v64
	v_mov_b32_e32 v68, v64
	v_mov_b32_e32 v69, v64
	v_mov_b32_e32 v70, v64
	v_mov_b32_e32 v71, v64
	v_mov_b32_e32 v72, v64
	v_mov_b32_e32 v73, v64
	v_mov_b32_e32 v74, v64
	v_mov_b32_e32 v75, v64
	v_mov_b32_e32 v76, v64
	v_mov_b32_e32 v77, v64
	v_mov_b32_e32 v78, v64
	v_mov_b32_e32 v79, v64
	s_and_saveexec_b64 s[4:5], s[6:7]
	ds_write_b32 v236, v93
	s_or_b64 exec, exec, s[4:5]
	v_sub_f32_e32 v143, v143, v92
	v_sub_f32_e32 v142, v142, v92
	v_sub_f32_e32 v141, v141, v92
	v_sub_f32_e32 v140, v140, v92
	v_sub_f32_e32 v139, v139, v92
	v_sub_f32_e32 v138, v138, v92
	v_sub_f32_e32 v137, v137, v92
	v_sub_f32_e32 v136, v136, v92
	v_sub_f32_e32 v135, v135, v92
	v_sub_f32_e32 v134, v134, v92
	v_sub_f32_e32 v133, v133, v92
	v_sub_f32_e32 v132, v132, v92
	v_sub_f32_e32 v131, v131, v92
	v_sub_f32_e32 v130, v130, v92
	v_sub_f32_e32 v129, v129, v92
	v_sub_f32_e32 v128, v128, v92
	v_sub_f32_e32 v127, v127, v92
	v_sub_f32_e32 v126, v126, v92
	v_sub_f32_e32 v125, v125, v92
	v_sub_f32_e32 v124, v124, v92
	v_sub_f32_e32 v123, v123, v92
	v_sub_f32_e32 v122, v122, v92
	v_sub_f32_e32 v121, v121, v92
	v_sub_f32_e32 v120, v120, v92
	v_sub_f32_e32 v119, v119, v92
	v_sub_f32_e32 v118, v118, v92
	v_sub_f32_e32 v117, v117, v92
	v_sub_f32_e32 v116, v116, v92
	v_sub_f32_e32 v115, v115, v92
	v_sub_f32_e32 v114, v114, v92
	v_sub_f32_e32 v113, v113, v92
	v_sub_f32_e32 v112, v112, v92
	v_mul_f32_e32 v243, v243, v93
	s_branch .LBB0_1439

.LBB0_1482:
	v_max_f32_e32 v113, 0, v96
	v_exp_f32_e64 v114, -v113
	v_add_f32_e32 v96, v237, v113
	v_xor_b32_e32 v96, 0x80000000, v96
	v_mov_b32_e32 v97, v96
	v_mov_b32_e32 v98, v96
	v_mov_b32_e32 v99, v96
	v_mov_b32_e32 v100, v96
	v_mov_b32_e32 v101, v96
	v_mov_b32_e32 v102, v96
	v_mov_b32_e32 v103, v96
	v_mov_b32_e32 v104, v96
	v_mov_b32_e32 v105, v96
	v_mov_b32_e32 v106, v96
	v_mov_b32_e32 v107, v96
	v_mov_b32_e32 v108, v96
	v_mov_b32_e32 v109, v96
	v_mov_b32_e32 v110, v96
	v_mov_b32_e32 v111, v96
	v_cmp_gt_u32_e32 vcc, 32, v231
	s_and_saveexec_b64 s[4:5], vcc
	ds_write_b32 v234, v114
	s_or_b64 exec, exec, s[4:5]
	v_sub_f32_e32 v95, v95, v113
	v_sub_f32_e32 v94, v94, v113
	v_sub_f32_e32 v93, v93, v113
	v_sub_f32_e32 v92, v92, v113
	v_sub_f32_e32 v91, v91, v113
	v_sub_f32_e32 v90, v90, v113
	v_sub_f32_e32 v89, v89, v113
	v_sub_f32_e32 v88, v88, v113
	v_sub_f32_e32 v87, v87, v113
	v_sub_f32_e32 v86, v86, v113
	v_sub_f32_e32 v85, v85, v113
	v_sub_f32_e32 v84, v84, v113
	v_sub_f32_e32 v83, v83, v113
	v_sub_f32_e32 v82, v82, v113
	v_sub_f32_e32 v81, v81, v113
	v_sub_f32_e32 v80, v80, v113
	v_sub_f32_e32 v79, v79, v113
	v_sub_f32_e32 v78, v78, v113
	v_sub_f32_e32 v77, v77, v113
	v_sub_f32_e32 v76, v76, v113
	v_sub_f32_e32 v75, v75, v113
	v_sub_f32_e32 v74, v74, v113
	v_sub_f32_e32 v73, v73, v113
	v_sub_f32_e32 v72, v72, v113
	v_sub_f32_e32 v71, v71, v113
	v_sub_f32_e32 v70, v70, v113
	v_sub_f32_e32 v69, v69, v113
	v_sub_f32_e32 v68, v68, v113
	v_sub_f32_e32 v67, v67, v113
	v_sub_f32_e32 v66, v66, v113
	v_sub_f32_e32 v65, v65, v113
	v_sub_f32_e32 v64, v64, v113
	v_mul_f32_e32 v112, v112, v114
	s_branch .LBB0_1351
.LBB0_1485:
	v_max_f32_e32 v113, 0, v96
	v_exp_f32_e64 v114, -v113
	v_add_f32_e32 v96, v238, v113
	v_xor_b32_e32 v96, 0x80000000, v96
	v_mov_b32_e32 v97, v96
	v_mov_b32_e32 v98, v96
	v_mov_b32_e32 v99, v96
	v_mov_b32_e32 v100, v96
	v_mov_b32_e32 v101, v96
	v_mov_b32_e32 v102, v96
	v_mov_b32_e32 v103, v96
	v_mov_b32_e32 v104, v96
	v_mov_b32_e32 v105, v96
	v_mov_b32_e32 v106, v96
	v_mov_b32_e32 v107, v96
	v_mov_b32_e32 v108, v96
	v_mov_b32_e32 v109, v96
	v_mov_b32_e32 v110, v96
	v_mov_b32_e32 v111, v96
	v_cmp_gt_u32_e32 vcc, 32, v231
	s_and_saveexec_b64 s[4:5], vcc
	ds_write_b32 v236, v114
	s_or_b64 exec, exec, s[4:5]
	v_sub_f32_e32 v95, v95, v113
	v_sub_f32_e32 v94, v94, v113
	v_sub_f32_e32 v93, v93, v113
	v_sub_f32_e32 v92, v92, v113
	v_sub_f32_e32 v91, v91, v113
	v_sub_f32_e32 v90, v90, v113
	v_sub_f32_e32 v89, v89, v113
	v_sub_f32_e32 v88, v88, v113
	v_sub_f32_e32 v87, v87, v113
	v_sub_f32_e32 v86, v86, v113
	v_sub_f32_e32 v85, v85, v113
	v_sub_f32_e32 v84, v84, v113
	v_sub_f32_e32 v83, v83, v113
	v_sub_f32_e32 v82, v82, v113
	v_sub_f32_e32 v81, v81, v113
	v_sub_f32_e32 v80, v80, v113
	v_sub_f32_e32 v79, v79, v113
	v_sub_f32_e32 v78, v78, v113
	v_sub_f32_e32 v77, v77, v113
	v_sub_f32_e32 v76, v76, v113
	v_sub_f32_e32 v75, v75, v113
	v_sub_f32_e32 v74, v74, v113
	v_sub_f32_e32 v73, v73, v113
	v_sub_f32_e32 v72, v72, v113
	v_sub_f32_e32 v71, v71, v113
	v_sub_f32_e32 v70, v70, v113
	v_sub_f32_e32 v69, v69, v113
	v_sub_f32_e32 v68, v68, v113
	v_sub_f32_e32 v67, v67, v113
	v_sub_f32_e32 v66, v66, v113
	v_sub_f32_e32 v65, v65, v113
	v_sub_f32_e32 v64, v64, v113
	v_mul_f32_e32 v112, v112, v114
	s_branch .LBB0_1428
